# GEMM core prologue issues its first DMA group before clearing accumulators; bump placement lazy (same schedule)
# speedup vs baseline: 1.0197x; 1.0044x over previous
.LBB0_224:
	s_add_u32 s12, s90, s2
	s_addc_u32 s37, s91, s3
	s_ashr_i32 s35, s34, 31
	s_lshl_b64 s[6:7], s[34:35], 18
	s_lshl_b64 s[2:3], s[34:35], 19
	s_add_u32 s2, s12, s2
	s_addc_u32 s3, s37, s3
	s_mov_b32 s56, s2
	s_mov_b32 s57, s3
	s_ashr_i32 s37, s36, 31
	s_lshl_b64 s[2:3], s[36:37], 19
	s_add_u32 s2, s90, s2
	s_addc_u32 s3, s91, s3
	s_mov_b32 s58, s2
	s_mov_b32 s59, s3
	s_movk_i32 s2, 0x100
	s_mov_b32 s3, -2
	v_lshrrev_b32_e32 v232, 6, v208
	v_and_b32_e32 v233, 63, v208
	v_readfirstlane_b32 s98, v232
	v_and_b32_e32 v234, 3, v233
	v_bfe_u32 v235, v233, 2, 1
	v_lshl_or_b32 v234, v235, 3, v234
	v_bfe_u32 v235, v233, 3, 1
	v_lshl_or_b32 v234, v235, 2, v234
	s_and_b32 s55, s98, 1
	s_lshr_b32 s100, s98, 2
	s_lshl_b32 s99, s98, 10
	v_lshrrev_b32_e32 v235, 4, v233
	v_bfe_u32 v236, v234, 1, 3
	v_xor_b32_e32 v236, v235, v236
	v_lshlrev_b32_e32 v236, 4, v236
	v_lshl_add_u32 v234, s55, 6, v234
	v_lshl_add_u32 v170, v234, 7, v236
	v_xor_b32_e32 v197, 64, v170
	v_add_u32_e32 v196, 0x10000, v170
	v_add_u32_e32 v198, 0x10000, v197
	v_bfe_u32 v236, v233, 1, 3
	v_xor_b32_e32 v236, v235, v236
	v_lshlrev_b32_e32 v236, 4, v236
	v_and_b32_e32 v234, 15, v233
	s_lshr_b32 s101, s98, 1
	v_lshl_add_u32 v234, s101, 5, v234
	v_lshl_add_u32 v199, v234, 7, v236
	v_add_u32_e32 v199, 0x8000, v199
	v_xor_b32_e32 v201, 64, v199
	v_add_u32_e32 v200, 0x10000, v199
	v_add_u32_e32 v202, 0x10000, v201
	v_lshl_add_u32 v236, s55, 2, v235
	v_and_b32_e32 v234, 7, v233
	v_xor_b32_e32 v236, v234, v236
	v_lshlrev_b32_e32 v236, 4, v236
	v_lshrrev_b32_e32 v234, 3, v233
	v_lshl_add_u32 v235, s98, 3, v234
	v_lshl_add_u32 v203, v235, 11, v236
	v_add_u32_e32 v204, 0x40000, v203
	v_add_u32_e32 v205, 0x20000, v203
	v_add_u32_e32 v206, 0x60000, v203
	s_and_b32 s101, s98, 3
	s_lshl_b32 s101, s101, 3
	s_lshl_b32 s55, s100, 6
	s_add_u32 s101, s101, s55
	v_add_u32_e32 v235, s101, v234
	v_lshl_add_u32 v207, v235, 11, v236
	v_add_u32_e32 v229, 0x40000, v207
	v_add_u32_e32 v230, 0x10000, v207
	v_add_u32_e32 v231, 0x50000, v207
	s_add_u32 m0, s99, 0x8000
	s_nop 0
	global_load_lds_dwordx4 v207, s[56:57]
	s_add_u32 m0, s99, 0xa000
	s_nop 0
	global_load_lds_dwordx4 v229, s[56:57]
	s_add_u32 m0, s99, 0x0
	s_nop 0
	global_load_lds_dwordx4 v203, s[58:59]
	s_add_u32 m0, s99, 0x2000
	s_nop 0
	global_load_lds_dwordx4 v204, s[58:59]
	s_add_u32 m0, s99, 0xc000
	s_nop 0
	global_load_lds_dwordx4 v230, s[56:57]
	s_add_u32 m0, s99, 0xe000
	s_nop 0
	global_load_lds_dwordx4 v231, s[56:57]
	s_add_u32 m0, s99, 0x4000
	s_nop 0
	global_load_lds_dwordx4 v205, s[58:59]
	s_add_u32 m0, s99, 0x6000
	s_nop 0
	global_load_lds_dwordx4 v206, s[58:59]
	v_mov_b32_e32 v112, 0
	v_mov_b32_e32 v113, 0
	v_mov_b32_e32 v114, 0
	v_mov_b32_e32 v115, 0
	v_mov_b32_e32 v116, 0
	v_mov_b32_e32 v117, 0
	v_mov_b32_e32 v118, 0
	v_mov_b32_e32 v119, 0
	v_mov_b32_e32 v120, 0
	v_mov_b32_e32 v121, 0
	v_mov_b32_e32 v122, 0
	v_mov_b32_e32 v123, 0
	v_mov_b32_e32 v124, 0
	v_mov_b32_e32 v125, 0
	v_mov_b32_e32 v126, 0
	v_mov_b32_e32 v127, 0
	v_mov_b32_e32 v80, 0
	v_mov_b32_e32 v81, 0
	v_mov_b32_e32 v82, 0
	v_mov_b32_e32 v83, 0
	v_mov_b32_e32 v84, 0
	v_mov_b32_e32 v85, 0
	v_mov_b32_e32 v86, 0
	v_mov_b32_e32 v87, 0
	v_mov_b32_e32 v88, 0
	v_mov_b32_e32 v89, 0
	v_mov_b32_e32 v90, 0
	v_mov_b32_e32 v91, 0
	v_mov_b32_e32 v92, 0
	v_mov_b32_e32 v93, 0
	v_mov_b32_e32 v94, 0
	v_mov_b32_e32 v95, 0
	v_mov_b32_e32 v96, 0
	v_mov_b32_e32 v97, 0
	v_mov_b32_e32 v98, 0
	v_mov_b32_e32 v99, 0
	v_mov_b32_e32 v100, 0
	v_mov_b32_e32 v101, 0
	v_mov_b32_e32 v102, 0
	v_mov_b32_e32 v103, 0
	v_mov_b32_e32 v104, 0
	v_mov_b32_e32 v105, 0
	v_mov_b32_e32 v106, 0
	v_mov_b32_e32 v107, 0
	v_mov_b32_e32 v108, 0
	v_mov_b32_e32 v109, 0
	v_mov_b32_e32 v110, 0
	v_mov_b32_e32 v111, 0
	v_mov_b32_e32 v64, 0
	v_mov_b32_e32 v65, 0
	v_mov_b32_e32 v66, 0
	v_mov_b32_e32 v67, 0
	v_mov_b32_e32 v68, 0
	v_mov_b32_e32 v69, 0
	v_mov_b32_e32 v70, 0
	v_mov_b32_e32 v71, 0
	v_mov_b32_e32 v72, 0
	v_mov_b32_e32 v73, 0
	v_mov_b32_e32 v74, 0
	v_mov_b32_e32 v75, 0
	v_mov_b32_e32 v76, 0
	v_mov_b32_e32 v77, 0
	v_mov_b32_e32 v78, 0
	v_mov_b32_e32 v79, 0
	v_mov_b32_e32 v48, 0
	v_mov_b32_e32 v49, 0
	v_mov_b32_e32 v50, 0
	v_mov_b32_e32 v51, 0
	v_mov_b32_e32 v52, 0
	v_mov_b32_e32 v53, 0
	v_mov_b32_e32 v54, 0
	v_mov_b32_e32 v55, 0
	v_mov_b32_e32 v56, 0
	v_mov_b32_e32 v57, 0
	v_mov_b32_e32 v58, 0
	v_mov_b32_e32 v59, 0
	v_mov_b32_e32 v60, 0
	v_mov_b32_e32 v61, 0
	v_mov_b32_e32 v62, 0
	v_mov_b32_e32 v63, 0
	v_mov_b32_e32 v16, 0
	v_mov_b32_e32 v17, 0
	v_mov_b32_e32 v18, 0
	v_mov_b32_e32 v19, 0
	v_mov_b32_e32 v20, 0
	v_mov_b32_e32 v21, 0
	v_mov_b32_e32 v22, 0
	v_mov_b32_e32 v23, 0
	v_mov_b32_e32 v24, 0
	v_mov_b32_e32 v25, 0
	v_mov_b32_e32 v26, 0
	v_mov_b32_e32 v27, 0
	v_mov_b32_e32 v28, 0
	v_mov_b32_e32 v29, 0
	v_mov_b32_e32 v30, 0
	v_mov_b32_e32 v31, 0
	v_mov_b32_e32 v32, 0
	v_mov_b32_e32 v33, 0
	v_mov_b32_e32 v34, 0
	v_mov_b32_e32 v35, 0
	v_mov_b32_e32 v36, 0
	v_mov_b32_e32 v37, 0
	v_mov_b32_e32 v38, 0
	v_mov_b32_e32 v39, 0
	v_mov_b32_e32 v40, 0
	v_mov_b32_e32 v41, 0
	v_mov_b32_e32 v42, 0
	v_mov_b32_e32 v43, 0
	v_mov_b32_e32 v44, 0
	v_mov_b32_e32 v45, 0
	v_mov_b32_e32 v46, 0
	v_mov_b32_e32 v47, 0
	v_mov_b32_e32 v0, 0
	v_mov_b32_e32 v1, 0
	v_mov_b32_e32 v2, 0
	v_mov_b32_e32 v3, 0
	v_mov_b32_e32 v4, 0
	v_mov_b32_e32 v5, 0
	v_mov_b32_e32 v6, 0
	v_mov_b32_e32 v7, 0
	v_mov_b32_e32 v8, 0
	v_mov_b32_e32 v9, 0
	v_mov_b32_e32 v10, 0
	v_mov_b32_e32 v11, 0
	v_mov_b32_e32 v12, 0
	v_mov_b32_e32 v13, 0
	v_mov_b32_e32 v14, 0
	v_mov_b32_e32 v15, 0
	s_cmp_eq_u32 s100, 0
	s_cbranch_scc1 .Lg8_p2_gb0
	s_barrier
.Lg8_p2_gb0:
	s_waitcnt vmcnt(4)
	s_barrier
	s_add_u32 s56, s56, 0x80
	s_addc_u32 s57, s57, 0
	s_add_u32 m0, s99, 0x18000
	s_nop 0
	global_load_lds_dwordx4 v207, s[56:57]
	s_add_u32 m0, s99, 0x1a000
	s_nop 0
	global_load_lds_dwordx4 v229, s[56:57]
	s_add_u32 s58, s58, 0x80
	s_addc_u32 s59, s59, 0
	s_add_u32 m0, s99, 0x10000
	s_nop 0
	global_load_lds_dwordx4 v203, s[58:59]
	s_add_u32 m0, s99, 0x12000
	s_nop 0
	global_load_lds_dwordx4 v204, s[58:59]
	s_add_u32 m0, s99, 0x1c000
	s_nop 0
	global_load_lds_dwordx4 v230, s[56:57]
	s_add_u32 m0, s99, 0x1e000
	s_nop 0
	global_load_lds_dwordx4 v231, s[56:57]
	s_waitcnt vmcnt(6)
	s_barrier
	s_mov_b32 s101, 7
.Lg8_p2_loop:
	ds_read_b128 v[160:163], v199 offset:0
	ds_read_b128 v[164:167], v201 offset:0
	ds_read_b128 v[172:175], v199 offset:2048
	ds_read_b128 v[176:179], v201 offset:2048
	ds_read_b128 v[128:131], v170 offset:0
	ds_read_b128 v[132:135], v197 offset:0
	ds_read_b128 v[136:139], v170 offset:2048
	ds_read_b128 v[140:143], v197 offset:2048
	ds_read_b128 v[144:147], v170 offset:4096
	ds_read_b128 v[148:151], v197 offset:4096
	ds_read_b128 v[152:155], v170 offset:6144
	ds_read_b128 v[156:159], v197 offset:6144
	s_add_u32 m0, s99, 0x14000
	s_nop 0
	global_load_lds_dwordx4 v205, s[58:59]
	s_add_u32 m0, s99, 0x16000
	s_nop 0
	global_load_lds_dwordx4 v206, s[58:59]
	s_waitcnt lgkmcnt(8)
	s_barrier
	s_waitcnt lgkmcnt(0)
	s_setprio 1
	v_mfma_f32_16x16x32_bf16 v[112:115], v[128:131], v[160:163], v[112:115]
	v_mfma_f32_16x16x32_bf16 v[112:115], v[132:135], v[164:167], v[112:115]
	v_mfma_f32_16x16x32_bf16 v[116:119], v[128:131], v[172:175], v[116:119]
	v_mfma_f32_16x16x32_bf16 v[116:119], v[132:135], v[176:179], v[116:119]
	v_mfma_f32_16x16x32_bf16 v[120:123], v[136:139], v[160:163], v[120:123]
	v_mfma_f32_16x16x32_bf16 v[120:123], v[140:143], v[164:167], v[120:123]
	v_mfma_f32_16x16x32_bf16 v[124:127], v[136:139], v[172:175], v[124:127]
	v_mfma_f32_16x16x32_bf16 v[124:127], v[140:143], v[176:179], v[124:127]
	v_mfma_f32_16x16x32_bf16 v[80:83], v[144:147], v[160:163], v[80:83]
	v_mfma_f32_16x16x32_bf16 v[80:83], v[148:151], v[164:167], v[80:83]
	v_mfma_f32_16x16x32_bf16 v[84:87], v[144:147], v[172:175], v[84:87]
	v_mfma_f32_16x16x32_bf16 v[84:87], v[148:151], v[176:179], v[84:87]
	v_mfma_f32_16x16x32_bf16 v[88:91], v[152:155], v[160:163], v[88:91]
	v_mfma_f32_16x16x32_bf16 v[88:91], v[156:159], v[164:167], v[88:91]
	v_mfma_f32_16x16x32_bf16 v[92:95], v[152:155], v[172:175], v[92:95]
	v_mfma_f32_16x16x32_bf16 v[92:95], v[156:159], v[176:179], v[92:95]
	s_setprio 0
	s_barrier
	ds_read_b128 v[180:183], v199 offset:16384
	ds_read_b128 v[184:187], v201 offset:16384
	ds_read_b128 v[188:191], v199 offset:18432
	ds_read_b128 v[192:195], v201 offset:18432
	s_add_u32 s56, s56, 0x80
	s_addc_u32 s57, s57, 0
	s_add_u32 m0, s99, 0x8000
	s_nop 0
	global_load_lds_dwordx4 v207, s[56:57]
	s_add_u32 m0, s99, 0xa000
	s_nop 0
	global_load_lds_dwordx4 v229, s[56:57]
	s_barrier
	s_waitcnt lgkmcnt(0)
	s_setprio 1
	v_mfma_f32_16x16x32_bf16 v[48:51], v[128:131], v[180:183], v[48:51]
	v_mfma_f32_16x16x32_bf16 v[48:51], v[132:135], v[184:187], v[48:51]
	v_mfma_f32_16x16x32_bf16 v[52:55], v[128:131], v[188:191], v[52:55]
	v_mfma_f32_16x16x32_bf16 v[52:55], v[132:135], v[192:195], v[52:55]
	v_mfma_f32_16x16x32_bf16 v[56:59], v[136:139], v[180:183], v[56:59]
	v_mfma_f32_16x16x32_bf16 v[56:59], v[140:143], v[184:187], v[56:59]
	v_mfma_f32_16x16x32_bf16 v[60:63], v[136:139], v[188:191], v[60:63]
	v_mfma_f32_16x16x32_bf16 v[60:63], v[140:143], v[192:195], v[60:63]
	v_mfma_f32_16x16x32_bf16 v[16:19], v[144:147], v[180:183], v[16:19]
	v_mfma_f32_16x16x32_bf16 v[16:19], v[148:151], v[184:187], v[16:19]
	v_mfma_f32_16x16x32_bf16 v[20:23], v[144:147], v[188:191], v[20:23]
	v_mfma_f32_16x16x32_bf16 v[20:23], v[148:151], v[192:195], v[20:23]
	v_mfma_f32_16x16x32_bf16 v[24:27], v[152:155], v[180:183], v[24:27]
	v_mfma_f32_16x16x32_bf16 v[24:27], v[156:159], v[184:187], v[24:27]
	v_mfma_f32_16x16x32_bf16 v[28:31], v[152:155], v[188:191], v[28:31]
	v_mfma_f32_16x16x32_bf16 v[28:31], v[156:159], v[192:195], v[28:31]
	s_setprio 0
	s_barrier
	ds_read_b128 v[128:131], v170 offset:16384
	ds_read_b128 v[132:135], v197 offset:16384
	ds_read_b128 v[136:139], v170 offset:18432
	ds_read_b128 v[140:143], v197 offset:18432
	ds_read_b128 v[144:147], v170 offset:20480
	ds_read_b128 v[148:151], v197 offset:20480
	ds_read_b128 v[152:155], v170 offset:22528
	ds_read_b128 v[156:159], v197 offset:22528
	s_add_u32 s58, s58, 0x80
	s_addc_u32 s59, s59, 0
	s_add_u32 m0, s99, 0x0
	s_nop 0
	global_load_lds_dwordx4 v203, s[58:59]
	s_add_u32 m0, s99, 0x2000
	s_nop 0
	global_load_lds_dwordx4 v204, s[58:59]
	s_barrier
	s_waitcnt lgkmcnt(0)
	s_setprio 1
	v_mfma_f32_16x16x32_bf16 v[96:99], v[128:131], v[160:163], v[96:99]
	v_mfma_f32_16x16x32_bf16 v[96:99], v[132:135], v[164:167], v[96:99]
	v_mfma_f32_16x16x32_bf16 v[100:103], v[128:131], v[172:175], v[100:103]
	v_mfma_f32_16x16x32_bf16 v[100:103], v[132:135], v[176:179], v[100:103]
	v_mfma_f32_16x16x32_bf16 v[104:107], v[136:139], v[160:163], v[104:107]
	v_mfma_f32_16x16x32_bf16 v[104:107], v[140:143], v[164:167], v[104:107]
	v_mfma_f32_16x16x32_bf16 v[108:111], v[136:139], v[172:175], v[108:111]
	v_mfma_f32_16x16x32_bf16 v[108:111], v[140:143], v[176:179], v[108:111]
	v_mfma_f32_16x16x32_bf16 v[64:67], v[144:147], v[160:163], v[64:67]
	v_mfma_f32_16x16x32_bf16 v[64:67], v[148:151], v[164:167], v[64:67]
	v_mfma_f32_16x16x32_bf16 v[68:71], v[144:147], v[172:175], v[68:71]
	v_mfma_f32_16x16x32_bf16 v[68:71], v[148:151], v[176:179], v[68:71]
	v_mfma_f32_16x16x32_bf16 v[72:75], v[152:155], v[160:163], v[72:75]
	v_mfma_f32_16x16x32_bf16 v[72:75], v[156:159], v[164:167], v[72:75]
	v_mfma_f32_16x16x32_bf16 v[76:79], v[152:155], v[172:175], v[76:79]
	v_mfma_f32_16x16x32_bf16 v[76:79], v[156:159], v[176:179], v[76:79]
	s_setprio 0
	s_barrier
	s_add_u32 m0, s99, 0xc000
	s_nop 0
	global_load_lds_dwordx4 v230, s[56:57]
	s_add_u32 m0, s99, 0xe000
	s_nop 0
	global_load_lds_dwordx4 v231, s[56:57]
	s_waitcnt vmcnt(6)
	s_barrier
	s_setprio 1
	v_mfma_f32_16x16x32_bf16 v[32:35], v[128:131], v[180:183], v[32:35]
	v_mfma_f32_16x16x32_bf16 v[32:35], v[132:135], v[184:187], v[32:35]
	v_mfma_f32_16x16x32_bf16 v[36:39], v[128:131], v[188:191], v[36:39]
	v_mfma_f32_16x16x32_bf16 v[36:39], v[132:135], v[192:195], v[36:39]
	v_mfma_f32_16x16x32_bf16 v[40:43], v[136:139], v[180:183], v[40:43]
	v_mfma_f32_16x16x32_bf16 v[40:43], v[140:143], v[184:187], v[40:43]
	v_mfma_f32_16x16x32_bf16 v[44:47], v[136:139], v[188:191], v[44:47]
	v_mfma_f32_16x16x32_bf16 v[44:47], v[140:143], v[192:195], v[44:47]
	v_mfma_f32_16x16x32_bf16 v[0:3], v[144:147], v[180:183], v[0:3]
	v_mfma_f32_16x16x32_bf16 v[0:3], v[148:151], v[184:187], v[0:3]
	v_mfma_f32_16x16x32_bf16 v[4:7], v[144:147], v[188:191], v[4:7]
	v_mfma_f32_16x16x32_bf16 v[4:7], v[148:151], v[192:195], v[4:7]
	v_mfma_f32_16x16x32_bf16 v[8:11], v[152:155], v[180:183], v[8:11]
	v_mfma_f32_16x16x32_bf16 v[8:11], v[156:159], v[184:187], v[8:11]
	v_mfma_f32_16x16x32_bf16 v[12:15], v[152:155], v[188:191], v[12:15]
	v_mfma_f32_16x16x32_bf16 v[12:15], v[156:159], v[192:195], v[12:15]
	s_setprio 0
	s_barrier
	ds_read_b128 v[160:163], v200 offset:0
	ds_read_b128 v[164:167], v202 offset:0
	ds_read_b128 v[172:175], v200 offset:2048
	ds_read_b128 v[176:179], v202 offset:2048
	ds_read_b128 v[128:131], v196 offset:0
	ds_read_b128 v[132:135], v198 offset:0
	ds_read_b128 v[136:139], v196 offset:2048
	ds_read_b128 v[140:143], v198 offset:2048
	ds_read_b128 v[144:147], v196 offset:4096
	ds_read_b128 v[148:151], v198 offset:4096
	ds_read_b128 v[152:155], v196 offset:6144
	ds_read_b128 v[156:159], v198 offset:6144
	s_add_u32 m0, s99, 0x4000
	s_nop 0
	global_load_lds_dwordx4 v205, s[58:59]
	s_add_u32 m0, s99, 0x6000
	s_nop 0
	global_load_lds_dwordx4 v206, s[58:59]
	s_waitcnt lgkmcnt(8)
	s_barrier
	s_waitcnt lgkmcnt(0)
	s_setprio 1
	v_mfma_f32_16x16x32_bf16 v[112:115], v[128:131], v[160:163], v[112:115]
	v_mfma_f32_16x16x32_bf16 v[112:115], v[132:135], v[164:167], v[112:115]
	v_mfma_f32_16x16x32_bf16 v[116:119], v[128:131], v[172:175], v[116:119]
	v_mfma_f32_16x16x32_bf16 v[116:119], v[132:135], v[176:179], v[116:119]
	v_mfma_f32_16x16x32_bf16 v[120:123], v[136:139], v[160:163], v[120:123]
	v_mfma_f32_16x16x32_bf16 v[120:123], v[140:143], v[164:167], v[120:123]
	v_mfma_f32_16x16x32_bf16 v[124:127], v[136:139], v[172:175], v[124:127]
	v_mfma_f32_16x16x32_bf16 v[124:127], v[140:143], v[176:179], v[124:127]
	v_mfma_f32_16x16x32_bf16 v[80:83], v[144:147], v[160:163], v[80:83]
	v_mfma_f32_16x16x32_bf16 v[80:83], v[148:151], v[164:167], v[80:83]
	v_mfma_f32_16x16x32_bf16 v[84:87], v[144:147], v[172:175], v[84:87]
	v_mfma_f32_16x16x32_bf16 v[84:87], v[148:151], v[176:179], v[84:87]
	v_mfma_f32_16x16x32_bf16 v[88:91], v[152:155], v[160:163], v[88:91]
	v_mfma_f32_16x16x32_bf16 v[88:91], v[156:159], v[164:167], v[88:91]
	v_mfma_f32_16x16x32_bf16 v[92:95], v[152:155], v[172:175], v[92:95]
	v_mfma_f32_16x16x32_bf16 v[92:95], v[156:159], v[176:179], v[92:95]
	s_setprio 0
	s_barrier
	ds_read_b128 v[180:183], v200 offset:16384
	ds_read_b128 v[184:187], v202 offset:16384
	ds_read_b128 v[188:191], v200 offset:18432
	ds_read_b128 v[192:195], v202 offset:18432
	s_add_u32 s56, s56, 0x80
	s_addc_u32 s57, s57, 0
	s_add_u32 m0, s99, 0x18000
	s_nop 0
	global_load_lds_dwordx4 v207, s[56:57]
	s_add_u32 m0, s99, 0x1a000
	s_nop 0
	global_load_lds_dwordx4 v229, s[56:57]
	s_barrier
	s_waitcnt lgkmcnt(0)
	s_setprio 1
	v_mfma_f32_16x16x32_bf16 v[48:51], v[128:131], v[180:183], v[48:51]
	v_mfma_f32_16x16x32_bf16 v[48:51], v[132:135], v[184:187], v[48:51]
	v_mfma_f32_16x16x32_bf16 v[52:55], v[128:131], v[188:191], v[52:55]
	v_mfma_f32_16x16x32_bf16 v[52:55], v[132:135], v[192:195], v[52:55]
	v_mfma_f32_16x16x32_bf16 v[56:59], v[136:139], v[180:183], v[56:59]
	v_mfma_f32_16x16x32_bf16 v[56:59], v[140:143], v[184:187], v[56:59]
	v_mfma_f32_16x16x32_bf16 v[60:63], v[136:139], v[188:191], v[60:63]
	v_mfma_f32_16x16x32_bf16 v[60:63], v[140:143], v[192:195], v[60:63]
	v_mfma_f32_16x16x32_bf16 v[16:19], v[144:147], v[180:183], v[16:19]
	v_mfma_f32_16x16x32_bf16 v[16:19], v[148:151], v[184:187], v[16:19]
	v_mfma_f32_16x16x32_bf16 v[20:23], v[144:147], v[188:191], v[20:23]
	v_mfma_f32_16x16x32_bf16 v[20:23], v[148:151], v[192:195], v[20:23]
	v_mfma_f32_16x16x32_bf16 v[24:27], v[152:155], v[180:183], v[24:27]
	v_mfma_f32_16x16x32_bf16 v[24:27], v[156:159], v[184:187], v[24:27]
	v_mfma_f32_16x16x32_bf16 v[28:31], v[152:155], v[188:191], v[28:31]
	v_mfma_f32_16x16x32_bf16 v[28:31], v[156:159], v[192:195], v[28:31]
	s_setprio 0
	s_barrier
	ds_read_b128 v[128:131], v196 offset:16384
	ds_read_b128 v[132:135], v198 offset:16384
	ds_read_b128 v[136:139], v196 offset:18432
	ds_read_b128 v[140:143], v198 offset:18432
	ds_read_b128 v[144:147], v196 offset:20480
	ds_read_b128 v[148:151], v198 offset:20480
	ds_read_b128 v[152:155], v196 offset:22528
	ds_read_b128 v[156:159], v198 offset:22528
	s_add_u32 s58, s58, 0x80
	s_addc_u32 s59, s59, 0
	s_add_u32 m0, s99, 0x10000
	s_nop 0
	global_load_lds_dwordx4 v203, s[58:59]
	s_add_u32 m0, s99, 0x12000
	s_nop 0
	global_load_lds_dwordx4 v204, s[58:59]
	s_barrier
	s_waitcnt lgkmcnt(0)
	s_setprio 1
	v_mfma_f32_16x16x32_bf16 v[96:99], v[128:131], v[160:163], v[96:99]
	v_mfma_f32_16x16x32_bf16 v[96:99], v[132:135], v[164:167], v[96:99]
	v_mfma_f32_16x16x32_bf16 v[100:103], v[128:131], v[172:175], v[100:103]
	v_mfma_f32_16x16x32_bf16 v[100:103], v[132:135], v[176:179], v[100:103]
	v_mfma_f32_16x16x32_bf16 v[104:107], v[136:139], v[160:163], v[104:107]
	v_mfma_f32_16x16x32_bf16 v[104:107], v[140:143], v[164:167], v[104:107]
	v_mfma_f32_16x16x32_bf16 v[108:111], v[136:139], v[172:175], v[108:111]
	v_mfma_f32_16x16x32_bf16 v[108:111], v[140:143], v[176:179], v[108:111]
	v_mfma_f32_16x16x32_bf16 v[64:67], v[144:147], v[160:163], v[64:67]
	v_mfma_f32_16x16x32_bf16 v[64:67], v[148:151], v[164:167], v[64:67]
	v_mfma_f32_16x16x32_bf16 v[68:71], v[144:147], v[172:175], v[68:71]
	v_mfma_f32_16x16x32_bf16 v[68:71], v[148:151], v[176:179], v[68:71]
	v_mfma_f32_16x16x32_bf16 v[72:75], v[152:155], v[160:163], v[72:75]
	v_mfma_f32_16x16x32_bf16 v[72:75], v[156:159], v[164:167], v[72:75]
	v_mfma_f32_16x16x32_bf16 v[76:79], v[152:155], v[172:175], v[76:79]
	v_mfma_f32_16x16x32_bf16 v[76:79], v[156:159], v[176:179], v[76:79]
	s_setprio 0
	s_barrier
	s_add_u32 m0, s99, 0x1c000
	s_nop 0
	global_load_lds_dwordx4 v230, s[56:57]
	s_add_u32 m0, s99, 0x1e000
	s_nop 0
	global_load_lds_dwordx4 v231, s[56:57]
	s_waitcnt vmcnt(6)
	s_barrier
	s_setprio 1
	v_mfma_f32_16x16x32_bf16 v[32:35], v[128:131], v[180:183], v[32:35]
	v_mfma_f32_16x16x32_bf16 v[32:35], v[132:135], v[184:187], v[32:35]
	v_mfma_f32_16x16x32_bf16 v[36:39], v[128:131], v[188:191], v[36:39]
	v_mfma_f32_16x16x32_bf16 v[36:39], v[132:135], v[192:195], v[36:39]
	v_mfma_f32_16x16x32_bf16 v[40:43], v[136:139], v[180:183], v[40:43]
	v_mfma_f32_16x16x32_bf16 v[40:43], v[140:143], v[184:187], v[40:43]
	v_mfma_f32_16x16x32_bf16 v[44:47], v[136:139], v[188:191], v[44:47]
	v_mfma_f32_16x16x32_bf16 v[44:47], v[140:143], v[192:195], v[44:47]
	v_mfma_f32_16x16x32_bf16 v[0:3], v[144:147], v[180:183], v[0:3]
	v_mfma_f32_16x16x32_bf16 v[0:3], v[148:151], v[184:187], v[0:3]
	v_mfma_f32_16x16x32_bf16 v[4:7], v[144:147], v[188:191], v[4:7]
	v_mfma_f32_16x16x32_bf16 v[4:7], v[148:151], v[192:195], v[4:7]
	v_mfma_f32_16x16x32_bf16 v[8:11], v[152:155], v[180:183], v[8:11]
	v_mfma_f32_16x16x32_bf16 v[8:11], v[156:159], v[184:187], v[8:11]
	v_mfma_f32_16x16x32_bf16 v[12:15], v[152:155], v[188:191], v[12:15]
	v_mfma_f32_16x16x32_bf16 v[12:15], v[156:159], v[192:195], v[12:15]
	s_setprio 0
	s_barrier
	s_sub_u32 s101, s101, 1
	s_cmp_lg_u32 s101, 0
	s_cbranch_scc1 .Lg8_p2_loop
	ds_read_b128 v[160:163], v199 offset:0
	ds_read_b128 v[164:167], v201 offset:0
	ds_read_b128 v[172:175], v199 offset:2048
	ds_read_b128 v[176:179], v201 offset:2048
	ds_read_b128 v[128:131], v170 offset:0
	ds_read_b128 v[132:135], v197 offset:0
	ds_read_b128 v[136:139], v170 offset:2048
	ds_read_b128 v[140:143], v197 offset:2048
	ds_read_b128 v[144:147], v170 offset:4096
	ds_read_b128 v[148:151], v197 offset:4096
	ds_read_b128 v[152:155], v170 offset:6144
	ds_read_b128 v[156:159], v197 offset:6144
	s_add_u32 m0, s99, 0x14000
	s_nop 0
	global_load_lds_dwordx4 v205, s[58:59]
	s_add_u32 m0, s99, 0x16000
	s_nop 0
	global_load_lds_dwordx4 v206, s[58:59]
	s_barrier
	s_waitcnt lgkmcnt(0)
	s_setprio 1
	v_mfma_f32_16x16x32_bf16 v[112:115], v[128:131], v[160:163], v[112:115]
	v_mfma_f32_16x16x32_bf16 v[112:115], v[132:135], v[164:167], v[112:115]
	v_mfma_f32_16x16x32_bf16 v[116:119], v[128:131], v[172:175], v[116:119]
	v_mfma_f32_16x16x32_bf16 v[116:119], v[132:135], v[176:179], v[116:119]
	v_mfma_f32_16x16x32_bf16 v[120:123], v[136:139], v[160:163], v[120:123]
	v_mfma_f32_16x16x32_bf16 v[120:123], v[140:143], v[164:167], v[120:123]
	v_mfma_f32_16x16x32_bf16 v[124:127], v[136:139], v[172:175], v[124:127]
	v_mfma_f32_16x16x32_bf16 v[124:127], v[140:143], v[176:179], v[124:127]
	v_mfma_f32_16x16x32_bf16 v[80:83], v[144:147], v[160:163], v[80:83]
	v_mfma_f32_16x16x32_bf16 v[80:83], v[148:151], v[164:167], v[80:83]
	v_mfma_f32_16x16x32_bf16 v[84:87], v[144:147], v[172:175], v[84:87]
	v_mfma_f32_16x16x32_bf16 v[84:87], v[148:151], v[176:179], v[84:87]
	v_mfma_f32_16x16x32_bf16 v[88:91], v[152:155], v[160:163], v[88:91]
	v_mfma_f32_16x16x32_bf16 v[88:91], v[156:159], v[164:167], v[88:91]
	v_mfma_f32_16x16x32_bf16 v[92:95], v[152:155], v[172:175], v[92:95]
	v_mfma_f32_16x16x32_bf16 v[92:95], v[156:159], v[176:179], v[92:95]
	s_setprio 0
	s_barrier
	ds_read_b128 v[180:183], v199 offset:16384
	ds_read_b128 v[184:187], v201 offset:16384
	ds_read_b128 v[188:191], v199 offset:18432
	ds_read_b128 v[192:195], v201 offset:18432
	s_barrier
	s_waitcnt lgkmcnt(0)
	s_setprio 1
	v_mfma_f32_16x16x32_bf16 v[48:51], v[128:131], v[180:183], v[48:51]
	v_mfma_f32_16x16x32_bf16 v[48:51], v[132:135], v[184:187], v[48:51]
	v_mfma_f32_16x16x32_bf16 v[52:55], v[128:131], v[188:191], v[52:55]
	v_mfma_f32_16x16x32_bf16 v[52:55], v[132:135], v[192:195], v[52:55]
	v_mfma_f32_16x16x32_bf16 v[56:59], v[136:139], v[180:183], v[56:59]
	v_mfma_f32_16x16x32_bf16 v[56:59], v[140:143], v[184:187], v[56:59]
	v_mfma_f32_16x16x32_bf16 v[60:63], v[136:139], v[188:191], v[60:63]
	v_mfma_f32_16x16x32_bf16 v[60:63], v[140:143], v[192:195], v[60:63]
	v_mfma_f32_16x16x32_bf16 v[16:19], v[144:147], v[180:183], v[16:19]
	v_mfma_f32_16x16x32_bf16 v[16:19], v[148:151], v[184:187], v[16:19]
	v_mfma_f32_16x16x32_bf16 v[20:23], v[144:147], v[188:191], v[20:23]
	v_mfma_f32_16x16x32_bf16 v[20:23], v[148:151], v[192:195], v[20:23]
	v_mfma_f32_16x16x32_bf16 v[24:27], v[152:155], v[180:183], v[24:27]
	v_mfma_f32_16x16x32_bf16 v[24:27], v[156:159], v[184:187], v[24:27]
	v_mfma_f32_16x16x32_bf16 v[28:31], v[152:155], v[188:191], v[28:31]
	v_mfma_f32_16x16x32_bf16 v[28:31], v[156:159], v[192:195], v[28:31]
	s_setprio 0
	s_barrier
	ds_read_b128 v[128:131], v170 offset:16384
	ds_read_b128 v[132:135], v197 offset:16384
	ds_read_b128 v[136:139], v170 offset:18432
	ds_read_b128 v[140:143], v197 offset:18432
	ds_read_b128 v[144:147], v170 offset:20480
	ds_read_b128 v[148:151], v197 offset:20480
	ds_read_b128 v[152:155], v170 offset:22528
	ds_read_b128 v[156:159], v197 offset:22528
	s_waitcnt vmcnt(4)
	s_barrier
	s_waitcnt lgkmcnt(0)
	s_setprio 1
	v_mfma_f32_16x16x32_bf16 v[96:99], v[128:131], v[160:163], v[96:99]
	v_mfma_f32_16x16x32_bf16 v[96:99], v[132:135], v[164:167], v[96:99]
	v_mfma_f32_16x16x32_bf16 v[100:103], v[128:131], v[172:175], v[100:103]
	v_mfma_f32_16x16x32_bf16 v[100:103], v[132:135], v[176:179], v[100:103]
	v_mfma_f32_16x16x32_bf16 v[104:107], v[136:139], v[160:163], v[104:107]
	v_mfma_f32_16x16x32_bf16 v[104:107], v[140:143], v[164:167], v[104:107]
	v_mfma_f32_16x16x32_bf16 v[108:111], v[136:139], v[172:175], v[108:111]
	v_mfma_f32_16x16x32_bf16 v[108:111], v[140:143], v[176:179], v[108:111]
	v_mfma_f32_16x16x32_bf16 v[64:67], v[144:147], v[160:163], v[64:67]
	v_mfma_f32_16x16x32_bf16 v[64:67], v[148:151], v[164:167], v[64:67]
	v_mfma_f32_16x16x32_bf16 v[68:71], v[144:147], v[172:175], v[68:71]
	v_mfma_f32_16x16x32_bf16 v[68:71], v[148:151], v[176:179], v[68:71]
	v_mfma_f32_16x16x32_bf16 v[72:75], v[152:155], v[160:163], v[72:75]
	v_mfma_f32_16x16x32_bf16 v[72:75], v[156:159], v[164:167], v[72:75]
	v_mfma_f32_16x16x32_bf16 v[76:79], v[152:155], v[172:175], v[76:79]
	v_mfma_f32_16x16x32_bf16 v[76:79], v[156:159], v[176:179], v[76:79]
	s_setprio 0
	s_setprio 1
	v_mfma_f32_16x16x32_bf16 v[32:35], v[128:131], v[180:183], v[32:35]
	v_mfma_f32_16x16x32_bf16 v[32:35], v[132:135], v[184:187], v[32:35]
	v_mfma_f32_16x16x32_bf16 v[36:39], v[128:131], v[188:191], v[36:39]
	v_mfma_f32_16x16x32_bf16 v[36:39], v[132:135], v[192:195], v[36:39]
	v_mfma_f32_16x16x32_bf16 v[40:43], v[136:139], v[180:183], v[40:43]
	v_mfma_f32_16x16x32_bf16 v[40:43], v[140:143], v[184:187], v[40:43]
	v_mfma_f32_16x16x32_bf16 v[44:47], v[136:139], v[188:191], v[44:47]
	v_mfma_f32_16x16x32_bf16 v[44:47], v[140:143], v[192:195], v[44:47]
	v_mfma_f32_16x16x32_bf16 v[0:3], v[144:147], v[180:183], v[0:3]
	v_mfma_f32_16x16x32_bf16 v[0:3], v[148:151], v[184:187], v[0:3]
	v_mfma_f32_16x16x32_bf16 v[4:7], v[144:147], v[188:191], v[4:7]
	v_mfma_f32_16x16x32_bf16 v[4:7], v[148:151], v[192:195], v[4:7]
	v_mfma_f32_16x16x32_bf16 v[8:11], v[152:155], v[180:183], v[8:11]
	v_mfma_f32_16x16x32_bf16 v[8:11], v[156:159], v[184:187], v[8:11]
	v_mfma_f32_16x16x32_bf16 v[12:15], v[152:155], v[188:191], v[12:15]
	v_mfma_f32_16x16x32_bf16 v[12:15], v[156:159], v[192:195], v[12:15]
	s_setprio 0
	s_barrier
	ds_read_b128 v[160:163], v200 offset:0
	ds_read_b128 v[164:167], v202 offset:0
	ds_read_b128 v[172:175], v200 offset:2048
	ds_read_b128 v[176:179], v202 offset:2048
	ds_read_b128 v[128:131], v196 offset:0
	ds_read_b128 v[132:135], v198 offset:0
	ds_read_b128 v[136:139], v196 offset:2048
	ds_read_b128 v[140:143], v198 offset:2048
	ds_read_b128 v[144:147], v196 offset:4096
	ds_read_b128 v[148:151], v198 offset:4096
	ds_read_b128 v[152:155], v196 offset:6144
	ds_read_b128 v[156:159], v198 offset:6144
	s_waitcnt vmcnt(2)
	s_barrier
	s_waitcnt lgkmcnt(0)
	s_setprio 1
	v_mfma_f32_16x16x32_bf16 v[112:115], v[128:131], v[160:163], v[112:115]
	v_mfma_f32_16x16x32_bf16 v[112:115], v[132:135], v[164:167], v[112:115]
	v_mfma_f32_16x16x32_bf16 v[116:119], v[128:131], v[172:175], v[116:119]
	v_mfma_f32_16x16x32_bf16 v[116:119], v[132:135], v[176:179], v[116:119]
	v_mfma_f32_16x16x32_bf16 v[120:123], v[136:139], v[160:163], v[120:123]
	v_mfma_f32_16x16x32_bf16 v[120:123], v[140:143], v[164:167], v[120:123]
	v_mfma_f32_16x16x32_bf16 v[124:127], v[136:139], v[172:175], v[124:127]
	v_mfma_f32_16x16x32_bf16 v[124:127], v[140:143], v[176:179], v[124:127]
	v_mfma_f32_16x16x32_bf16 v[80:83], v[144:147], v[160:163], v[80:83]
	v_mfma_f32_16x16x32_bf16 v[80:83], v[148:151], v[164:167], v[80:83]
	v_mfma_f32_16x16x32_bf16 v[84:87], v[144:147], v[172:175], v[84:87]
	v_mfma_f32_16x16x32_bf16 v[84:87], v[148:151], v[176:179], v[84:87]
	v_mfma_f32_16x16x32_bf16 v[88:91], v[152:155], v[160:163], v[88:91]
	v_mfma_f32_16x16x32_bf16 v[88:91], v[156:159], v[164:167], v[88:91]
	v_mfma_f32_16x16x32_bf16 v[92:95], v[152:155], v[172:175], v[92:95]
	v_mfma_f32_16x16x32_bf16 v[92:95], v[156:159], v[176:179], v[92:95]
	s_setprio 0
	s_barrier
	ds_read_b128 v[180:183], v200 offset:16384
	ds_read_b128 v[184:187], v202 offset:16384
	ds_read_b128 v[188:191], v200 offset:18432
	ds_read_b128 v[192:195], v202 offset:18432
	s_waitcnt vmcnt(0)
	s_barrier
	s_waitcnt lgkmcnt(0)
	s_setprio 1
	v_mfma_f32_16x16x32_bf16 v[48:51], v[128:131], v[180:183], v[48:51]
	v_mfma_f32_16x16x32_bf16 v[48:51], v[132:135], v[184:187], v[48:51]
	v_mfma_f32_16x16x32_bf16 v[52:55], v[128:131], v[188:191], v[52:55]
	v_mfma_f32_16x16x32_bf16 v[52:55], v[132:135], v[192:195], v[52:55]
	v_mfma_f32_16x16x32_bf16 v[56:59], v[136:139], v[180:183], v[56:59]
	v_mfma_f32_16x16x32_bf16 v[56:59], v[140:143], v[184:187], v[56:59]
	v_mfma_f32_16x16x32_bf16 v[60:63], v[136:139], v[188:191], v[60:63]
	v_mfma_f32_16x16x32_bf16 v[60:63], v[140:143], v[192:195], v[60:63]
	v_mfma_f32_16x16x32_bf16 v[16:19], v[144:147], v[180:183], v[16:19]
	v_mfma_f32_16x16x32_bf16 v[16:19], v[148:151], v[184:187], v[16:19]
	v_mfma_f32_16x16x32_bf16 v[20:23], v[144:147], v[188:191], v[20:23]
	v_mfma_f32_16x16x32_bf16 v[20:23], v[148:151], v[192:195], v[20:23]
	v_mfma_f32_16x16x32_bf16 v[24:27], v[152:155], v[180:183], v[24:27]
	v_mfma_f32_16x16x32_bf16 v[24:27], v[156:159], v[184:187], v[24:27]
	v_mfma_f32_16x16x32_bf16 v[28:31], v[152:155], v[188:191], v[28:31]
	v_mfma_f32_16x16x32_bf16 v[28:31], v[156:159], v[192:195], v[28:31]
	s_setprio 0
	s_barrier
	ds_read_b128 v[128:131], v196 offset:16384
	ds_read_b128 v[132:135], v198 offset:16384
	ds_read_b128 v[136:139], v196 offset:18432
	ds_read_b128 v[140:143], v198 offset:18432
	ds_read_b128 v[144:147], v196 offset:20480
	ds_read_b128 v[148:151], v198 offset:20480
	ds_read_b128 v[152:155], v196 offset:22528
	ds_read_b128 v[156:159], v198 offset:22528
	s_barrier
	s_waitcnt lgkmcnt(0)
	s_setprio 1
	v_mfma_f32_16x16x32_bf16 v[96:99], v[128:131], v[160:163], v[96:99]
	v_mfma_f32_16x16x32_bf16 v[96:99], v[132:135], v[164:167], v[96:99]
	v_mfma_f32_16x16x32_bf16 v[100:103], v[128:131], v[172:175], v[100:103]
	v_mfma_f32_16x16x32_bf16 v[100:103], v[132:135], v[176:179], v[100:103]
	v_mfma_f32_16x16x32_bf16 v[104:107], v[136:139], v[160:163], v[104:107]
	v_mfma_f32_16x16x32_bf16 v[104:107], v[140:143], v[164:167], v[104:107]
	v_mfma_f32_16x16x32_bf16 v[108:111], v[136:139], v[172:175], v[108:111]
	v_mfma_f32_16x16x32_bf16 v[108:111], v[140:143], v[176:179], v[108:111]
	v_mfma_f32_16x16x32_bf16 v[64:67], v[144:147], v[160:163], v[64:67]
	v_mfma_f32_16x16x32_bf16 v[64:67], v[148:151], v[164:167], v[64:67]
	v_mfma_f32_16x16x32_bf16 v[68:71], v[144:147], v[172:175], v[68:71]
	v_mfma_f32_16x16x32_bf16 v[68:71], v[148:151], v[176:179], v[68:71]
	v_mfma_f32_16x16x32_bf16 v[72:75], v[152:155], v[160:163], v[72:75]
	v_mfma_f32_16x16x32_bf16 v[72:75], v[156:159], v[164:167], v[72:75]
	v_mfma_f32_16x16x32_bf16 v[76:79], v[152:155], v[172:175], v[76:79]
	v_mfma_f32_16x16x32_bf16 v[76:79], v[156:159], v[176:179], v[76:79]
	s_setprio 0
	s_setprio 1
	v_mfma_f32_16x16x32_bf16 v[32:35], v[128:131], v[180:183], v[32:35]
	v_mfma_f32_16x16x32_bf16 v[32:35], v[132:135], v[184:187], v[32:35]
	v_mfma_f32_16x16x32_bf16 v[36:39], v[128:131], v[188:191], v[36:39]
	v_mfma_f32_16x16x32_bf16 v[36:39], v[132:135], v[192:195], v[36:39]
	v_mfma_f32_16x16x32_bf16 v[40:43], v[136:139], v[180:183], v[40:43]
	v_mfma_f32_16x16x32_bf16 v[40:43], v[140:143], v[184:187], v[40:43]
	v_mfma_f32_16x16x32_bf16 v[44:47], v[136:139], v[188:191], v[44:47]
	v_mfma_f32_16x16x32_bf16 v[44:47], v[140:143], v[192:195], v[44:47]
	v_mfma_f32_16x16x32_bf16 v[0:3], v[144:147], v[180:183], v[0:3]
	v_mfma_f32_16x16x32_bf16 v[0:3], v[148:151], v[184:187], v[0:3]
	v_mfma_f32_16x16x32_bf16 v[4:7], v[144:147], v[188:191], v[4:7]
	v_mfma_f32_16x16x32_bf16 v[4:7], v[148:151], v[192:195], v[4:7]
	v_mfma_f32_16x16x32_bf16 v[8:11], v[152:155], v[180:183], v[8:11]
	v_mfma_f32_16x16x32_bf16 v[8:11], v[156:159], v[184:187], v[8:11]
	v_mfma_f32_16x16x32_bf16 v[12:15], v[152:155], v[188:191], v[12:15]
	v_mfma_f32_16x16x32_bf16 v[12:15], v[156:159], v[192:195], v[12:15]
	s_setprio 0
	s_barrier
	s_cmp_lg_u32 s100, 0
	s_cbranch_scc1 .Lg8_p2_gb1
	s_barrier

.LBB0_514:
	s_ashr_i32 s28, s1, 2
	s_ashr_i32 s29, s28, 31
	s_and_b32 s42, s1, 3
	v_lshrrev_b32_e32 v212, 6, v208
	v_and_b32_e32 v213, 63, v208
	v_readfirstlane_b32 s98, v212
	v_and_b32_e32 v214, 3, v213
	v_bfe_u32 v215, v213, 2, 1
	v_lshl_or_b32 v214, v215, 3, v214
	v_bfe_u32 v215, v213, 3, 1
	v_lshl_or_b32 v214, v215, 2, v214
	s_and_b32 s2, s98, 1
	s_lshr_b32 s100, s98, 2
	s_lshl_b32 s99, s98, 10
	v_lshrrev_b32_e32 v215, 4, v213
	v_bfe_u32 v216, v214, 1, 3
	v_xor_b32_e32 v216, v215, v216
	v_lshlrev_b32_e32 v216, 4, v216
	v_lshl_add_u32 v214, s2, 6, v214
	v_lshl_add_u32 v184, v214, 7, v216
	v_xor_b32_e32 v187, 64, v184
	v_add_u32_e32 v186, 0x10000, v184
	v_add_u32_e32 v196, 0x10000, v187
	v_bfe_u32 v216, v213, 1, 3
	v_xor_b32_e32 v216, v215, v216
	v_lshlrev_b32_e32 v216, 4, v216
	v_and_b32_e32 v214, 15, v213
	s_lshr_b32 s101, s98, 1
	v_lshl_add_u32 v214, s101, 5, v214
	v_lshl_add_u32 v197, v214, 7, v216
	v_add_u32_e32 v197, 0x8000, v197
	v_xor_b32_e32 v199, 64, v197
	v_add_u32_e32 v198, 0x10000, v197
	v_add_u32_e32 v200, 0x10000, v199
	v_lshl_add_u32 v216, s2, 2, v215
	v_and_b32_e32 v214, 7, v213
	v_xor_b32_e32 v216, v214, v216
	v_lshlrev_b32_e32 v216, 4, v216
	v_lshrrev_b32_e32 v214, 3, v213
	v_lshl_add_u32 v215, s98, 3, v214
	v_lshl_add_u32 v201, v215, 12, v216
	v_add_u32_e32 v202, 0x80000, v201
	v_add_u32_e32 v203, 0x40000, v201
	v_add_u32_e32 v204, 0xc0000, v201
	s_and_b32 s101, s98, 3
	s_lshl_b32 s101, s101, 3
	s_lshl_b32 s2, s100, 6
	s_add_u32 s101, s101, s2
	v_add_u32_e32 v215, s101, v214
	v_lshl_add_u32 v205, v215, 12, v216
	v_add_u32_e32 v206, 0x80000, v205
	v_add_u32_e32 v210, 0x20000, v205
	v_add_u32_e32 v211, 0xa0000, v205
	s_lshl_b64 s[44:45], s[28:29], 20
	s_add_u32 s44, s61, s44
	s_addc_u32 s45, s62, s45
	s_lshl_b32 s2, s42, 20
	s_add_u32 s46, s30, s2
	s_addc_u32 s47, s31, 0
	s_add_u32 m0, s99, 0x8000
	s_nop 0
	global_load_lds_dwordx4 v205, s[44:45]
	s_add_u32 m0, s99, 0xa000
	s_nop 0
	global_load_lds_dwordx4 v206, s[44:45]
	s_add_u32 m0, s99, 0x0
	s_nop 0
	global_load_lds_dwordx4 v201, s[46:47]
	s_add_u32 m0, s99, 0x2000
	s_nop 0
	global_load_lds_dwordx4 v202, s[46:47]
	s_add_u32 m0, s99, 0xc000
	s_nop 0
	global_load_lds_dwordx4 v210, s[44:45]
	s_add_u32 m0, s99, 0xe000
	s_nop 0
	global_load_lds_dwordx4 v211, s[44:45]
	s_add_u32 m0, s99, 0x4000
	s_nop 0
	global_load_lds_dwordx4 v203, s[46:47]
	s_add_u32 m0, s99, 0x6000
	s_nop 0
	global_load_lds_dwordx4 v204, s[46:47]
	v_mov_b32_e32 v112, 0
	v_mov_b32_e32 v113, 0
	v_mov_b32_e32 v114, 0
	v_mov_b32_e32 v115, 0
	v_mov_b32_e32 v116, 0
	v_mov_b32_e32 v117, 0
	v_mov_b32_e32 v118, 0
	v_mov_b32_e32 v119, 0
	v_mov_b32_e32 v120, 0
	v_mov_b32_e32 v121, 0
	v_mov_b32_e32 v122, 0
	v_mov_b32_e32 v123, 0
	v_mov_b32_e32 v124, 0
	v_mov_b32_e32 v125, 0
	v_mov_b32_e32 v126, 0
	v_mov_b32_e32 v127, 0
	v_mov_b32_e32 v96, 0
	v_mov_b32_e32 v97, 0
	v_mov_b32_e32 v98, 0
	v_mov_b32_e32 v99, 0
	v_mov_b32_e32 v100, 0
	v_mov_b32_e32 v101, 0
	v_mov_b32_e32 v102, 0
	v_mov_b32_e32 v103, 0
	v_mov_b32_e32 v104, 0
	v_mov_b32_e32 v105, 0
	v_mov_b32_e32 v106, 0
	v_mov_b32_e32 v107, 0
	v_mov_b32_e32 v108, 0
	v_mov_b32_e32 v109, 0
	v_mov_b32_e32 v110, 0
	v_mov_b32_e32 v111, 0
	v_mov_b32_e32 v64, 0
	v_mov_b32_e32 v65, 0
	v_mov_b32_e32 v66, 0
	v_mov_b32_e32 v67, 0
	v_mov_b32_e32 v68, 0
	v_mov_b32_e32 v69, 0
	v_mov_b32_e32 v70, 0
	v_mov_b32_e32 v71, 0
	v_mov_b32_e32 v72, 0
	v_mov_b32_e32 v73, 0
	v_mov_b32_e32 v74, 0
	v_mov_b32_e32 v75, 0
	v_mov_b32_e32 v76, 0
	v_mov_b32_e32 v77, 0
	v_mov_b32_e32 v78, 0
	v_mov_b32_e32 v79, 0
	v_mov_b32_e32 v80, 0
	v_mov_b32_e32 v81, 0
	v_mov_b32_e32 v82, 0
	v_mov_b32_e32 v83, 0
	v_mov_b32_e32 v84, 0
	v_mov_b32_e32 v85, 0
	v_mov_b32_e32 v86, 0
	v_mov_b32_e32 v87, 0
	v_mov_b32_e32 v88, 0
	v_mov_b32_e32 v89, 0
	v_mov_b32_e32 v90, 0
	v_mov_b32_e32 v91, 0
	v_mov_b32_e32 v92, 0
	v_mov_b32_e32 v93, 0
	v_mov_b32_e32 v94, 0
	v_mov_b32_e32 v95, 0
	v_mov_b32_e32 v48, 0
	v_mov_b32_e32 v49, 0
	v_mov_b32_e32 v50, 0
	v_mov_b32_e32 v51, 0
	v_mov_b32_e32 v52, 0
	v_mov_b32_e32 v53, 0
	v_mov_b32_e32 v54, 0
	v_mov_b32_e32 v55, 0
	v_mov_b32_e32 v56, 0
	v_mov_b32_e32 v57, 0
	v_mov_b32_e32 v58, 0
	v_mov_b32_e32 v59, 0
	v_mov_b32_e32 v60, 0
	v_mov_b32_e32 v61, 0
	v_mov_b32_e32 v62, 0
	v_mov_b32_e32 v63, 0
	v_mov_b32_e32 v32, 0
	v_mov_b32_e32 v33, 0
	v_mov_b32_e32 v34, 0
	v_mov_b32_e32 v35, 0
	v_mov_b32_e32 v36, 0
	v_mov_b32_e32 v37, 0
	v_mov_b32_e32 v38, 0
	v_mov_b32_e32 v39, 0
	v_mov_b32_e32 v40, 0
	v_mov_b32_e32 v41, 0
	v_mov_b32_e32 v42, 0
	v_mov_b32_e32 v43, 0
	v_mov_b32_e32 v44, 0
	v_mov_b32_e32 v45, 0
	v_mov_b32_e32 v46, 0
	v_mov_b32_e32 v47, 0
	v_mov_b32_e32 v16, 0
	v_mov_b32_e32 v17, 0
	v_mov_b32_e32 v18, 0
	v_mov_b32_e32 v19, 0
	v_mov_b32_e32 v20, 0
	v_mov_b32_e32 v21, 0
	v_mov_b32_e32 v22, 0
	v_mov_b32_e32 v23, 0
	v_mov_b32_e32 v24, 0
	v_mov_b32_e32 v25, 0
	v_mov_b32_e32 v26, 0
	v_mov_b32_e32 v27, 0
	v_mov_b32_e32 v28, 0
	v_mov_b32_e32 v29, 0
	v_mov_b32_e32 v30, 0
	v_mov_b32_e32 v31, 0
	v_mov_b32_e32 v0, 0
	v_mov_b32_e32 v1, 0
	v_mov_b32_e32 v2, 0
	v_mov_b32_e32 v3, 0
	v_mov_b32_e32 v4, 0
	v_mov_b32_e32 v5, 0
	v_mov_b32_e32 v6, 0
	v_mov_b32_e32 v7, 0
	v_mov_b32_e32 v8, 0
	v_mov_b32_e32 v9, 0
	v_mov_b32_e32 v10, 0
	v_mov_b32_e32 v11, 0
	v_mov_b32_e32 v12, 0
	v_mov_b32_e32 v13, 0
	v_mov_b32_e32 v14, 0
	v_mov_b32_e32 v15, 0
	s_cmp_eq_u32 s100, 0
	s_cbranch_scc1 .Lg8_p4_gb0
	s_barrier
.Lg8_p4_gb0:
	s_waitcnt vmcnt(4)
	s_barrier
	s_add_u32 s44, s44, 0x80
	s_addc_u32 s45, s45, 0
	s_add_u32 m0, s99, 0x18000
	s_nop 0
	global_load_lds_dwordx4 v205, s[44:45]
	s_add_u32 m0, s99, 0x1a000
	s_nop 0
	global_load_lds_dwordx4 v206, s[44:45]
	s_add_u32 s46, s46, 0x80
	s_addc_u32 s47, s47, 0
	s_add_u32 m0, s99, 0x10000
	s_nop 0
	global_load_lds_dwordx4 v201, s[46:47]
	s_add_u32 m0, s99, 0x12000
	s_nop 0
	global_load_lds_dwordx4 v202, s[46:47]
	s_add_u32 m0, s99, 0x1c000
	s_nop 0
	global_load_lds_dwordx4 v210, s[44:45]
	s_add_u32 m0, s99, 0x1e000
	s_nop 0
	global_load_lds_dwordx4 v211, s[44:45]
	s_waitcnt vmcnt(6)
	s_barrier
	s_mov_b32 s101, 15
.Lg8_p4_loop:
	ds_read_b128 v[160:163], v197 offset:0
	ds_read_b128 v[164:167], v199 offset:0
	ds_read_b128 v[168:171], v197 offset:2048
	ds_read_b128 v[172:175], v199 offset:2048
	ds_read_b128 v[128:131], v184 offset:0
	ds_read_b128 v[132:135], v187 offset:0
	ds_read_b128 v[136:139], v184 offset:2048
	ds_read_b128 v[140:143], v187 offset:2048
	ds_read_b128 v[144:147], v184 offset:4096
	ds_read_b128 v[148:151], v187 offset:4096
	ds_read_b128 v[152:155], v184 offset:6144
	ds_read_b128 v[156:159], v187 offset:6144
	s_add_u32 m0, s99, 0x14000
	s_nop 0
	global_load_lds_dwordx4 v203, s[46:47]
	s_add_u32 m0, s99, 0x16000
	s_nop 0
	global_load_lds_dwordx4 v204, s[46:47]
	s_waitcnt lgkmcnt(8)
	s_barrier
	s_waitcnt lgkmcnt(0)
	s_setprio 1
	v_mfma_f32_16x16x32_bf16 v[112:115], v[128:131], v[160:163], v[112:115]
	v_mfma_f32_16x16x32_bf16 v[112:115], v[132:135], v[164:167], v[112:115]
	v_mfma_f32_16x16x32_bf16 v[116:119], v[128:131], v[168:171], v[116:119]
	v_mfma_f32_16x16x32_bf16 v[116:119], v[132:135], v[172:175], v[116:119]
	v_mfma_f32_16x16x32_bf16 v[120:123], v[136:139], v[160:163], v[120:123]
	v_mfma_f32_16x16x32_bf16 v[120:123], v[140:143], v[164:167], v[120:123]
	v_mfma_f32_16x16x32_bf16 v[124:127], v[136:139], v[168:171], v[124:127]
	v_mfma_f32_16x16x32_bf16 v[124:127], v[140:143], v[172:175], v[124:127]
	v_mfma_f32_16x16x32_bf16 v[96:99], v[144:147], v[160:163], v[96:99]
	v_mfma_f32_16x16x32_bf16 v[96:99], v[148:151], v[164:167], v[96:99]
	v_mfma_f32_16x16x32_bf16 v[100:103], v[144:147], v[168:171], v[100:103]
	v_mfma_f32_16x16x32_bf16 v[100:103], v[148:151], v[172:175], v[100:103]
	v_mfma_f32_16x16x32_bf16 v[104:107], v[152:155], v[160:163], v[104:107]
	v_mfma_f32_16x16x32_bf16 v[104:107], v[156:159], v[164:167], v[104:107]
	v_mfma_f32_16x16x32_bf16 v[108:111], v[152:155], v[168:171], v[108:111]
	v_mfma_f32_16x16x32_bf16 v[108:111], v[156:159], v[172:175], v[108:111]
	s_setprio 0
	s_barrier
	ds_read_b128 v[176:179], v197 offset:16384
	ds_read_b128 v[180:183], v199 offset:16384
	ds_read_b128 v[188:191], v197 offset:18432
	ds_read_b128 v[192:195], v199 offset:18432
	s_add_u32 s44, s44, 0x80
	s_addc_u32 s45, s45, 0
	s_add_u32 m0, s99, 0x8000
	s_nop 0
	global_load_lds_dwordx4 v205, s[44:45]
	s_add_u32 m0, s99, 0xa000
	s_nop 0
	global_load_lds_dwordx4 v206, s[44:45]
	s_barrier
	s_waitcnt lgkmcnt(0)
	s_setprio 1
	v_mfma_f32_16x16x32_bf16 v[48:51], v[128:131], v[176:179], v[48:51]
	v_mfma_f32_16x16x32_bf16 v[48:51], v[132:135], v[180:183], v[48:51]
	v_mfma_f32_16x16x32_bf16 v[52:55], v[128:131], v[188:191], v[52:55]
	v_mfma_f32_16x16x32_bf16 v[52:55], v[132:135], v[192:195], v[52:55]
	v_mfma_f32_16x16x32_bf16 v[56:59], v[136:139], v[176:179], v[56:59]
	v_mfma_f32_16x16x32_bf16 v[56:59], v[140:143], v[180:183], v[56:59]
	v_mfma_f32_16x16x32_bf16 v[60:63], v[136:139], v[188:191], v[60:63]
	v_mfma_f32_16x16x32_bf16 v[60:63], v[140:143], v[192:195], v[60:63]
	v_mfma_f32_16x16x32_bf16 v[32:35], v[144:147], v[176:179], v[32:35]
	v_mfma_f32_16x16x32_bf16 v[32:35], v[148:151], v[180:183], v[32:35]
	v_mfma_f32_16x16x32_bf16 v[36:39], v[144:147], v[188:191], v[36:39]
	v_mfma_f32_16x16x32_bf16 v[36:39], v[148:151], v[192:195], v[36:39]
	v_mfma_f32_16x16x32_bf16 v[40:43], v[152:155], v[176:179], v[40:43]
	v_mfma_f32_16x16x32_bf16 v[40:43], v[156:159], v[180:183], v[40:43]
	v_mfma_f32_16x16x32_bf16 v[44:47], v[152:155], v[188:191], v[44:47]
	v_mfma_f32_16x16x32_bf16 v[44:47], v[156:159], v[192:195], v[44:47]
	s_setprio 0
	s_barrier
	ds_read_b128 v[128:131], v184 offset:16384
	ds_read_b128 v[132:135], v187 offset:16384
	ds_read_b128 v[136:139], v184 offset:18432
	ds_read_b128 v[140:143], v187 offset:18432
	ds_read_b128 v[144:147], v184 offset:20480
	ds_read_b128 v[148:151], v187 offset:20480
	ds_read_b128 v[152:155], v184 offset:22528
	ds_read_b128 v[156:159], v187 offset:22528
	s_add_u32 s46, s46, 0x80
	s_addc_u32 s47, s47, 0
	s_add_u32 m0, s99, 0x0
	s_nop 0
	global_load_lds_dwordx4 v201, s[46:47]
	s_add_u32 m0, s99, 0x2000
	s_nop 0
	global_load_lds_dwordx4 v202, s[46:47]
	s_barrier
	s_waitcnt lgkmcnt(0)
	s_setprio 1
	v_mfma_f32_16x16x32_bf16 v[64:67], v[128:131], v[160:163], v[64:67]
	v_mfma_f32_16x16x32_bf16 v[64:67], v[132:135], v[164:167], v[64:67]
	v_mfma_f32_16x16x32_bf16 v[68:71], v[128:131], v[168:171], v[68:71]
	v_mfma_f32_16x16x32_bf16 v[68:71], v[132:135], v[172:175], v[68:71]
	v_mfma_f32_16x16x32_bf16 v[72:75], v[136:139], v[160:163], v[72:75]
	v_mfma_f32_16x16x32_bf16 v[72:75], v[140:143], v[164:167], v[72:75]
	v_mfma_f32_16x16x32_bf16 v[76:79], v[136:139], v[168:171], v[76:79]
	v_mfma_f32_16x16x32_bf16 v[76:79], v[140:143], v[172:175], v[76:79]
	v_mfma_f32_16x16x32_bf16 v[80:83], v[144:147], v[160:163], v[80:83]
	v_mfma_f32_16x16x32_bf16 v[80:83], v[148:151], v[164:167], v[80:83]
	v_mfma_f32_16x16x32_bf16 v[84:87], v[144:147], v[168:171], v[84:87]
	v_mfma_f32_16x16x32_bf16 v[84:87], v[148:151], v[172:175], v[84:87]
	v_mfma_f32_16x16x32_bf16 v[88:91], v[152:155], v[160:163], v[88:91]
	v_mfma_f32_16x16x32_bf16 v[88:91], v[156:159], v[164:167], v[88:91]
	v_mfma_f32_16x16x32_bf16 v[92:95], v[152:155], v[168:171], v[92:95]
	v_mfma_f32_16x16x32_bf16 v[92:95], v[156:159], v[172:175], v[92:95]
	s_setprio 0
	s_barrier
	s_add_u32 m0, s99, 0xc000
	s_nop 0
	global_load_lds_dwordx4 v210, s[44:45]
	s_add_u32 m0, s99, 0xe000
	s_nop 0
	global_load_lds_dwordx4 v211, s[44:45]
	s_waitcnt vmcnt(6)
	s_barrier
	s_setprio 1
	v_mfma_f32_16x16x32_bf16 v[16:19], v[128:131], v[176:179], v[16:19]
	v_mfma_f32_16x16x32_bf16 v[16:19], v[132:135], v[180:183], v[16:19]
	v_mfma_f32_16x16x32_bf16 v[20:23], v[128:131], v[188:191], v[20:23]
	v_mfma_f32_16x16x32_bf16 v[20:23], v[132:135], v[192:195], v[20:23]
	v_mfma_f32_16x16x32_bf16 v[24:27], v[136:139], v[176:179], v[24:27]
	v_mfma_f32_16x16x32_bf16 v[24:27], v[140:143], v[180:183], v[24:27]
	v_mfma_f32_16x16x32_bf16 v[28:31], v[136:139], v[188:191], v[28:31]
	v_mfma_f32_16x16x32_bf16 v[28:31], v[140:143], v[192:195], v[28:31]
	v_mfma_f32_16x16x32_bf16 v[0:3], v[144:147], v[176:179], v[0:3]
	v_mfma_f32_16x16x32_bf16 v[0:3], v[148:151], v[180:183], v[0:3]
	v_mfma_f32_16x16x32_bf16 v[4:7], v[144:147], v[188:191], v[4:7]
	v_mfma_f32_16x16x32_bf16 v[4:7], v[148:151], v[192:195], v[4:7]
	v_mfma_f32_16x16x32_bf16 v[8:11], v[152:155], v[176:179], v[8:11]
	v_mfma_f32_16x16x32_bf16 v[8:11], v[156:159], v[180:183], v[8:11]
	v_mfma_f32_16x16x32_bf16 v[12:15], v[152:155], v[188:191], v[12:15]
	v_mfma_f32_16x16x32_bf16 v[12:15], v[156:159], v[192:195], v[12:15]
	s_setprio 0
	s_barrier
	ds_read_b128 v[160:163], v198 offset:0
	ds_read_b128 v[164:167], v200 offset:0
	ds_read_b128 v[168:171], v198 offset:2048
	ds_read_b128 v[172:175], v200 offset:2048
	ds_read_b128 v[128:131], v186 offset:0
	ds_read_b128 v[132:135], v196 offset:0
	ds_read_b128 v[136:139], v186 offset:2048
	ds_read_b128 v[140:143], v196 offset:2048
	ds_read_b128 v[144:147], v186 offset:4096
	ds_read_b128 v[148:151], v196 offset:4096
	ds_read_b128 v[152:155], v186 offset:6144
	ds_read_b128 v[156:159], v196 offset:6144
	s_add_u32 m0, s99, 0x4000
	s_nop 0
	global_load_lds_dwordx4 v203, s[46:47]
	s_add_u32 m0, s99, 0x6000
	s_nop 0
	global_load_lds_dwordx4 v204, s[46:47]
	s_waitcnt lgkmcnt(8)
	s_barrier
	s_waitcnt lgkmcnt(0)
	s_setprio 1
	v_mfma_f32_16x16x32_bf16 v[112:115], v[128:131], v[160:163], v[112:115]
	v_mfma_f32_16x16x32_bf16 v[112:115], v[132:135], v[164:167], v[112:115]
	v_mfma_f32_16x16x32_bf16 v[116:119], v[128:131], v[168:171], v[116:119]
	v_mfma_f32_16x16x32_bf16 v[116:119], v[132:135], v[172:175], v[116:119]
	v_mfma_f32_16x16x32_bf16 v[120:123], v[136:139], v[160:163], v[120:123]
	v_mfma_f32_16x16x32_bf16 v[120:123], v[140:143], v[164:167], v[120:123]
	v_mfma_f32_16x16x32_bf16 v[124:127], v[136:139], v[168:171], v[124:127]
	v_mfma_f32_16x16x32_bf16 v[124:127], v[140:143], v[172:175], v[124:127]
	v_mfma_f32_16x16x32_bf16 v[96:99], v[144:147], v[160:163], v[96:99]
	v_mfma_f32_16x16x32_bf16 v[96:99], v[148:151], v[164:167], v[96:99]
	v_mfma_f32_16x16x32_bf16 v[100:103], v[144:147], v[168:171], v[100:103]
	v_mfma_f32_16x16x32_bf16 v[100:103], v[148:151], v[172:175], v[100:103]
	v_mfma_f32_16x16x32_bf16 v[104:107], v[152:155], v[160:163], v[104:107]
	v_mfma_f32_16x16x32_bf16 v[104:107], v[156:159], v[164:167], v[104:107]
	v_mfma_f32_16x16x32_bf16 v[108:111], v[152:155], v[168:171], v[108:111]
	v_mfma_f32_16x16x32_bf16 v[108:111], v[156:159], v[172:175], v[108:111]
	s_setprio 0
	s_barrier
	ds_read_b128 v[176:179], v198 offset:16384
	ds_read_b128 v[180:183], v200 offset:16384
	ds_read_b128 v[188:191], v198 offset:18432
	ds_read_b128 v[192:195], v200 offset:18432
	s_add_u32 s44, s44, 0x80
	s_addc_u32 s45, s45, 0
	s_add_u32 m0, s99, 0x18000
	s_nop 0
	global_load_lds_dwordx4 v205, s[44:45]
	s_add_u32 m0, s99, 0x1a000
	s_nop 0
	global_load_lds_dwordx4 v206, s[44:45]
	s_barrier
	s_waitcnt lgkmcnt(0)
	s_setprio 1
	v_mfma_f32_16x16x32_bf16 v[48:51], v[128:131], v[176:179], v[48:51]
	v_mfma_f32_16x16x32_bf16 v[48:51], v[132:135], v[180:183], v[48:51]
	v_mfma_f32_16x16x32_bf16 v[52:55], v[128:131], v[188:191], v[52:55]
	v_mfma_f32_16x16x32_bf16 v[52:55], v[132:135], v[192:195], v[52:55]
	v_mfma_f32_16x16x32_bf16 v[56:59], v[136:139], v[176:179], v[56:59]
	v_mfma_f32_16x16x32_bf16 v[56:59], v[140:143], v[180:183], v[56:59]
	v_mfma_f32_16x16x32_bf16 v[60:63], v[136:139], v[188:191], v[60:63]
	v_mfma_f32_16x16x32_bf16 v[60:63], v[140:143], v[192:195], v[60:63]
	v_mfma_f32_16x16x32_bf16 v[32:35], v[144:147], v[176:179], v[32:35]
	v_mfma_f32_16x16x32_bf16 v[32:35], v[148:151], v[180:183], v[32:35]
	v_mfma_f32_16x16x32_bf16 v[36:39], v[144:147], v[188:191], v[36:39]
	v_mfma_f32_16x16x32_bf16 v[36:39], v[148:151], v[192:195], v[36:39]
	v_mfma_f32_16x16x32_bf16 v[40:43], v[152:155], v[176:179], v[40:43]
	v_mfma_f32_16x16x32_bf16 v[40:43], v[156:159], v[180:183], v[40:43]
	v_mfma_f32_16x16x32_bf16 v[44:47], v[152:155], v[188:191], v[44:47]
	v_mfma_f32_16x16x32_bf16 v[44:47], v[156:159], v[192:195], v[44:47]
	s_setprio 0
	s_barrier
	ds_read_b128 v[128:131], v186 offset:16384
	ds_read_b128 v[132:135], v196 offset:16384
	ds_read_b128 v[136:139], v186 offset:18432
	ds_read_b128 v[140:143], v196 offset:18432
	ds_read_b128 v[144:147], v186 offset:20480
	ds_read_b128 v[148:151], v196 offset:20480
	ds_read_b128 v[152:155], v186 offset:22528
	ds_read_b128 v[156:159], v196 offset:22528
	s_add_u32 s46, s46, 0x80
	s_addc_u32 s47, s47, 0
	s_add_u32 m0, s99, 0x10000
	s_nop 0
	global_load_lds_dwordx4 v201, s[46:47]
	s_add_u32 m0, s99, 0x12000
	s_nop 0
	global_load_lds_dwordx4 v202, s[46:47]
	s_barrier
	s_waitcnt lgkmcnt(0)
	s_setprio 1
	v_mfma_f32_16x16x32_bf16 v[64:67], v[128:131], v[160:163], v[64:67]
	v_mfma_f32_16x16x32_bf16 v[64:67], v[132:135], v[164:167], v[64:67]
	v_mfma_f32_16x16x32_bf16 v[68:71], v[128:131], v[168:171], v[68:71]
	v_mfma_f32_16x16x32_bf16 v[68:71], v[132:135], v[172:175], v[68:71]
	v_mfma_f32_16x16x32_bf16 v[72:75], v[136:139], v[160:163], v[72:75]
	v_mfma_f32_16x16x32_bf16 v[72:75], v[140:143], v[164:167], v[72:75]
	v_mfma_f32_16x16x32_bf16 v[76:79], v[136:139], v[168:171], v[76:79]
	v_mfma_f32_16x16x32_bf16 v[76:79], v[140:143], v[172:175], v[76:79]
	v_mfma_f32_16x16x32_bf16 v[80:83], v[144:147], v[160:163], v[80:83]
	v_mfma_f32_16x16x32_bf16 v[80:83], v[148:151], v[164:167], v[80:83]
	v_mfma_f32_16x16x32_bf16 v[84:87], v[144:147], v[168:171], v[84:87]
	v_mfma_f32_16x16x32_bf16 v[84:87], v[148:151], v[172:175], v[84:87]
	v_mfma_f32_16x16x32_bf16 v[88:91], v[152:155], v[160:163], v[88:91]
	v_mfma_f32_16x16x32_bf16 v[88:91], v[156:159], v[164:167], v[88:91]
	v_mfma_f32_16x16x32_bf16 v[92:95], v[152:155], v[168:171], v[92:95]
	v_mfma_f32_16x16x32_bf16 v[92:95], v[156:159], v[172:175], v[92:95]
	s_setprio 0
	s_barrier
	s_add_u32 m0, s99, 0x1c000
	s_nop 0
	global_load_lds_dwordx4 v210, s[44:45]
	s_add_u32 m0, s99, 0x1e000
	s_nop 0
	global_load_lds_dwordx4 v211, s[44:45]
	s_waitcnt vmcnt(6)
	s_barrier
	s_setprio 1
	v_mfma_f32_16x16x32_bf16 v[16:19], v[128:131], v[176:179], v[16:19]
	v_mfma_f32_16x16x32_bf16 v[16:19], v[132:135], v[180:183], v[16:19]
	v_mfma_f32_16x16x32_bf16 v[20:23], v[128:131], v[188:191], v[20:23]
	v_mfma_f32_16x16x32_bf16 v[20:23], v[132:135], v[192:195], v[20:23]
	v_mfma_f32_16x16x32_bf16 v[24:27], v[136:139], v[176:179], v[24:27]
	v_mfma_f32_16x16x32_bf16 v[24:27], v[140:143], v[180:183], v[24:27]
	v_mfma_f32_16x16x32_bf16 v[28:31], v[136:139], v[188:191], v[28:31]
	v_mfma_f32_16x16x32_bf16 v[28:31], v[140:143], v[192:195], v[28:31]
	v_mfma_f32_16x16x32_bf16 v[0:3], v[144:147], v[176:179], v[0:3]
	v_mfma_f32_16x16x32_bf16 v[0:3], v[148:151], v[180:183], v[0:3]
	v_mfma_f32_16x16x32_bf16 v[4:7], v[144:147], v[188:191], v[4:7]
	v_mfma_f32_16x16x32_bf16 v[4:7], v[148:151], v[192:195], v[4:7]
	v_mfma_f32_16x16x32_bf16 v[8:11], v[152:155], v[176:179], v[8:11]
	v_mfma_f32_16x16x32_bf16 v[8:11], v[156:159], v[180:183], v[8:11]
	v_mfma_f32_16x16x32_bf16 v[12:15], v[152:155], v[188:191], v[12:15]
	v_mfma_f32_16x16x32_bf16 v[12:15], v[156:159], v[192:195], v[12:15]
	s_setprio 0
	s_barrier
	s_sub_u32 s101, s101, 1
	s_cmp_lg_u32 s101, 0
	s_cbranch_scc1 .Lg8_p4_loop
	ds_read_b128 v[160:163], v197 offset:0
	ds_read_b128 v[164:167], v199 offset:0
	ds_read_b128 v[168:171], v197 offset:2048
	ds_read_b128 v[172:175], v199 offset:2048
	ds_read_b128 v[128:131], v184 offset:0
	ds_read_b128 v[132:135], v187 offset:0
	ds_read_b128 v[136:139], v184 offset:2048
	ds_read_b128 v[140:143], v187 offset:2048
	ds_read_b128 v[144:147], v184 offset:4096
	ds_read_b128 v[148:151], v187 offset:4096
	ds_read_b128 v[152:155], v184 offset:6144
	ds_read_b128 v[156:159], v187 offset:6144
	s_add_u32 m0, s99, 0x14000
	s_nop 0
	global_load_lds_dwordx4 v203, s[46:47]
	s_add_u32 m0, s99, 0x16000
	s_nop 0
	global_load_lds_dwordx4 v204, s[46:47]
	s_barrier
	s_waitcnt lgkmcnt(0)
	s_setprio 1
	v_mfma_f32_16x16x32_bf16 v[112:115], v[128:131], v[160:163], v[112:115]
	v_mfma_f32_16x16x32_bf16 v[112:115], v[132:135], v[164:167], v[112:115]
	v_mfma_f32_16x16x32_bf16 v[116:119], v[128:131], v[168:171], v[116:119]
	v_mfma_f32_16x16x32_bf16 v[116:119], v[132:135], v[172:175], v[116:119]
	v_mfma_f32_16x16x32_bf16 v[120:123], v[136:139], v[160:163], v[120:123]
	v_mfma_f32_16x16x32_bf16 v[120:123], v[140:143], v[164:167], v[120:123]
	v_mfma_f32_16x16x32_bf16 v[124:127], v[136:139], v[168:171], v[124:127]
	v_mfma_f32_16x16x32_bf16 v[124:127], v[140:143], v[172:175], v[124:127]
	v_mfma_f32_16x16x32_bf16 v[96:99], v[144:147], v[160:163], v[96:99]
	v_mfma_f32_16x16x32_bf16 v[96:99], v[148:151], v[164:167], v[96:99]
	v_mfma_f32_16x16x32_bf16 v[100:103], v[144:147], v[168:171], v[100:103]
	v_mfma_f32_16x16x32_bf16 v[100:103], v[148:151], v[172:175], v[100:103]
	v_mfma_f32_16x16x32_bf16 v[104:107], v[152:155], v[160:163], v[104:107]
	v_mfma_f32_16x16x32_bf16 v[104:107], v[156:159], v[164:167], v[104:107]
	v_mfma_f32_16x16x32_bf16 v[108:111], v[152:155], v[168:171], v[108:111]
	v_mfma_f32_16x16x32_bf16 v[108:111], v[156:159], v[172:175], v[108:111]
	s_setprio 0
	s_barrier
	ds_read_b128 v[176:179], v197 offset:16384
	ds_read_b128 v[180:183], v199 offset:16384
	ds_read_b128 v[188:191], v197 offset:18432
	ds_read_b128 v[192:195], v199 offset:18432
	s_barrier
	s_waitcnt lgkmcnt(0)
	s_setprio 1
	v_mfma_f32_16x16x32_bf16 v[48:51], v[128:131], v[176:179], v[48:51]
	v_mfma_f32_16x16x32_bf16 v[48:51], v[132:135], v[180:183], v[48:51]
	v_mfma_f32_16x16x32_bf16 v[52:55], v[128:131], v[188:191], v[52:55]
	v_mfma_f32_16x16x32_bf16 v[52:55], v[132:135], v[192:195], v[52:55]
	v_mfma_f32_16x16x32_bf16 v[56:59], v[136:139], v[176:179], v[56:59]
	v_mfma_f32_16x16x32_bf16 v[56:59], v[140:143], v[180:183], v[56:59]
	v_mfma_f32_16x16x32_bf16 v[60:63], v[136:139], v[188:191], v[60:63]
	v_mfma_f32_16x16x32_bf16 v[60:63], v[140:143], v[192:195], v[60:63]
	v_mfma_f32_16x16x32_bf16 v[32:35], v[144:147], v[176:179], v[32:35]
	v_mfma_f32_16x16x32_bf16 v[32:35], v[148:151], v[180:183], v[32:35]
	v_mfma_f32_16x16x32_bf16 v[36:39], v[144:147], v[188:191], v[36:39]
	v_mfma_f32_16x16x32_bf16 v[36:39], v[148:151], v[192:195], v[36:39]
	v_mfma_f32_16x16x32_bf16 v[40:43], v[152:155], v[176:179], v[40:43]
	v_mfma_f32_16x16x32_bf16 v[40:43], v[156:159], v[180:183], v[40:43]
	v_mfma_f32_16x16x32_bf16 v[44:47], v[152:155], v[188:191], v[44:47]
	v_mfma_f32_16x16x32_bf16 v[44:47], v[156:159], v[192:195], v[44:47]
	s_setprio 0
	s_barrier
	ds_read_b128 v[128:131], v184 offset:16384
	ds_read_b128 v[132:135], v187 offset:16384
	ds_read_b128 v[136:139], v184 offset:18432
	ds_read_b128 v[140:143], v187 offset:18432
	ds_read_b128 v[144:147], v184 offset:20480
	ds_read_b128 v[148:151], v187 offset:20480
	ds_read_b128 v[152:155], v184 offset:22528
	ds_read_b128 v[156:159], v187 offset:22528
	s_waitcnt vmcnt(4)
	s_barrier
	s_waitcnt lgkmcnt(0)
	s_setprio 1
	v_mfma_f32_16x16x32_bf16 v[64:67], v[128:131], v[160:163], v[64:67]
	v_mfma_f32_16x16x32_bf16 v[64:67], v[132:135], v[164:167], v[64:67]
	v_mfma_f32_16x16x32_bf16 v[68:71], v[128:131], v[168:171], v[68:71]
	v_mfma_f32_16x16x32_bf16 v[68:71], v[132:135], v[172:175], v[68:71]
	v_mfma_f32_16x16x32_bf16 v[72:75], v[136:139], v[160:163], v[72:75]
	v_mfma_f32_16x16x32_bf16 v[72:75], v[140:143], v[164:167], v[72:75]
	v_mfma_f32_16x16x32_bf16 v[76:79], v[136:139], v[168:171], v[76:79]
	v_mfma_f32_16x16x32_bf16 v[76:79], v[140:143], v[172:175], v[76:79]
	v_mfma_f32_16x16x32_bf16 v[80:83], v[144:147], v[160:163], v[80:83]
	v_mfma_f32_16x16x32_bf16 v[80:83], v[148:151], v[164:167], v[80:83]
	v_mfma_f32_16x16x32_bf16 v[84:87], v[144:147], v[168:171], v[84:87]
	v_mfma_f32_16x16x32_bf16 v[84:87], v[148:151], v[172:175], v[84:87]
	v_mfma_f32_16x16x32_bf16 v[88:91], v[152:155], v[160:163], v[88:91]
	v_mfma_f32_16x16x32_bf16 v[88:91], v[156:159], v[164:167], v[88:91]
	v_mfma_f32_16x16x32_bf16 v[92:95], v[152:155], v[168:171], v[92:95]
	v_mfma_f32_16x16x32_bf16 v[92:95], v[156:159], v[172:175], v[92:95]
	s_setprio 0
	s_setprio 1
	v_mfma_f32_16x16x32_bf16 v[16:19], v[128:131], v[176:179], v[16:19]
	v_mfma_f32_16x16x32_bf16 v[16:19], v[132:135], v[180:183], v[16:19]
	v_mfma_f32_16x16x32_bf16 v[20:23], v[128:131], v[188:191], v[20:23]
	v_mfma_f32_16x16x32_bf16 v[20:23], v[132:135], v[192:195], v[20:23]
	v_mfma_f32_16x16x32_bf16 v[24:27], v[136:139], v[176:179], v[24:27]
	v_mfma_f32_16x16x32_bf16 v[24:27], v[140:143], v[180:183], v[24:27]
	v_mfma_f32_16x16x32_bf16 v[28:31], v[136:139], v[188:191], v[28:31]
	v_mfma_f32_16x16x32_bf16 v[28:31], v[140:143], v[192:195], v[28:31]
	v_mfma_f32_16x16x32_bf16 v[0:3], v[144:147], v[176:179], v[0:3]
	v_mfma_f32_16x16x32_bf16 v[0:3], v[148:151], v[180:183], v[0:3]
	v_mfma_f32_16x16x32_bf16 v[4:7], v[144:147], v[188:191], v[4:7]
	v_mfma_f32_16x16x32_bf16 v[4:7], v[148:151], v[192:195], v[4:7]
	v_mfma_f32_16x16x32_bf16 v[8:11], v[152:155], v[176:179], v[8:11]
	v_mfma_f32_16x16x32_bf16 v[8:11], v[156:159], v[180:183], v[8:11]
	v_mfma_f32_16x16x32_bf16 v[12:15], v[152:155], v[188:191], v[12:15]
	v_mfma_f32_16x16x32_bf16 v[12:15], v[156:159], v[192:195], v[12:15]
	s_setprio 0
	s_barrier
	ds_read_b128 v[160:163], v198 offset:0
	ds_read_b128 v[164:167], v200 offset:0
	ds_read_b128 v[168:171], v198 offset:2048
	ds_read_b128 v[172:175], v200 offset:2048
	ds_read_b128 v[128:131], v186 offset:0
	ds_read_b128 v[132:135], v196 offset:0
	ds_read_b128 v[136:139], v186 offset:2048
	ds_read_b128 v[140:143], v196 offset:2048
	ds_read_b128 v[144:147], v186 offset:4096
	ds_read_b128 v[148:151], v196 offset:4096
	ds_read_b128 v[152:155], v186 offset:6144
	ds_read_b128 v[156:159], v196 offset:6144
	s_waitcnt vmcnt(2)
	s_barrier
	s_waitcnt lgkmcnt(0)
	s_setprio 1
	v_mfma_f32_16x16x32_bf16 v[112:115], v[128:131], v[160:163], v[112:115]
	v_mfma_f32_16x16x32_bf16 v[112:115], v[132:135], v[164:167], v[112:115]
	v_mfma_f32_16x16x32_bf16 v[116:119], v[128:131], v[168:171], v[116:119]
	v_mfma_f32_16x16x32_bf16 v[116:119], v[132:135], v[172:175], v[116:119]
	v_mfma_f32_16x16x32_bf16 v[120:123], v[136:139], v[160:163], v[120:123]
	v_mfma_f32_16x16x32_bf16 v[120:123], v[140:143], v[164:167], v[120:123]
	v_mfma_f32_16x16x32_bf16 v[124:127], v[136:139], v[168:171], v[124:127]
	v_mfma_f32_16x16x32_bf16 v[124:127], v[140:143], v[172:175], v[124:127]
	v_mfma_f32_16x16x32_bf16 v[96:99], v[144:147], v[160:163], v[96:99]
	v_mfma_f32_16x16x32_bf16 v[96:99], v[148:151], v[164:167], v[96:99]
	v_mfma_f32_16x16x32_bf16 v[100:103], v[144:147], v[168:171], v[100:103]
	v_mfma_f32_16x16x32_bf16 v[100:103], v[148:151], v[172:175], v[100:103]
	v_mfma_f32_16x16x32_bf16 v[104:107], v[152:155], v[160:163], v[104:107]
	v_mfma_f32_16x16x32_bf16 v[104:107], v[156:159], v[164:167], v[104:107]
	v_mfma_f32_16x16x32_bf16 v[108:111], v[152:155], v[168:171], v[108:111]
	v_mfma_f32_16x16x32_bf16 v[108:111], v[156:159], v[172:175], v[108:111]
	s_setprio 0
	s_barrier
	ds_read_b128 v[176:179], v198 offset:16384
	ds_read_b128 v[180:183], v200 offset:16384
	ds_read_b128 v[188:191], v198 offset:18432
	ds_read_b128 v[192:195], v200 offset:18432
	s_waitcnt vmcnt(0)
	s_barrier
	s_waitcnt lgkmcnt(0)
	s_setprio 1
	v_mfma_f32_16x16x32_bf16 v[48:51], v[128:131], v[176:179], v[48:51]
	v_mfma_f32_16x16x32_bf16 v[48:51], v[132:135], v[180:183], v[48:51]
	v_mfma_f32_16x16x32_bf16 v[52:55], v[128:131], v[188:191], v[52:55]
	v_mfma_f32_16x16x32_bf16 v[52:55], v[132:135], v[192:195], v[52:55]
	v_mfma_f32_16x16x32_bf16 v[56:59], v[136:139], v[176:179], v[56:59]
	v_mfma_f32_16x16x32_bf16 v[56:59], v[140:143], v[180:183], v[56:59]
	v_mfma_f32_16x16x32_bf16 v[60:63], v[136:139], v[188:191], v[60:63]
	v_mfma_f32_16x16x32_bf16 v[60:63], v[140:143], v[192:195], v[60:63]
	v_mfma_f32_16x16x32_bf16 v[32:35], v[144:147], v[176:179], v[32:35]
	v_mfma_f32_16x16x32_bf16 v[32:35], v[148:151], v[180:183], v[32:35]
	v_mfma_f32_16x16x32_bf16 v[36:39], v[144:147], v[188:191], v[36:39]
	v_mfma_f32_16x16x32_bf16 v[36:39], v[148:151], v[192:195], v[36:39]
	v_mfma_f32_16x16x32_bf16 v[40:43], v[152:155], v[176:179], v[40:43]
	v_mfma_f32_16x16x32_bf16 v[40:43], v[156:159], v[180:183], v[40:43]
	v_mfma_f32_16x16x32_bf16 v[44:47], v[152:155], v[188:191], v[44:47]
	v_mfma_f32_16x16x32_bf16 v[44:47], v[156:159], v[192:195], v[44:47]
	s_setprio 0
	s_barrier
	ds_read_b128 v[128:131], v186 offset:16384
	ds_read_b128 v[132:135], v196 offset:16384
	ds_read_b128 v[136:139], v186 offset:18432
	ds_read_b128 v[140:143], v196 offset:18432
	ds_read_b128 v[144:147], v186 offset:20480
	ds_read_b128 v[148:151], v196 offset:20480
	ds_read_b128 v[152:155], v186 offset:22528
	ds_read_b128 v[156:159], v196 offset:22528
	s_barrier
	s_waitcnt lgkmcnt(0)
	s_setprio 1
	v_mfma_f32_16x16x32_bf16 v[64:67], v[128:131], v[160:163], v[64:67]
	v_mfma_f32_16x16x32_bf16 v[64:67], v[132:135], v[164:167], v[64:67]
	v_mfma_f32_16x16x32_bf16 v[68:71], v[128:131], v[168:171], v[68:71]
	v_mfma_f32_16x16x32_bf16 v[68:71], v[132:135], v[172:175], v[68:71]
	v_mfma_f32_16x16x32_bf16 v[72:75], v[136:139], v[160:163], v[72:75]
	v_mfma_f32_16x16x32_bf16 v[72:75], v[140:143], v[164:167], v[72:75]
	v_mfma_f32_16x16x32_bf16 v[76:79], v[136:139], v[168:171], v[76:79]
	v_mfma_f32_16x16x32_bf16 v[76:79], v[140:143], v[172:175], v[76:79]
	v_mfma_f32_16x16x32_bf16 v[80:83], v[144:147], v[160:163], v[80:83]
	v_mfma_f32_16x16x32_bf16 v[80:83], v[148:151], v[164:167], v[80:83]
	v_mfma_f32_16x16x32_bf16 v[84:87], v[144:147], v[168:171], v[84:87]
	v_mfma_f32_16x16x32_bf16 v[84:87], v[148:151], v[172:175], v[84:87]
	v_mfma_f32_16x16x32_bf16 v[88:91], v[152:155], v[160:163], v[88:91]
	v_mfma_f32_16x16x32_bf16 v[88:91], v[156:159], v[164:167], v[88:91]
	v_mfma_f32_16x16x32_bf16 v[92:95], v[152:155], v[168:171], v[92:95]
	v_mfma_f32_16x16x32_bf16 v[92:95], v[156:159], v[172:175], v[92:95]
	s_setprio 0
	s_setprio 1
	v_mfma_f32_16x16x32_bf16 v[16:19], v[128:131], v[176:179], v[16:19]
	v_mfma_f32_16x16x32_bf16 v[16:19], v[132:135], v[180:183], v[16:19]
	v_mfma_f32_16x16x32_bf16 v[20:23], v[128:131], v[188:191], v[20:23]
	v_mfma_f32_16x16x32_bf16 v[20:23], v[132:135], v[192:195], v[20:23]
	v_mfma_f32_16x16x32_bf16 v[24:27], v[136:139], v[176:179], v[24:27]
	v_mfma_f32_16x16x32_bf16 v[24:27], v[140:143], v[180:183], v[24:27]
	v_mfma_f32_16x16x32_bf16 v[28:31], v[136:139], v[188:191], v[28:31]
	v_mfma_f32_16x16x32_bf16 v[28:31], v[140:143], v[192:195], v[28:31]
	v_mfma_f32_16x16x32_bf16 v[0:3], v[144:147], v[176:179], v[0:3]
	v_mfma_f32_16x16x32_bf16 v[0:3], v[148:151], v[180:183], v[0:3]
	v_mfma_f32_16x16x32_bf16 v[4:7], v[144:147], v[188:191], v[4:7]
	v_mfma_f32_16x16x32_bf16 v[4:7], v[148:151], v[192:195], v[4:7]
	v_mfma_f32_16x16x32_bf16 v[8:11], v[152:155], v[176:179], v[8:11]
	v_mfma_f32_16x16x32_bf16 v[8:11], v[156:159], v[180:183], v[8:11]
	v_mfma_f32_16x16x32_bf16 v[12:15], v[152:155], v[188:191], v[12:15]
	v_mfma_f32_16x16x32_bf16 v[12:15], v[156:159], v[192:195], v[12:15]
	s_setprio 0
	s_barrier
	s_cmp_lg_u32 s100, 0
	s_cbranch_scc1 .Lg8_p4_gb1
	s_barrier

.LBB0_628:
	s_cmpk_gt_i32 s83, 0x3ff
	s_mov_b64 s[2:3], -1
	s_cbranch_scc0 .LBB0_632
	s_add_i32 s2, s83, 0xfffffc00
	s_lshr_b32 s2, s2, 3
	s_mov_b32 s3, s15
	s_lshl_b64 s[6:7], s[2:3], 19
	s_add_u32 s6, s63, s6
	s_addc_u32 s7, s68, s7
	s_mov_b32 s56, s6
	s_mov_b32 s57, s7
	s_lshl_b32 s6, s83, 8
	s_and_b32 s6, s6, 0x700
	s_lshl_b32 s7, s6, 11
	s_add_u32 s54, s1, s7
	s_addc_u32 s55, s69, 0
	s_add_u32 s58, s54, 0x400000
	s_addc_u32 s59, s55, 0
	s_movk_i32 s7, 0x100
	s_mov_b32 s54, -2
	v_lshrrev_b32_e32 v212, 6, v208
	v_and_b32_e32 v213, 63, v208
	v_readfirstlane_b32 s98, v212
	v_and_b32_e32 v214, 3, v213
	v_bfe_u32 v215, v213, 2, 1
	v_lshl_or_b32 v214, v215, 3, v214
	v_bfe_u32 v215, v213, 3, 1
	v_lshl_or_b32 v214, v215, 2, v214
	s_and_b32 s14, s98, 1
	s_lshr_b32 s100, s98, 2
	s_lshl_b32 s99, s98, 10
	v_lshrrev_b32_e32 v215, 4, v213
	v_bfe_u32 v216, v214, 1, 3
	v_xor_b32_e32 v216, v215, v216
	v_lshlrev_b32_e32 v216, 4, v216
	v_lshl_add_u32 v214, s14, 6, v214
	v_lshl_add_u32 v168, v214, 7, v216
	v_xor_b32_e32 v171, 64, v168
	v_add_u32_e32 v170, 0x10000, v168
	v_add_u32_e32 v196, 0x10000, v171
	v_bfe_u32 v216, v213, 1, 3
	v_xor_b32_e32 v216, v215, v216
	v_lshlrev_b32_e32 v216, 4, v216
	v_and_b32_e32 v214, 15, v213
	s_lshr_b32 s101, s98, 1
	v_lshl_add_u32 v214, s101, 5, v214
	v_lshl_add_u32 v197, v214, 7, v216
	v_add_u32_e32 v197, 0x8000, v197
	v_xor_b32_e32 v199, 64, v197
	v_add_u32_e32 v198, 0x10000, v197
	v_add_u32_e32 v200, 0x10000, v199
	v_lshl_add_u32 v216, s14, 2, v215
	v_and_b32_e32 v214, 7, v213
	v_xor_b32_e32 v216, v214, v216
	v_lshlrev_b32_e32 v216, 4, v216
	v_lshrrev_b32_e32 v214, 3, v213
	v_lshl_add_u32 v215, s98, 3, v214
	v_lshl_add_u32 v201, v215, 11, v216
	v_add_u32_e32 v202, 0x40000, v201
	v_add_u32_e32 v203, 0x20000, v201
	v_add_u32_e32 v204, 0x60000, v201
	s_and_b32 s101, s98, 3
	s_lshl_b32 s101, s101, 3
	s_lshl_b32 s14, s100, 6
	s_add_u32 s101, s101, s14
	v_add_u32_e32 v215, s101, v214
	v_lshl_add_u32 v205, v215, 11, v216
	v_add_u32_e32 v206, 0x40000, v205
	v_add_u32_e32 v210, 0x10000, v205
	v_add_u32_e32 v211, 0x50000, v205
	s_add_u32 m0, s99, 0x8000
	s_nop 0
	global_load_lds_dwordx4 v205, s[56:57]
	s_add_u32 m0, s99, 0xa000
	s_nop 0
	global_load_lds_dwordx4 v206, s[56:57]
	s_add_u32 m0, s99, 0x0
	s_nop 0
	global_load_lds_dwordx4 v201, s[58:59]
	s_add_u32 m0, s99, 0x2000
	s_nop 0
	global_load_lds_dwordx4 v202, s[58:59]
	s_add_u32 m0, s99, 0xc000
	s_nop 0
	global_load_lds_dwordx4 v210, s[56:57]
	s_add_u32 m0, s99, 0xe000
	s_nop 0
	global_load_lds_dwordx4 v211, s[56:57]
	s_add_u32 m0, s99, 0x4000
	s_nop 0
	global_load_lds_dwordx4 v203, s[58:59]
	s_add_u32 m0, s99, 0x6000
	s_nop 0
	global_load_lds_dwordx4 v204, s[58:59]
	v_mov_b32_e32 v112, 0
	v_mov_b32_e32 v113, 0
	v_mov_b32_e32 v114, 0
	v_mov_b32_e32 v115, 0
	v_mov_b32_e32 v116, 0
	v_mov_b32_e32 v117, 0
	v_mov_b32_e32 v118, 0
	v_mov_b32_e32 v119, 0
	v_mov_b32_e32 v120, 0
	v_mov_b32_e32 v121, 0
	v_mov_b32_e32 v122, 0
	v_mov_b32_e32 v123, 0
	v_mov_b32_e32 v124, 0
	v_mov_b32_e32 v125, 0
	v_mov_b32_e32 v126, 0
	v_mov_b32_e32 v127, 0
	v_mov_b32_e32 v96, 0
	v_mov_b32_e32 v97, 0
	v_mov_b32_e32 v98, 0
	v_mov_b32_e32 v99, 0
	v_mov_b32_e32 v100, 0
	v_mov_b32_e32 v101, 0
	v_mov_b32_e32 v102, 0
	v_mov_b32_e32 v103, 0
	v_mov_b32_e32 v104, 0
	v_mov_b32_e32 v105, 0
	v_mov_b32_e32 v106, 0
	v_mov_b32_e32 v107, 0
	v_mov_b32_e32 v108, 0
	v_mov_b32_e32 v109, 0
	v_mov_b32_e32 v110, 0
	v_mov_b32_e32 v111, 0
	v_mov_b32_e32 v80, 0
	v_mov_b32_e32 v81, 0
	v_mov_b32_e32 v82, 0
	v_mov_b32_e32 v83, 0
	v_mov_b32_e32 v84, 0
	v_mov_b32_e32 v85, 0
	v_mov_b32_e32 v86, 0
	v_mov_b32_e32 v87, 0
	v_mov_b32_e32 v88, 0
	v_mov_b32_e32 v89, 0
	v_mov_b32_e32 v90, 0
	v_mov_b32_e32 v91, 0
	v_mov_b32_e32 v92, 0
	v_mov_b32_e32 v93, 0
	v_mov_b32_e32 v94, 0
	v_mov_b32_e32 v95, 0
	v_mov_b32_e32 v64, 0
	v_mov_b32_e32 v65, 0
	v_mov_b32_e32 v66, 0
	v_mov_b32_e32 v67, 0
	v_mov_b32_e32 v68, 0
	v_mov_b32_e32 v69, 0
	v_mov_b32_e32 v70, 0
	v_mov_b32_e32 v71, 0
	v_mov_b32_e32 v72, 0
	v_mov_b32_e32 v73, 0
	v_mov_b32_e32 v74, 0
	v_mov_b32_e32 v75, 0
	v_mov_b32_e32 v76, 0
	v_mov_b32_e32 v77, 0
	v_mov_b32_e32 v78, 0
	v_mov_b32_e32 v79, 0
	v_mov_b32_e32 v48, 0
	v_mov_b32_e32 v49, 0
	v_mov_b32_e32 v50, 0
	v_mov_b32_e32 v51, 0
	v_mov_b32_e32 v52, 0
	v_mov_b32_e32 v53, 0
	v_mov_b32_e32 v54, 0
	v_mov_b32_e32 v55, 0
	v_mov_b32_e32 v56, 0
	v_mov_b32_e32 v57, 0
	v_mov_b32_e32 v58, 0
	v_mov_b32_e32 v59, 0
	v_mov_b32_e32 v60, 0
	v_mov_b32_e32 v61, 0
	v_mov_b32_e32 v62, 0
	v_mov_b32_e32 v63, 0
	v_mov_b32_e32 v32, 0
	v_mov_b32_e32 v33, 0
	v_mov_b32_e32 v34, 0
	v_mov_b32_e32 v35, 0
	v_mov_b32_e32 v36, 0
	v_mov_b32_e32 v37, 0
	v_mov_b32_e32 v38, 0
	v_mov_b32_e32 v39, 0
	v_mov_b32_e32 v40, 0
	v_mov_b32_e32 v41, 0
	v_mov_b32_e32 v42, 0
	v_mov_b32_e32 v43, 0
	v_mov_b32_e32 v44, 0
	v_mov_b32_e32 v45, 0
	v_mov_b32_e32 v46, 0
	v_mov_b32_e32 v47, 0
	v_mov_b32_e32 v16, 0
	v_mov_b32_e32 v17, 0
	v_mov_b32_e32 v18, 0
	v_mov_b32_e32 v19, 0
	v_mov_b32_e32 v20, 0
	v_mov_b32_e32 v21, 0
	v_mov_b32_e32 v22, 0
	v_mov_b32_e32 v23, 0
	v_mov_b32_e32 v24, 0
	v_mov_b32_e32 v25, 0
	v_mov_b32_e32 v26, 0
	v_mov_b32_e32 v27, 0
	v_mov_b32_e32 v28, 0
	v_mov_b32_e32 v29, 0
	v_mov_b32_e32 v30, 0
	v_mov_b32_e32 v31, 0
	v_mov_b32_e32 v0, 0
	v_mov_b32_e32 v1, 0
	v_mov_b32_e32 v2, 0
	v_mov_b32_e32 v3, 0
	v_mov_b32_e32 v4, 0
	v_mov_b32_e32 v5, 0
	v_mov_b32_e32 v6, 0
	v_mov_b32_e32 v7, 0
	v_mov_b32_e32 v8, 0
	v_mov_b32_e32 v9, 0
	v_mov_b32_e32 v10, 0
	v_mov_b32_e32 v11, 0
	v_mov_b32_e32 v12, 0
	v_mov_b32_e32 v13, 0
	v_mov_b32_e32 v14, 0
	v_mov_b32_e32 v15, 0
	s_cmp_eq_u32 s100, 0
	s_cbranch_scc1 .Lg8_p6g_gb0
	s_barrier
.Lg8_p6g_gb0:
	s_waitcnt vmcnt(4)
	s_barrier
	s_add_u32 s56, s56, 0x80
	s_addc_u32 s57, s57, 0
	s_add_u32 m0, s99, 0x18000
	s_nop 0
	global_load_lds_dwordx4 v205, s[56:57]
	s_add_u32 m0, s99, 0x1a000
	s_nop 0
	global_load_lds_dwordx4 v206, s[56:57]
	s_add_u32 s58, s58, 0x80
	s_addc_u32 s59, s59, 0
	s_add_u32 m0, s99, 0x10000
	s_nop 0
	global_load_lds_dwordx4 v201, s[58:59]
	s_add_u32 m0, s99, 0x12000
	s_nop 0
	global_load_lds_dwordx4 v202, s[58:59]
	s_add_u32 m0, s99, 0x1c000
	s_nop 0
	global_load_lds_dwordx4 v210, s[56:57]
	s_add_u32 m0, s99, 0x1e000
	s_nop 0
	global_load_lds_dwordx4 v211, s[56:57]
	s_waitcnt vmcnt(6)
	s_barrier
	s_mov_b32 s101, 7
.Lg8_p6g_loop:
	ds_read_b128 v[160:163], v197 offset:0
	ds_read_b128 v[164:167], v199 offset:0
	ds_read_b128 v[172:175], v197 offset:2048
	ds_read_b128 v[176:179], v199 offset:2048
	ds_read_b128 v[128:131], v168 offset:0
	ds_read_b128 v[132:135], v171 offset:0
	ds_read_b128 v[136:139], v168 offset:2048
	ds_read_b128 v[140:143], v171 offset:2048
	ds_read_b128 v[144:147], v168 offset:4096
	ds_read_b128 v[148:151], v171 offset:4096
	ds_read_b128 v[152:155], v168 offset:6144
	ds_read_b128 v[156:159], v171 offset:6144
	s_add_u32 m0, s99, 0x14000
	s_nop 0
	global_load_lds_dwordx4 v203, s[58:59]
	s_add_u32 m0, s99, 0x16000
	s_nop 0
	global_load_lds_dwordx4 v204, s[58:59]
	s_waitcnt lgkmcnt(8)
	s_barrier
	s_waitcnt lgkmcnt(0)
	s_setprio 1
	v_mfma_f32_16x16x32_bf16 v[112:115], v[128:131], v[160:163], v[112:115]
	v_mfma_f32_16x16x32_bf16 v[112:115], v[132:135], v[164:167], v[112:115]
	v_mfma_f32_16x16x32_bf16 v[116:119], v[128:131], v[172:175], v[116:119]
	v_mfma_f32_16x16x32_bf16 v[116:119], v[132:135], v[176:179], v[116:119]
	v_mfma_f32_16x16x32_bf16 v[120:123], v[136:139], v[160:163], v[120:123]
	v_mfma_f32_16x16x32_bf16 v[120:123], v[140:143], v[164:167], v[120:123]
	v_mfma_f32_16x16x32_bf16 v[124:127], v[136:139], v[172:175], v[124:127]
	v_mfma_f32_16x16x32_bf16 v[124:127], v[140:143], v[176:179], v[124:127]
	v_mfma_f32_16x16x32_bf16 v[96:99], v[144:147], v[160:163], v[96:99]
	v_mfma_f32_16x16x32_bf16 v[96:99], v[148:151], v[164:167], v[96:99]
	v_mfma_f32_16x16x32_bf16 v[100:103], v[144:147], v[172:175], v[100:103]
	v_mfma_f32_16x16x32_bf16 v[100:103], v[148:151], v[176:179], v[100:103]
	v_mfma_f32_16x16x32_bf16 v[104:107], v[152:155], v[160:163], v[104:107]
	v_mfma_f32_16x16x32_bf16 v[104:107], v[156:159], v[164:167], v[104:107]
	v_mfma_f32_16x16x32_bf16 v[108:111], v[152:155], v[172:175], v[108:111]
	v_mfma_f32_16x16x32_bf16 v[108:111], v[156:159], v[176:179], v[108:111]
	s_setprio 0
	s_barrier
	ds_read_b128 v[180:183], v197 offset:16384
	ds_read_b128 v[184:187], v199 offset:16384
	ds_read_b128 v[188:191], v197 offset:18432
	ds_read_b128 v[192:195], v199 offset:18432
	s_add_u32 s56, s56, 0x80
	s_addc_u32 s57, s57, 0
	s_add_u32 m0, s99, 0x8000
	s_nop 0
	global_load_lds_dwordx4 v205, s[56:57]
	s_add_u32 m0, s99, 0xa000
	s_nop 0
	global_load_lds_dwordx4 v206, s[56:57]
	s_barrier
	s_waitcnt lgkmcnt(0)
	s_setprio 1
	v_mfma_f32_16x16x32_bf16 v[48:51], v[128:131], v[180:183], v[48:51]
	v_mfma_f32_16x16x32_bf16 v[48:51], v[132:135], v[184:187], v[48:51]
	v_mfma_f32_16x16x32_bf16 v[52:55], v[128:131], v[188:191], v[52:55]
	v_mfma_f32_16x16x32_bf16 v[52:55], v[132:135], v[192:195], v[52:55]
	v_mfma_f32_16x16x32_bf16 v[56:59], v[136:139], v[180:183], v[56:59]
	v_mfma_f32_16x16x32_bf16 v[56:59], v[140:143], v[184:187], v[56:59]
	v_mfma_f32_16x16x32_bf16 v[60:63], v[136:139], v[188:191], v[60:63]
	v_mfma_f32_16x16x32_bf16 v[60:63], v[140:143], v[192:195], v[60:63]
	v_mfma_f32_16x16x32_bf16 v[32:35], v[144:147], v[180:183], v[32:35]
	v_mfma_f32_16x16x32_bf16 v[32:35], v[148:151], v[184:187], v[32:35]
	v_mfma_f32_16x16x32_bf16 v[36:39], v[144:147], v[188:191], v[36:39]
	v_mfma_f32_16x16x32_bf16 v[36:39], v[148:151], v[192:195], v[36:39]
	v_mfma_f32_16x16x32_bf16 v[40:43], v[152:155], v[180:183], v[40:43]
	v_mfma_f32_16x16x32_bf16 v[40:43], v[156:159], v[184:187], v[40:43]
	v_mfma_f32_16x16x32_bf16 v[44:47], v[152:155], v[188:191], v[44:47]
	v_mfma_f32_16x16x32_bf16 v[44:47], v[156:159], v[192:195], v[44:47]
	s_setprio 0
	s_barrier
	ds_read_b128 v[128:131], v168 offset:16384
	ds_read_b128 v[132:135], v171 offset:16384
	ds_read_b128 v[136:139], v168 offset:18432
	ds_read_b128 v[140:143], v171 offset:18432
	ds_read_b128 v[144:147], v168 offset:20480
	ds_read_b128 v[148:151], v171 offset:20480
	ds_read_b128 v[152:155], v168 offset:22528
	ds_read_b128 v[156:159], v171 offset:22528
	s_add_u32 s58, s58, 0x80
	s_addc_u32 s59, s59, 0
	s_add_u32 m0, s99, 0x0
	s_nop 0
	global_load_lds_dwordx4 v201, s[58:59]
	s_add_u32 m0, s99, 0x2000
	s_nop 0
	global_load_lds_dwordx4 v202, s[58:59]
	s_barrier
	s_waitcnt lgkmcnt(0)
	s_setprio 1
	v_mfma_f32_16x16x32_bf16 v[80:83], v[128:131], v[160:163], v[80:83]
	v_mfma_f32_16x16x32_bf16 v[80:83], v[132:135], v[164:167], v[80:83]
	v_mfma_f32_16x16x32_bf16 v[84:87], v[128:131], v[172:175], v[84:87]
	v_mfma_f32_16x16x32_bf16 v[84:87], v[132:135], v[176:179], v[84:87]
	v_mfma_f32_16x16x32_bf16 v[88:91], v[136:139], v[160:163], v[88:91]
	v_mfma_f32_16x16x32_bf16 v[88:91], v[140:143], v[164:167], v[88:91]
	v_mfma_f32_16x16x32_bf16 v[92:95], v[136:139], v[172:175], v[92:95]
	v_mfma_f32_16x16x32_bf16 v[92:95], v[140:143], v[176:179], v[92:95]
	v_mfma_f32_16x16x32_bf16 v[64:67], v[144:147], v[160:163], v[64:67]
	v_mfma_f32_16x16x32_bf16 v[64:67], v[148:151], v[164:167], v[64:67]
	v_mfma_f32_16x16x32_bf16 v[68:71], v[144:147], v[172:175], v[68:71]
	v_mfma_f32_16x16x32_bf16 v[68:71], v[148:151], v[176:179], v[68:71]
	v_mfma_f32_16x16x32_bf16 v[72:75], v[152:155], v[160:163], v[72:75]
	v_mfma_f32_16x16x32_bf16 v[72:75], v[156:159], v[164:167], v[72:75]
	v_mfma_f32_16x16x32_bf16 v[76:79], v[152:155], v[172:175], v[76:79]
	v_mfma_f32_16x16x32_bf16 v[76:79], v[156:159], v[176:179], v[76:79]
	s_setprio 0
	s_barrier
	s_add_u32 m0, s99, 0xc000
	s_nop 0
	global_load_lds_dwordx4 v210, s[56:57]
	s_add_u32 m0, s99, 0xe000
	s_nop 0
	global_load_lds_dwordx4 v211, s[56:57]
	s_waitcnt vmcnt(6)
	s_barrier
	s_setprio 1
	v_mfma_f32_16x16x32_bf16 v[16:19], v[128:131], v[180:183], v[16:19]
	v_mfma_f32_16x16x32_bf16 v[16:19], v[132:135], v[184:187], v[16:19]
	v_mfma_f32_16x16x32_bf16 v[20:23], v[128:131], v[188:191], v[20:23]
	v_mfma_f32_16x16x32_bf16 v[20:23], v[132:135], v[192:195], v[20:23]
	v_mfma_f32_16x16x32_bf16 v[24:27], v[136:139], v[180:183], v[24:27]
	v_mfma_f32_16x16x32_bf16 v[24:27], v[140:143], v[184:187], v[24:27]
	v_mfma_f32_16x16x32_bf16 v[28:31], v[136:139], v[188:191], v[28:31]
	v_mfma_f32_16x16x32_bf16 v[28:31], v[140:143], v[192:195], v[28:31]
	v_mfma_f32_16x16x32_bf16 v[0:3], v[144:147], v[180:183], v[0:3]
	v_mfma_f32_16x16x32_bf16 v[0:3], v[148:151], v[184:187], v[0:3]
	v_mfma_f32_16x16x32_bf16 v[4:7], v[144:147], v[188:191], v[4:7]
	v_mfma_f32_16x16x32_bf16 v[4:7], v[148:151], v[192:195], v[4:7]
	v_mfma_f32_16x16x32_bf16 v[8:11], v[152:155], v[180:183], v[8:11]
	v_mfma_f32_16x16x32_bf16 v[8:11], v[156:159], v[184:187], v[8:11]
	v_mfma_f32_16x16x32_bf16 v[12:15], v[152:155], v[188:191], v[12:15]
	v_mfma_f32_16x16x32_bf16 v[12:15], v[156:159], v[192:195], v[12:15]
	s_setprio 0
	s_barrier
	ds_read_b128 v[160:163], v198 offset:0
	ds_read_b128 v[164:167], v200 offset:0
	ds_read_b128 v[172:175], v198 offset:2048
	ds_read_b128 v[176:179], v200 offset:2048
	ds_read_b128 v[128:131], v170 offset:0
	ds_read_b128 v[132:135], v196 offset:0
	ds_read_b128 v[136:139], v170 offset:2048
	ds_read_b128 v[140:143], v196 offset:2048
	ds_read_b128 v[144:147], v170 offset:4096
	ds_read_b128 v[148:151], v196 offset:4096
	ds_read_b128 v[152:155], v170 offset:6144
	ds_read_b128 v[156:159], v196 offset:6144
	s_add_u32 m0, s99, 0x4000
	s_nop 0
	global_load_lds_dwordx4 v203, s[58:59]
	s_add_u32 m0, s99, 0x6000
	s_nop 0
	global_load_lds_dwordx4 v204, s[58:59]
	s_waitcnt lgkmcnt(8)
	s_barrier
	s_waitcnt lgkmcnt(0)
	s_setprio 1
	v_mfma_f32_16x16x32_bf16 v[112:115], v[128:131], v[160:163], v[112:115]
	v_mfma_f32_16x16x32_bf16 v[112:115], v[132:135], v[164:167], v[112:115]
	v_mfma_f32_16x16x32_bf16 v[116:119], v[128:131], v[172:175], v[116:119]
	v_mfma_f32_16x16x32_bf16 v[116:119], v[132:135], v[176:179], v[116:119]
	v_mfma_f32_16x16x32_bf16 v[120:123], v[136:139], v[160:163], v[120:123]
	v_mfma_f32_16x16x32_bf16 v[120:123], v[140:143], v[164:167], v[120:123]
	v_mfma_f32_16x16x32_bf16 v[124:127], v[136:139], v[172:175], v[124:127]
	v_mfma_f32_16x16x32_bf16 v[124:127], v[140:143], v[176:179], v[124:127]
	v_mfma_f32_16x16x32_bf16 v[96:99], v[144:147], v[160:163], v[96:99]
	v_mfma_f32_16x16x32_bf16 v[96:99], v[148:151], v[164:167], v[96:99]
	v_mfma_f32_16x16x32_bf16 v[100:103], v[144:147], v[172:175], v[100:103]
	v_mfma_f32_16x16x32_bf16 v[100:103], v[148:151], v[176:179], v[100:103]
	v_mfma_f32_16x16x32_bf16 v[104:107], v[152:155], v[160:163], v[104:107]
	v_mfma_f32_16x16x32_bf16 v[104:107], v[156:159], v[164:167], v[104:107]
	v_mfma_f32_16x16x32_bf16 v[108:111], v[152:155], v[172:175], v[108:111]
	v_mfma_f32_16x16x32_bf16 v[108:111], v[156:159], v[176:179], v[108:111]
	s_setprio 0
	s_barrier
	ds_read_b128 v[180:183], v198 offset:16384
	ds_read_b128 v[184:187], v200 offset:16384
	ds_read_b128 v[188:191], v198 offset:18432
	ds_read_b128 v[192:195], v200 offset:18432
	s_add_u32 s56, s56, 0x80
	s_addc_u32 s57, s57, 0
	s_add_u32 m0, s99, 0x18000
	s_nop 0
	global_load_lds_dwordx4 v205, s[56:57]
	s_add_u32 m0, s99, 0x1a000
	s_nop 0
	global_load_lds_dwordx4 v206, s[56:57]
	s_barrier
	s_waitcnt lgkmcnt(0)
	s_setprio 1
	v_mfma_f32_16x16x32_bf16 v[48:51], v[128:131], v[180:183], v[48:51]
	v_mfma_f32_16x16x32_bf16 v[48:51], v[132:135], v[184:187], v[48:51]
	v_mfma_f32_16x16x32_bf16 v[52:55], v[128:131], v[188:191], v[52:55]
	v_mfma_f32_16x16x32_bf16 v[52:55], v[132:135], v[192:195], v[52:55]
	v_mfma_f32_16x16x32_bf16 v[56:59], v[136:139], v[180:183], v[56:59]
	v_mfma_f32_16x16x32_bf16 v[56:59], v[140:143], v[184:187], v[56:59]
	v_mfma_f32_16x16x32_bf16 v[60:63], v[136:139], v[188:191], v[60:63]
	v_mfma_f32_16x16x32_bf16 v[60:63], v[140:143], v[192:195], v[60:63]
	v_mfma_f32_16x16x32_bf16 v[32:35], v[144:147], v[180:183], v[32:35]
	v_mfma_f32_16x16x32_bf16 v[32:35], v[148:151], v[184:187], v[32:35]
	v_mfma_f32_16x16x32_bf16 v[36:39], v[144:147], v[188:191], v[36:39]
	v_mfma_f32_16x16x32_bf16 v[36:39], v[148:151], v[192:195], v[36:39]
	v_mfma_f32_16x16x32_bf16 v[40:43], v[152:155], v[180:183], v[40:43]
	v_mfma_f32_16x16x32_bf16 v[40:43], v[156:159], v[184:187], v[40:43]
	v_mfma_f32_16x16x32_bf16 v[44:47], v[152:155], v[188:191], v[44:47]
	v_mfma_f32_16x16x32_bf16 v[44:47], v[156:159], v[192:195], v[44:47]
	s_setprio 0
	s_barrier
	ds_read_b128 v[128:131], v170 offset:16384
	ds_read_b128 v[132:135], v196 offset:16384
	ds_read_b128 v[136:139], v170 offset:18432
	ds_read_b128 v[140:143], v196 offset:18432
	ds_read_b128 v[144:147], v170 offset:20480
	ds_read_b128 v[148:151], v196 offset:20480
	ds_read_b128 v[152:155], v170 offset:22528
	ds_read_b128 v[156:159], v196 offset:22528
	s_add_u32 s58, s58, 0x80
	s_addc_u32 s59, s59, 0
	s_add_u32 m0, s99, 0x10000
	s_nop 0
	global_load_lds_dwordx4 v201, s[58:59]
	s_add_u32 m0, s99, 0x12000
	s_nop 0
	global_load_lds_dwordx4 v202, s[58:59]
	s_barrier
	s_waitcnt lgkmcnt(0)
	s_setprio 1
	v_mfma_f32_16x16x32_bf16 v[80:83], v[128:131], v[160:163], v[80:83]
	v_mfma_f32_16x16x32_bf16 v[80:83], v[132:135], v[164:167], v[80:83]
	v_mfma_f32_16x16x32_bf16 v[84:87], v[128:131], v[172:175], v[84:87]
	v_mfma_f32_16x16x32_bf16 v[84:87], v[132:135], v[176:179], v[84:87]
	v_mfma_f32_16x16x32_bf16 v[88:91], v[136:139], v[160:163], v[88:91]
	v_mfma_f32_16x16x32_bf16 v[88:91], v[140:143], v[164:167], v[88:91]
	v_mfma_f32_16x16x32_bf16 v[92:95], v[136:139], v[172:175], v[92:95]
	v_mfma_f32_16x16x32_bf16 v[92:95], v[140:143], v[176:179], v[92:95]
	v_mfma_f32_16x16x32_bf16 v[64:67], v[144:147], v[160:163], v[64:67]
	v_mfma_f32_16x16x32_bf16 v[64:67], v[148:151], v[164:167], v[64:67]
	v_mfma_f32_16x16x32_bf16 v[68:71], v[144:147], v[172:175], v[68:71]
	v_mfma_f32_16x16x32_bf16 v[68:71], v[148:151], v[176:179], v[68:71]
	v_mfma_f32_16x16x32_bf16 v[72:75], v[152:155], v[160:163], v[72:75]
	v_mfma_f32_16x16x32_bf16 v[72:75], v[156:159], v[164:167], v[72:75]
	v_mfma_f32_16x16x32_bf16 v[76:79], v[152:155], v[172:175], v[76:79]
	v_mfma_f32_16x16x32_bf16 v[76:79], v[156:159], v[176:179], v[76:79]
	s_setprio 0
	s_barrier
	s_add_u32 m0, s99, 0x1c000
	s_nop 0
	global_load_lds_dwordx4 v210, s[56:57]
	s_add_u32 m0, s99, 0x1e000
	s_nop 0
	global_load_lds_dwordx4 v211, s[56:57]
	s_waitcnt vmcnt(6)
	s_barrier
	s_setprio 1
	v_mfma_f32_16x16x32_bf16 v[16:19], v[128:131], v[180:183], v[16:19]
	v_mfma_f32_16x16x32_bf16 v[16:19], v[132:135], v[184:187], v[16:19]
	v_mfma_f32_16x16x32_bf16 v[20:23], v[128:131], v[188:191], v[20:23]
	v_mfma_f32_16x16x32_bf16 v[20:23], v[132:135], v[192:195], v[20:23]
	v_mfma_f32_16x16x32_bf16 v[24:27], v[136:139], v[180:183], v[24:27]
	v_mfma_f32_16x16x32_bf16 v[24:27], v[140:143], v[184:187], v[24:27]
	v_mfma_f32_16x16x32_bf16 v[28:31], v[136:139], v[188:191], v[28:31]
	v_mfma_f32_16x16x32_bf16 v[28:31], v[140:143], v[192:195], v[28:31]
	v_mfma_f32_16x16x32_bf16 v[0:3], v[144:147], v[180:183], v[0:3]
	v_mfma_f32_16x16x32_bf16 v[0:3], v[148:151], v[184:187], v[0:3]
	v_mfma_f32_16x16x32_bf16 v[4:7], v[144:147], v[188:191], v[4:7]
	v_mfma_f32_16x16x32_bf16 v[4:7], v[148:151], v[192:195], v[4:7]
	v_mfma_f32_16x16x32_bf16 v[8:11], v[152:155], v[180:183], v[8:11]
	v_mfma_f32_16x16x32_bf16 v[8:11], v[156:159], v[184:187], v[8:11]
	v_mfma_f32_16x16x32_bf16 v[12:15], v[152:155], v[188:191], v[12:15]
	v_mfma_f32_16x16x32_bf16 v[12:15], v[156:159], v[192:195], v[12:15]
	s_setprio 0
	s_barrier
	s_sub_u32 s101, s101, 1
	s_cmp_lg_u32 s101, 0
	s_cbranch_scc1 .Lg8_p6g_loop
	ds_read_b128 v[160:163], v197 offset:0
	ds_read_b128 v[164:167], v199 offset:0
	ds_read_b128 v[172:175], v197 offset:2048
	ds_read_b128 v[176:179], v199 offset:2048
	ds_read_b128 v[128:131], v168 offset:0
	ds_read_b128 v[132:135], v171 offset:0
	ds_read_b128 v[136:139], v168 offset:2048
	ds_read_b128 v[140:143], v171 offset:2048
	ds_read_b128 v[144:147], v168 offset:4096
	ds_read_b128 v[148:151], v171 offset:4096
	ds_read_b128 v[152:155], v168 offset:6144
	ds_read_b128 v[156:159], v171 offset:6144
	s_add_u32 m0, s99, 0x14000
	s_nop 0
	global_load_lds_dwordx4 v203, s[58:59]
	s_add_u32 m0, s99, 0x16000
	s_nop 0
	global_load_lds_dwordx4 v204, s[58:59]
	s_barrier
	s_waitcnt lgkmcnt(0)
	s_setprio 1
	v_mfma_f32_16x16x32_bf16 v[112:115], v[128:131], v[160:163], v[112:115]
	v_mfma_f32_16x16x32_bf16 v[112:115], v[132:135], v[164:167], v[112:115]
	v_mfma_f32_16x16x32_bf16 v[116:119], v[128:131], v[172:175], v[116:119]
	v_mfma_f32_16x16x32_bf16 v[116:119], v[132:135], v[176:179], v[116:119]
	v_mfma_f32_16x16x32_bf16 v[120:123], v[136:139], v[160:163], v[120:123]
	v_mfma_f32_16x16x32_bf16 v[120:123], v[140:143], v[164:167], v[120:123]
	v_mfma_f32_16x16x32_bf16 v[124:127], v[136:139], v[172:175], v[124:127]
	v_mfma_f32_16x16x32_bf16 v[124:127], v[140:143], v[176:179], v[124:127]
	v_mfma_f32_16x16x32_bf16 v[96:99], v[144:147], v[160:163], v[96:99]
	v_mfma_f32_16x16x32_bf16 v[96:99], v[148:151], v[164:167], v[96:99]
	v_mfma_f32_16x16x32_bf16 v[100:103], v[144:147], v[172:175], v[100:103]
	v_mfma_f32_16x16x32_bf16 v[100:103], v[148:151], v[176:179], v[100:103]
	v_mfma_f32_16x16x32_bf16 v[104:107], v[152:155], v[160:163], v[104:107]
	v_mfma_f32_16x16x32_bf16 v[104:107], v[156:159], v[164:167], v[104:107]
	v_mfma_f32_16x16x32_bf16 v[108:111], v[152:155], v[172:175], v[108:111]
	v_mfma_f32_16x16x32_bf16 v[108:111], v[156:159], v[176:179], v[108:111]
	s_setprio 0
	s_barrier
	ds_read_b128 v[180:183], v197 offset:16384
	ds_read_b128 v[184:187], v199 offset:16384
	ds_read_b128 v[188:191], v197 offset:18432
	ds_read_b128 v[192:195], v199 offset:18432
	s_barrier
	s_waitcnt lgkmcnt(0)
	s_setprio 1
	v_mfma_f32_16x16x32_bf16 v[48:51], v[128:131], v[180:183], v[48:51]
	v_mfma_f32_16x16x32_bf16 v[48:51], v[132:135], v[184:187], v[48:51]
	v_mfma_f32_16x16x32_bf16 v[52:55], v[128:131], v[188:191], v[52:55]
	v_mfma_f32_16x16x32_bf16 v[52:55], v[132:135], v[192:195], v[52:55]
	v_mfma_f32_16x16x32_bf16 v[56:59], v[136:139], v[180:183], v[56:59]
	v_mfma_f32_16x16x32_bf16 v[56:59], v[140:143], v[184:187], v[56:59]
	v_mfma_f32_16x16x32_bf16 v[60:63], v[136:139], v[188:191], v[60:63]
	v_mfma_f32_16x16x32_bf16 v[60:63], v[140:143], v[192:195], v[60:63]
	v_mfma_f32_16x16x32_bf16 v[32:35], v[144:147], v[180:183], v[32:35]
	v_mfma_f32_16x16x32_bf16 v[32:35], v[148:151], v[184:187], v[32:35]
	v_mfma_f32_16x16x32_bf16 v[36:39], v[144:147], v[188:191], v[36:39]
	v_mfma_f32_16x16x32_bf16 v[36:39], v[148:151], v[192:195], v[36:39]
	v_mfma_f32_16x16x32_bf16 v[40:43], v[152:155], v[180:183], v[40:43]
	v_mfma_f32_16x16x32_bf16 v[40:43], v[156:159], v[184:187], v[40:43]
	v_mfma_f32_16x16x32_bf16 v[44:47], v[152:155], v[188:191], v[44:47]
	v_mfma_f32_16x16x32_bf16 v[44:47], v[156:159], v[192:195], v[44:47]
	s_setprio 0
	s_barrier
	ds_read_b128 v[128:131], v168 offset:16384
	ds_read_b128 v[132:135], v171 offset:16384
	ds_read_b128 v[136:139], v168 offset:18432
	ds_read_b128 v[140:143], v171 offset:18432
	ds_read_b128 v[144:147], v168 offset:20480
	ds_read_b128 v[148:151], v171 offset:20480
	ds_read_b128 v[152:155], v168 offset:22528
	ds_read_b128 v[156:159], v171 offset:22528
	s_waitcnt vmcnt(4)
	s_barrier
	s_waitcnt lgkmcnt(0)
	s_setprio 1
	v_mfma_f32_16x16x32_bf16 v[80:83], v[128:131], v[160:163], v[80:83]
	v_mfma_f32_16x16x32_bf16 v[80:83], v[132:135], v[164:167], v[80:83]
	v_mfma_f32_16x16x32_bf16 v[84:87], v[128:131], v[172:175], v[84:87]
	v_mfma_f32_16x16x32_bf16 v[84:87], v[132:135], v[176:179], v[84:87]
	v_mfma_f32_16x16x32_bf16 v[88:91], v[136:139], v[160:163], v[88:91]
	v_mfma_f32_16x16x32_bf16 v[88:91], v[140:143], v[164:167], v[88:91]
	v_mfma_f32_16x16x32_bf16 v[92:95], v[136:139], v[172:175], v[92:95]
	v_mfma_f32_16x16x32_bf16 v[92:95], v[140:143], v[176:179], v[92:95]
	v_mfma_f32_16x16x32_bf16 v[64:67], v[144:147], v[160:163], v[64:67]
	v_mfma_f32_16x16x32_bf16 v[64:67], v[148:151], v[164:167], v[64:67]
	v_mfma_f32_16x16x32_bf16 v[68:71], v[144:147], v[172:175], v[68:71]
	v_mfma_f32_16x16x32_bf16 v[68:71], v[148:151], v[176:179], v[68:71]
	v_mfma_f32_16x16x32_bf16 v[72:75], v[152:155], v[160:163], v[72:75]
	v_mfma_f32_16x16x32_bf16 v[72:75], v[156:159], v[164:167], v[72:75]
	v_mfma_f32_16x16x32_bf16 v[76:79], v[152:155], v[172:175], v[76:79]
	v_mfma_f32_16x16x32_bf16 v[76:79], v[156:159], v[176:179], v[76:79]
	s_setprio 0
	s_setprio 1
	v_mfma_f32_16x16x32_bf16 v[16:19], v[128:131], v[180:183], v[16:19]
	v_mfma_f32_16x16x32_bf16 v[16:19], v[132:135], v[184:187], v[16:19]
	v_mfma_f32_16x16x32_bf16 v[20:23], v[128:131], v[188:191], v[20:23]
	v_mfma_f32_16x16x32_bf16 v[20:23], v[132:135], v[192:195], v[20:23]
	v_mfma_f32_16x16x32_bf16 v[24:27], v[136:139], v[180:183], v[24:27]
	v_mfma_f32_16x16x32_bf16 v[24:27], v[140:143], v[184:187], v[24:27]
	v_mfma_f32_16x16x32_bf16 v[28:31], v[136:139], v[188:191], v[28:31]
	v_mfma_f32_16x16x32_bf16 v[28:31], v[140:143], v[192:195], v[28:31]
	v_mfma_f32_16x16x32_bf16 v[0:3], v[144:147], v[180:183], v[0:3]
	v_mfma_f32_16x16x32_bf16 v[0:3], v[148:151], v[184:187], v[0:3]
	v_mfma_f32_16x16x32_bf16 v[4:7], v[144:147], v[188:191], v[4:7]
	v_mfma_f32_16x16x32_bf16 v[4:7], v[148:151], v[192:195], v[4:7]
	v_mfma_f32_16x16x32_bf16 v[8:11], v[152:155], v[180:183], v[8:11]
	v_mfma_f32_16x16x32_bf16 v[8:11], v[156:159], v[184:187], v[8:11]
	v_mfma_f32_16x16x32_bf16 v[12:15], v[152:155], v[188:191], v[12:15]
	v_mfma_f32_16x16x32_bf16 v[12:15], v[156:159], v[192:195], v[12:15]
	s_setprio 0
	s_barrier
	ds_read_b128 v[160:163], v198 offset:0
	ds_read_b128 v[164:167], v200 offset:0
	ds_read_b128 v[172:175], v198 offset:2048
	ds_read_b128 v[176:179], v200 offset:2048
	ds_read_b128 v[128:131], v170 offset:0
	ds_read_b128 v[132:135], v196 offset:0
	ds_read_b128 v[136:139], v170 offset:2048
	ds_read_b128 v[140:143], v196 offset:2048
	ds_read_b128 v[144:147], v170 offset:4096
	ds_read_b128 v[148:151], v196 offset:4096
	ds_read_b128 v[152:155], v170 offset:6144
	ds_read_b128 v[156:159], v196 offset:6144
	s_waitcnt vmcnt(2)
	s_barrier
	s_waitcnt lgkmcnt(0)
	s_setprio 1
	v_mfma_f32_16x16x32_bf16 v[112:115], v[128:131], v[160:163], v[112:115]
	v_mfma_f32_16x16x32_bf16 v[112:115], v[132:135], v[164:167], v[112:115]
	v_mfma_f32_16x16x32_bf16 v[116:119], v[128:131], v[172:175], v[116:119]
	v_mfma_f32_16x16x32_bf16 v[116:119], v[132:135], v[176:179], v[116:119]
	v_mfma_f32_16x16x32_bf16 v[120:123], v[136:139], v[160:163], v[120:123]
	v_mfma_f32_16x16x32_bf16 v[120:123], v[140:143], v[164:167], v[120:123]
	v_mfma_f32_16x16x32_bf16 v[124:127], v[136:139], v[172:175], v[124:127]
	v_mfma_f32_16x16x32_bf16 v[124:127], v[140:143], v[176:179], v[124:127]
	v_mfma_f32_16x16x32_bf16 v[96:99], v[144:147], v[160:163], v[96:99]
	v_mfma_f32_16x16x32_bf16 v[96:99], v[148:151], v[164:167], v[96:99]
	v_mfma_f32_16x16x32_bf16 v[100:103], v[144:147], v[172:175], v[100:103]
	v_mfma_f32_16x16x32_bf16 v[100:103], v[148:151], v[176:179], v[100:103]
	v_mfma_f32_16x16x32_bf16 v[104:107], v[152:155], v[160:163], v[104:107]
	v_mfma_f32_16x16x32_bf16 v[104:107], v[156:159], v[164:167], v[104:107]
	v_mfma_f32_16x16x32_bf16 v[108:111], v[152:155], v[172:175], v[108:111]
	v_mfma_f32_16x16x32_bf16 v[108:111], v[156:159], v[176:179], v[108:111]
	s_setprio 0
	s_barrier
	ds_read_b128 v[180:183], v198 offset:16384
	ds_read_b128 v[184:187], v200 offset:16384
	ds_read_b128 v[188:191], v198 offset:18432
	ds_read_b128 v[192:195], v200 offset:18432
	s_waitcnt vmcnt(0)
	s_barrier
	s_waitcnt lgkmcnt(0)
	s_setprio 1
	v_mfma_f32_16x16x32_bf16 v[48:51], v[128:131], v[180:183], v[48:51]
	v_mfma_f32_16x16x32_bf16 v[48:51], v[132:135], v[184:187], v[48:51]
	v_mfma_f32_16x16x32_bf16 v[52:55], v[128:131], v[188:191], v[52:55]
	v_mfma_f32_16x16x32_bf16 v[52:55], v[132:135], v[192:195], v[52:55]
	v_mfma_f32_16x16x32_bf16 v[56:59], v[136:139], v[180:183], v[56:59]
	v_mfma_f32_16x16x32_bf16 v[56:59], v[140:143], v[184:187], v[56:59]
	v_mfma_f32_16x16x32_bf16 v[60:63], v[136:139], v[188:191], v[60:63]
	v_mfma_f32_16x16x32_bf16 v[60:63], v[140:143], v[192:195], v[60:63]
	v_mfma_f32_16x16x32_bf16 v[32:35], v[144:147], v[180:183], v[32:35]
	v_mfma_f32_16x16x32_bf16 v[32:35], v[148:151], v[184:187], v[32:35]
	v_mfma_f32_16x16x32_bf16 v[36:39], v[144:147], v[188:191], v[36:39]
	v_mfma_f32_16x16x32_bf16 v[36:39], v[148:151], v[192:195], v[36:39]
	v_mfma_f32_16x16x32_bf16 v[40:43], v[152:155], v[180:183], v[40:43]
	v_mfma_f32_16x16x32_bf16 v[40:43], v[156:159], v[184:187], v[40:43]
	v_mfma_f32_16x16x32_bf16 v[44:47], v[152:155], v[188:191], v[44:47]
	v_mfma_f32_16x16x32_bf16 v[44:47], v[156:159], v[192:195], v[44:47]
	s_setprio 0
	s_barrier
	ds_read_b128 v[128:131], v170 offset:16384
	ds_read_b128 v[132:135], v196 offset:16384
	ds_read_b128 v[136:139], v170 offset:18432
	ds_read_b128 v[140:143], v196 offset:18432
	ds_read_b128 v[144:147], v170 offset:20480
	ds_read_b128 v[148:151], v196 offset:20480
	ds_read_b128 v[152:155], v170 offset:22528
	ds_read_b128 v[156:159], v196 offset:22528
	s_barrier
	s_waitcnt lgkmcnt(0)
	s_setprio 1
	v_mfma_f32_16x16x32_bf16 v[80:83], v[128:131], v[160:163], v[80:83]
	v_mfma_f32_16x16x32_bf16 v[80:83], v[132:135], v[164:167], v[80:83]
	v_mfma_f32_16x16x32_bf16 v[84:87], v[128:131], v[172:175], v[84:87]
	v_mfma_f32_16x16x32_bf16 v[84:87], v[132:135], v[176:179], v[84:87]
	v_mfma_f32_16x16x32_bf16 v[88:91], v[136:139], v[160:163], v[88:91]
	v_mfma_f32_16x16x32_bf16 v[88:91], v[140:143], v[164:167], v[88:91]
	v_mfma_f32_16x16x32_bf16 v[92:95], v[136:139], v[172:175], v[92:95]
	v_mfma_f32_16x16x32_bf16 v[92:95], v[140:143], v[176:179], v[92:95]
	v_mfma_f32_16x16x32_bf16 v[64:67], v[144:147], v[160:163], v[64:67]
	v_mfma_f32_16x16x32_bf16 v[64:67], v[148:151], v[164:167], v[64:67]
	v_mfma_f32_16x16x32_bf16 v[68:71], v[144:147], v[172:175], v[68:71]
	v_mfma_f32_16x16x32_bf16 v[68:71], v[148:151], v[176:179], v[68:71]
	v_mfma_f32_16x16x32_bf16 v[72:75], v[152:155], v[160:163], v[72:75]
	v_mfma_f32_16x16x32_bf16 v[72:75], v[156:159], v[164:167], v[72:75]
	v_mfma_f32_16x16x32_bf16 v[76:79], v[152:155], v[172:175], v[76:79]
	v_mfma_f32_16x16x32_bf16 v[76:79], v[156:159], v[176:179], v[76:79]
	s_setprio 0
	s_setprio 1
	v_mfma_f32_16x16x32_bf16 v[16:19], v[128:131], v[180:183], v[16:19]
	v_mfma_f32_16x16x32_bf16 v[16:19], v[132:135], v[184:187], v[16:19]
	v_mfma_f32_16x16x32_bf16 v[20:23], v[128:131], v[188:191], v[20:23]
	v_mfma_f32_16x16x32_bf16 v[20:23], v[132:135], v[192:195], v[20:23]
	v_mfma_f32_16x16x32_bf16 v[24:27], v[136:139], v[180:183], v[24:27]
	v_mfma_f32_16x16x32_bf16 v[24:27], v[140:143], v[184:187], v[24:27]
	v_mfma_f32_16x16x32_bf16 v[28:31], v[136:139], v[188:191], v[28:31]
	v_mfma_f32_16x16x32_bf16 v[28:31], v[140:143], v[192:195], v[28:31]
	v_mfma_f32_16x16x32_bf16 v[0:3], v[144:147], v[180:183], v[0:3]
	v_mfma_f32_16x16x32_bf16 v[0:3], v[148:151], v[184:187], v[0:3]
	v_mfma_f32_16x16x32_bf16 v[4:7], v[144:147], v[188:191], v[4:7]
	v_mfma_f32_16x16x32_bf16 v[4:7], v[148:151], v[192:195], v[4:7]
	v_mfma_f32_16x16x32_bf16 v[8:11], v[152:155], v[180:183], v[8:11]
	v_mfma_f32_16x16x32_bf16 v[8:11], v[156:159], v[184:187], v[8:11]
	v_mfma_f32_16x16x32_bf16 v[12:15], v[152:155], v[188:191], v[12:15]
	v_mfma_f32_16x16x32_bf16 v[12:15], v[156:159], v[192:195], v[12:15]
	s_setprio 0
	s_barrier
	s_cmp_lg_u32 s100, 0
	s_cbranch_scc1 .Lg8_p6g_gb1
	s_barrier

.LBB0_632:
	s_and_b64 vcc, exec, s[2:3]
	s_cbranch_vccz .LBB0_627
	s_and_b32 s58, s83, 7
	s_ashr_i32 s2, s83, 3
	s_lshl_b32 s3, s58, 19
	s_add_u32 s6, s1, s3
	s_addc_u32 s7, s69, 0
	s_mov_b32 s54, s6
	s_mov_b32 s55, s7
	s_ashr_i32 s3, s2, 31
	s_lshl_b64 s[6:7], s[2:3], 19
	s_add_u32 s6, s63, s6
	s_addc_u32 s7, s68, s7
	s_mov_b32 s56, s6
	s_mov_b32 s57, s7
	s_movk_i32 s3, 0x100
	s_mov_b32 s6, -2
	v_lshrrev_b32_e32 v212, 6, v208
	v_and_b32_e32 v213, 63, v208
	v_readfirstlane_b32 s98, v212
	v_and_b32_e32 v214, 3, v213
	v_bfe_u32 v215, v213, 2, 1
	v_lshl_or_b32 v214, v215, 3, v214
	v_bfe_u32 v215, v213, 3, 1
	v_lshl_or_b32 v214, v215, 2, v214
	s_and_b32 s14, s98, 1
	s_lshr_b32 s100, s98, 2
	s_lshl_b32 s99, s98, 10
	v_lshrrev_b32_e32 v215, 4, v213
	v_bfe_u32 v216, v214, 1, 3
	v_xor_b32_e32 v216, v215, v216
	v_lshlrev_b32_e32 v216, 4, v216
	v_lshl_add_u32 v214, s14, 6, v214
	v_lshl_add_u32 v168, v214, 7, v216
	v_xor_b32_e32 v171, 64, v168
	v_add_u32_e32 v170, 0x10000, v168
	v_add_u32_e32 v196, 0x10000, v171
	v_bfe_u32 v216, v213, 1, 3
	v_xor_b32_e32 v216, v215, v216
	v_lshlrev_b32_e32 v216, 4, v216
	v_and_b32_e32 v214, 15, v213
	s_lshr_b32 s101, s98, 1
	v_lshl_add_u32 v214, s101, 5, v214
	v_lshl_add_u32 v197, v214, 7, v216
	v_add_u32_e32 v197, 0x8000, v197
	v_xor_b32_e32 v199, 64, v197
	v_add_u32_e32 v198, 0x10000, v197
	v_add_u32_e32 v200, 0x10000, v199
	v_lshl_add_u32 v216, s14, 2, v215
	v_and_b32_e32 v214, 7, v213
	v_xor_b32_e32 v216, v214, v216
	v_lshlrev_b32_e32 v216, 4, v216
	v_lshrrev_b32_e32 v214, 3, v213
	v_lshl_add_u32 v215, s98, 3, v214
	v_lshl_add_u32 v201, v215, 11, v216
	v_add_u32_e32 v202, 0x40000, v201
	v_add_u32_e32 v203, 0x20000, v201
	v_add_u32_e32 v204, 0x60000, v201
	s_and_b32 s101, s98, 3
	s_lshl_b32 s101, s101, 3
	s_lshl_b32 s14, s100, 6
	s_add_u32 s101, s101, s14
	v_add_u32_e32 v215, s101, v214
	v_lshl_add_u32 v205, v215, 11, v216
	v_add_u32_e32 v206, 0x40000, v205
	v_add_u32_e32 v210, 0x10000, v205
	v_add_u32_e32 v211, 0x50000, v205
	s_add_u32 m0, s99, 0x8000
	s_nop 0
	global_load_lds_dwordx4 v205, s[54:55]
	s_add_u32 m0, s99, 0xa000
	s_nop 0
	global_load_lds_dwordx4 v206, s[54:55]
	s_add_u32 m0, s99, 0x0
	s_nop 0
	global_load_lds_dwordx4 v201, s[56:57]
	s_add_u32 m0, s99, 0x2000
	s_nop 0
	global_load_lds_dwordx4 v202, s[56:57]
	s_add_u32 m0, s99, 0xc000
	s_nop 0
	global_load_lds_dwordx4 v210, s[54:55]
	s_add_u32 m0, s99, 0xe000
	s_nop 0
	global_load_lds_dwordx4 v211, s[54:55]
	s_add_u32 m0, s99, 0x4000
	s_nop 0
	global_load_lds_dwordx4 v203, s[56:57]
	s_add_u32 m0, s99, 0x6000
	s_nop 0
	global_load_lds_dwordx4 v204, s[56:57]
	v_mov_b32_e32 v0, 0
	v_mov_b32_e32 v1, 0
	v_mov_b32_e32 v2, 0
	v_mov_b32_e32 v3, 0
	v_mov_b32_e32 v4, 0
	v_mov_b32_e32 v5, 0
	v_mov_b32_e32 v6, 0
	v_mov_b32_e32 v7, 0
	v_mov_b32_e32 v8, 0
	v_mov_b32_e32 v9, 0
	v_mov_b32_e32 v10, 0
	v_mov_b32_e32 v11, 0
	v_mov_b32_e32 v12, 0
	v_mov_b32_e32 v13, 0
	v_mov_b32_e32 v14, 0
	v_mov_b32_e32 v15, 0
	v_mov_b32_e32 v112, 0
	v_mov_b32_e32 v113, 0
	v_mov_b32_e32 v114, 0
	v_mov_b32_e32 v115, 0
	v_mov_b32_e32 v116, 0
	v_mov_b32_e32 v117, 0
	v_mov_b32_e32 v118, 0
	v_mov_b32_e32 v119, 0
	v_mov_b32_e32 v120, 0
	v_mov_b32_e32 v121, 0
	v_mov_b32_e32 v122, 0
	v_mov_b32_e32 v123, 0
	v_mov_b32_e32 v124, 0
	v_mov_b32_e32 v125, 0
	v_mov_b32_e32 v126, 0
	v_mov_b32_e32 v127, 0
	v_mov_b32_e32 v96, 0
	v_mov_b32_e32 v97, 0
	v_mov_b32_e32 v98, 0
	v_mov_b32_e32 v99, 0
	v_mov_b32_e32 v100, 0
	v_mov_b32_e32 v101, 0
	v_mov_b32_e32 v102, 0
	v_mov_b32_e32 v103, 0
	v_mov_b32_e32 v104, 0
	v_mov_b32_e32 v105, 0
	v_mov_b32_e32 v106, 0
	v_mov_b32_e32 v107, 0
	v_mov_b32_e32 v108, 0
	v_mov_b32_e32 v109, 0
	v_mov_b32_e32 v110, 0
	v_mov_b32_e32 v111, 0
	v_mov_b32_e32 v80, 0
	v_mov_b32_e32 v81, 0
	v_mov_b32_e32 v82, 0
	v_mov_b32_e32 v83, 0
	v_mov_b32_e32 v84, 0
	v_mov_b32_e32 v85, 0
	v_mov_b32_e32 v86, 0
	v_mov_b32_e32 v87, 0
	v_mov_b32_e32 v88, 0
	v_mov_b32_e32 v89, 0
	v_mov_b32_e32 v90, 0
	v_mov_b32_e32 v91, 0
	v_mov_b32_e32 v92, 0
	v_mov_b32_e32 v93, 0
	v_mov_b32_e32 v94, 0
	v_mov_b32_e32 v95, 0
	v_mov_b32_e32 v64, 0
	v_mov_b32_e32 v65, 0
	v_mov_b32_e32 v66, 0
	v_mov_b32_e32 v67, 0
	v_mov_b32_e32 v68, 0
	v_mov_b32_e32 v69, 0
	v_mov_b32_e32 v70, 0
	v_mov_b32_e32 v71, 0
	v_mov_b32_e32 v72, 0
	v_mov_b32_e32 v73, 0
	v_mov_b32_e32 v74, 0
	v_mov_b32_e32 v75, 0
	v_mov_b32_e32 v76, 0
	v_mov_b32_e32 v77, 0
	v_mov_b32_e32 v78, 0
	v_mov_b32_e32 v79, 0
	v_mov_b32_e32 v48, 0
	v_mov_b32_e32 v49, 0
	v_mov_b32_e32 v50, 0
	v_mov_b32_e32 v51, 0
	v_mov_b32_e32 v52, 0
	v_mov_b32_e32 v53, 0
	v_mov_b32_e32 v54, 0
	v_mov_b32_e32 v55, 0
	v_mov_b32_e32 v56, 0
	v_mov_b32_e32 v57, 0
	v_mov_b32_e32 v58, 0
	v_mov_b32_e32 v59, 0
	v_mov_b32_e32 v60, 0
	v_mov_b32_e32 v61, 0
	v_mov_b32_e32 v62, 0
	v_mov_b32_e32 v63, 0
	v_mov_b32_e32 v32, 0
	v_mov_b32_e32 v33, 0
	v_mov_b32_e32 v34, 0
	v_mov_b32_e32 v35, 0
	v_mov_b32_e32 v36, 0
	v_mov_b32_e32 v37, 0
	v_mov_b32_e32 v38, 0
	v_mov_b32_e32 v39, 0
	v_mov_b32_e32 v40, 0
	v_mov_b32_e32 v41, 0
	v_mov_b32_e32 v42, 0
	v_mov_b32_e32 v43, 0
	v_mov_b32_e32 v44, 0
	v_mov_b32_e32 v45, 0
	v_mov_b32_e32 v46, 0
	v_mov_b32_e32 v47, 0
	v_mov_b32_e32 v16, 0
	v_mov_b32_e32 v17, 0
	v_mov_b32_e32 v18, 0
	v_mov_b32_e32 v19, 0
	v_mov_b32_e32 v20, 0
	v_mov_b32_e32 v21, 0
	v_mov_b32_e32 v22, 0
	v_mov_b32_e32 v23, 0
	v_mov_b32_e32 v24, 0
	v_mov_b32_e32 v25, 0
	v_mov_b32_e32 v26, 0
	v_mov_b32_e32 v27, 0
	v_mov_b32_e32 v28, 0
	v_mov_b32_e32 v29, 0
	v_mov_b32_e32 v30, 0
	v_mov_b32_e32 v31, 0
	s_cmp_eq_u32 s100, 0
	s_cbranch_scc1 .Lg8_p6h_gb0
	s_barrier
.Lg8_p6h_gb0:
	s_waitcnt vmcnt(4)
	s_barrier
	s_add_u32 s54, s54, 0x80
	s_addc_u32 s55, s55, 0
	s_add_u32 m0, s99, 0x18000
	s_nop 0
	global_load_lds_dwordx4 v205, s[54:55]
	s_add_u32 m0, s99, 0x1a000
	s_nop 0
	global_load_lds_dwordx4 v206, s[54:55]
	s_add_u32 s56, s56, 0x80
	s_addc_u32 s57, s57, 0
	s_add_u32 m0, s99, 0x10000
	s_nop 0
	global_load_lds_dwordx4 v201, s[56:57]
	s_add_u32 m0, s99, 0x12000
	s_nop 0
	global_load_lds_dwordx4 v202, s[56:57]
	s_add_u32 m0, s99, 0x1c000
	s_nop 0
	global_load_lds_dwordx4 v210, s[54:55]
	s_add_u32 m0, s99, 0x1e000
	s_nop 0
	global_load_lds_dwordx4 v211, s[54:55]
	s_waitcnt vmcnt(6)
	s_barrier
	s_mov_b32 s101, 7
.Lg8_p6h_loop:
	ds_read_b128 v[160:163], v197 offset:0
	ds_read_b128 v[164:167], v199 offset:0
	ds_read_b128 v[172:175], v197 offset:2048
	ds_read_b128 v[176:179], v199 offset:2048
	ds_read_b128 v[128:131], v168 offset:0
	ds_read_b128 v[132:135], v171 offset:0
	ds_read_b128 v[136:139], v168 offset:2048
	ds_read_b128 v[140:143], v171 offset:2048
	ds_read_b128 v[144:147], v168 offset:4096
	ds_read_b128 v[148:151], v171 offset:4096
	ds_read_b128 v[152:155], v168 offset:6144
	ds_read_b128 v[156:159], v171 offset:6144
	s_add_u32 m0, s99, 0x14000
	s_nop 0
	global_load_lds_dwordx4 v203, s[56:57]
	s_add_u32 m0, s99, 0x16000
	s_nop 0
	global_load_lds_dwordx4 v204, s[56:57]
	s_waitcnt lgkmcnt(8)
	s_barrier
	s_waitcnt lgkmcnt(0)
	s_setprio 1
	v_mfma_f32_16x16x32_bf16 v[0:3], v[128:131], v[160:163], v[0:3]
	v_mfma_f32_16x16x32_bf16 v[0:3], v[132:135], v[164:167], v[0:3]
	v_mfma_f32_16x16x32_bf16 v[4:7], v[128:131], v[172:175], v[4:7]
	v_mfma_f32_16x16x32_bf16 v[4:7], v[132:135], v[176:179], v[4:7]
	v_mfma_f32_16x16x32_bf16 v[8:11], v[136:139], v[160:163], v[8:11]
	v_mfma_f32_16x16x32_bf16 v[8:11], v[140:143], v[164:167], v[8:11]
	v_mfma_f32_16x16x32_bf16 v[12:15], v[136:139], v[172:175], v[12:15]
	v_mfma_f32_16x16x32_bf16 v[12:15], v[140:143], v[176:179], v[12:15]
	v_mfma_f32_16x16x32_bf16 v[112:115], v[144:147], v[160:163], v[112:115]
	v_mfma_f32_16x16x32_bf16 v[112:115], v[148:151], v[164:167], v[112:115]
	v_mfma_f32_16x16x32_bf16 v[116:119], v[144:147], v[172:175], v[116:119]
	v_mfma_f32_16x16x32_bf16 v[116:119], v[148:151], v[176:179], v[116:119]
	v_mfma_f32_16x16x32_bf16 v[120:123], v[152:155], v[160:163], v[120:123]
	v_mfma_f32_16x16x32_bf16 v[120:123], v[156:159], v[164:167], v[120:123]
	v_mfma_f32_16x16x32_bf16 v[124:127], v[152:155], v[172:175], v[124:127]
	v_mfma_f32_16x16x32_bf16 v[124:127], v[156:159], v[176:179], v[124:127]
	s_setprio 0
	s_barrier
	ds_read_b128 v[180:183], v197 offset:16384
	ds_read_b128 v[184:187], v199 offset:16384
	ds_read_b128 v[188:191], v197 offset:18432
	ds_read_b128 v[192:195], v199 offset:18432
	s_add_u32 s54, s54, 0x80
	s_addc_u32 s55, s55, 0
	s_add_u32 m0, s99, 0x8000
	s_nop 0
	global_load_lds_dwordx4 v205, s[54:55]
	s_add_u32 m0, s99, 0xa000
	s_nop 0
	global_load_lds_dwordx4 v206, s[54:55]
	s_barrier
	s_waitcnt lgkmcnt(0)
	s_setprio 1
	v_mfma_f32_16x16x32_bf16 v[64:67], v[128:131], v[180:183], v[64:67]
	v_mfma_f32_16x16x32_bf16 v[64:67], v[132:135], v[184:187], v[64:67]
	v_mfma_f32_16x16x32_bf16 v[68:71], v[128:131], v[188:191], v[68:71]
	v_mfma_f32_16x16x32_bf16 v[68:71], v[132:135], v[192:195], v[68:71]
	v_mfma_f32_16x16x32_bf16 v[72:75], v[136:139], v[180:183], v[72:75]
	v_mfma_f32_16x16x32_bf16 v[72:75], v[140:143], v[184:187], v[72:75]
	v_mfma_f32_16x16x32_bf16 v[76:79], v[136:139], v[188:191], v[76:79]
	v_mfma_f32_16x16x32_bf16 v[76:79], v[140:143], v[192:195], v[76:79]
	v_mfma_f32_16x16x32_bf16 v[48:51], v[144:147], v[180:183], v[48:51]
	v_mfma_f32_16x16x32_bf16 v[48:51], v[148:151], v[184:187], v[48:51]
	v_mfma_f32_16x16x32_bf16 v[52:55], v[144:147], v[188:191], v[52:55]
	v_mfma_f32_16x16x32_bf16 v[52:55], v[148:151], v[192:195], v[52:55]
	v_mfma_f32_16x16x32_bf16 v[56:59], v[152:155], v[180:183], v[56:59]
	v_mfma_f32_16x16x32_bf16 v[56:59], v[156:159], v[184:187], v[56:59]
	v_mfma_f32_16x16x32_bf16 v[60:63], v[152:155], v[188:191], v[60:63]
	v_mfma_f32_16x16x32_bf16 v[60:63], v[156:159], v[192:195], v[60:63]
	s_setprio 0
	s_barrier
	ds_read_b128 v[128:131], v168 offset:16384
	ds_read_b128 v[132:135], v171 offset:16384
	ds_read_b128 v[136:139], v168 offset:18432
	ds_read_b128 v[140:143], v171 offset:18432
	ds_read_b128 v[144:147], v168 offset:20480
	ds_read_b128 v[148:151], v171 offset:20480
	ds_read_b128 v[152:155], v168 offset:22528
	ds_read_b128 v[156:159], v171 offset:22528
	s_add_u32 s56, s56, 0x80
	s_addc_u32 s57, s57, 0
	s_add_u32 m0, s99, 0x0
	s_nop 0
	global_load_lds_dwordx4 v201, s[56:57]
	s_add_u32 m0, s99, 0x2000
	s_nop 0
	global_load_lds_dwordx4 v202, s[56:57]
	s_barrier
	s_waitcnt lgkmcnt(0)
	s_setprio 1
	v_mfma_f32_16x16x32_bf16 v[96:99], v[128:131], v[160:163], v[96:99]
	v_mfma_f32_16x16x32_bf16 v[96:99], v[132:135], v[164:167], v[96:99]
	v_mfma_f32_16x16x32_bf16 v[100:103], v[128:131], v[172:175], v[100:103]
	v_mfma_f32_16x16x32_bf16 v[100:103], v[132:135], v[176:179], v[100:103]
	v_mfma_f32_16x16x32_bf16 v[104:107], v[136:139], v[160:163], v[104:107]
	v_mfma_f32_16x16x32_bf16 v[104:107], v[140:143], v[164:167], v[104:107]
	v_mfma_f32_16x16x32_bf16 v[108:111], v[136:139], v[172:175], v[108:111]
	v_mfma_f32_16x16x32_bf16 v[108:111], v[140:143], v[176:179], v[108:111]
	v_mfma_f32_16x16x32_bf16 v[80:83], v[144:147], v[160:163], v[80:83]
	v_mfma_f32_16x16x32_bf16 v[80:83], v[148:151], v[164:167], v[80:83]
	v_mfma_f32_16x16x32_bf16 v[84:87], v[144:147], v[172:175], v[84:87]
	v_mfma_f32_16x16x32_bf16 v[84:87], v[148:151], v[176:179], v[84:87]
	v_mfma_f32_16x16x32_bf16 v[88:91], v[152:155], v[160:163], v[88:91]
	v_mfma_f32_16x16x32_bf16 v[88:91], v[156:159], v[164:167], v[88:91]
	v_mfma_f32_16x16x32_bf16 v[92:95], v[152:155], v[172:175], v[92:95]
	v_mfma_f32_16x16x32_bf16 v[92:95], v[156:159], v[176:179], v[92:95]
	s_setprio 0
	s_barrier
	s_add_u32 m0, s99, 0xc000
	s_nop 0
	global_load_lds_dwordx4 v210, s[54:55]
	s_add_u32 m0, s99, 0xe000
	s_nop 0
	global_load_lds_dwordx4 v211, s[54:55]
	s_waitcnt vmcnt(6)
	s_barrier
	s_setprio 1
	v_mfma_f32_16x16x32_bf16 v[32:35], v[128:131], v[180:183], v[32:35]
	v_mfma_f32_16x16x32_bf16 v[32:35], v[132:135], v[184:187], v[32:35]
	v_mfma_f32_16x16x32_bf16 v[36:39], v[128:131], v[188:191], v[36:39]
	v_mfma_f32_16x16x32_bf16 v[36:39], v[132:135], v[192:195], v[36:39]
	v_mfma_f32_16x16x32_bf16 v[40:43], v[136:139], v[180:183], v[40:43]
	v_mfma_f32_16x16x32_bf16 v[40:43], v[140:143], v[184:187], v[40:43]
	v_mfma_f32_16x16x32_bf16 v[44:47], v[136:139], v[188:191], v[44:47]
	v_mfma_f32_16x16x32_bf16 v[44:47], v[140:143], v[192:195], v[44:47]
	v_mfma_f32_16x16x32_bf16 v[16:19], v[144:147], v[180:183], v[16:19]
	v_mfma_f32_16x16x32_bf16 v[16:19], v[148:151], v[184:187], v[16:19]
	v_mfma_f32_16x16x32_bf16 v[20:23], v[144:147], v[188:191], v[20:23]
	v_mfma_f32_16x16x32_bf16 v[20:23], v[148:151], v[192:195], v[20:23]
	v_mfma_f32_16x16x32_bf16 v[24:27], v[152:155], v[180:183], v[24:27]
	v_mfma_f32_16x16x32_bf16 v[24:27], v[156:159], v[184:187], v[24:27]
	v_mfma_f32_16x16x32_bf16 v[28:31], v[152:155], v[188:191], v[28:31]
	v_mfma_f32_16x16x32_bf16 v[28:31], v[156:159], v[192:195], v[28:31]
	s_setprio 0
	s_barrier
	ds_read_b128 v[160:163], v198 offset:0
	ds_read_b128 v[164:167], v200 offset:0
	ds_read_b128 v[172:175], v198 offset:2048
	ds_read_b128 v[176:179], v200 offset:2048
	ds_read_b128 v[128:131], v170 offset:0
	ds_read_b128 v[132:135], v196 offset:0
	ds_read_b128 v[136:139], v170 offset:2048
	ds_read_b128 v[140:143], v196 offset:2048
	ds_read_b128 v[144:147], v170 offset:4096
	ds_read_b128 v[148:151], v196 offset:4096
	ds_read_b128 v[152:155], v170 offset:6144
	ds_read_b128 v[156:159], v196 offset:6144
	s_add_u32 m0, s99, 0x4000
	s_nop 0
	global_load_lds_dwordx4 v203, s[56:57]
	s_add_u32 m0, s99, 0x6000
	s_nop 0
	global_load_lds_dwordx4 v204, s[56:57]
	s_waitcnt lgkmcnt(8)
	s_barrier
	s_waitcnt lgkmcnt(0)
	s_setprio 1
	v_mfma_f32_16x16x32_bf16 v[0:3], v[128:131], v[160:163], v[0:3]
	v_mfma_f32_16x16x32_bf16 v[0:3], v[132:135], v[164:167], v[0:3]
	v_mfma_f32_16x16x32_bf16 v[4:7], v[128:131], v[172:175], v[4:7]
	v_mfma_f32_16x16x32_bf16 v[4:7], v[132:135], v[176:179], v[4:7]
	v_mfma_f32_16x16x32_bf16 v[8:11], v[136:139], v[160:163], v[8:11]
	v_mfma_f32_16x16x32_bf16 v[8:11], v[140:143], v[164:167], v[8:11]
	v_mfma_f32_16x16x32_bf16 v[12:15], v[136:139], v[172:175], v[12:15]
	v_mfma_f32_16x16x32_bf16 v[12:15], v[140:143], v[176:179], v[12:15]
	v_mfma_f32_16x16x32_bf16 v[112:115], v[144:147], v[160:163], v[112:115]
	v_mfma_f32_16x16x32_bf16 v[112:115], v[148:151], v[164:167], v[112:115]
	v_mfma_f32_16x16x32_bf16 v[116:119], v[144:147], v[172:175], v[116:119]
	v_mfma_f32_16x16x32_bf16 v[116:119], v[148:151], v[176:179], v[116:119]
	v_mfma_f32_16x16x32_bf16 v[120:123], v[152:155], v[160:163], v[120:123]
	v_mfma_f32_16x16x32_bf16 v[120:123], v[156:159], v[164:167], v[120:123]
	v_mfma_f32_16x16x32_bf16 v[124:127], v[152:155], v[172:175], v[124:127]
	v_mfma_f32_16x16x32_bf16 v[124:127], v[156:159], v[176:179], v[124:127]
	s_setprio 0
	s_barrier
	ds_read_b128 v[180:183], v198 offset:16384
	ds_read_b128 v[184:187], v200 offset:16384
	ds_read_b128 v[188:191], v198 offset:18432
	ds_read_b128 v[192:195], v200 offset:18432
	s_add_u32 s54, s54, 0x80
	s_addc_u32 s55, s55, 0
	s_add_u32 m0, s99, 0x18000
	s_nop 0
	global_load_lds_dwordx4 v205, s[54:55]
	s_add_u32 m0, s99, 0x1a000
	s_nop 0
	global_load_lds_dwordx4 v206, s[54:55]
	s_barrier
	s_waitcnt lgkmcnt(0)
	s_setprio 1
	v_mfma_f32_16x16x32_bf16 v[64:67], v[128:131], v[180:183], v[64:67]
	v_mfma_f32_16x16x32_bf16 v[64:67], v[132:135], v[184:187], v[64:67]
	v_mfma_f32_16x16x32_bf16 v[68:71], v[128:131], v[188:191], v[68:71]
	v_mfma_f32_16x16x32_bf16 v[68:71], v[132:135], v[192:195], v[68:71]
	v_mfma_f32_16x16x32_bf16 v[72:75], v[136:139], v[180:183], v[72:75]
	v_mfma_f32_16x16x32_bf16 v[72:75], v[140:143], v[184:187], v[72:75]
	v_mfma_f32_16x16x32_bf16 v[76:79], v[136:139], v[188:191], v[76:79]
	v_mfma_f32_16x16x32_bf16 v[76:79], v[140:143], v[192:195], v[76:79]
	v_mfma_f32_16x16x32_bf16 v[48:51], v[144:147], v[180:183], v[48:51]
	v_mfma_f32_16x16x32_bf16 v[48:51], v[148:151], v[184:187], v[48:51]
	v_mfma_f32_16x16x32_bf16 v[52:55], v[144:147], v[188:191], v[52:55]
	v_mfma_f32_16x16x32_bf16 v[52:55], v[148:151], v[192:195], v[52:55]
	v_mfma_f32_16x16x32_bf16 v[56:59], v[152:155], v[180:183], v[56:59]
	v_mfma_f32_16x16x32_bf16 v[56:59], v[156:159], v[184:187], v[56:59]
	v_mfma_f32_16x16x32_bf16 v[60:63], v[152:155], v[188:191], v[60:63]
	v_mfma_f32_16x16x32_bf16 v[60:63], v[156:159], v[192:195], v[60:63]
	s_setprio 0
	s_barrier
	ds_read_b128 v[128:131], v170 offset:16384
	ds_read_b128 v[132:135], v196 offset:16384
	ds_read_b128 v[136:139], v170 offset:18432
	ds_read_b128 v[140:143], v196 offset:18432
	ds_read_b128 v[144:147], v170 offset:20480
	ds_read_b128 v[148:151], v196 offset:20480
	ds_read_b128 v[152:155], v170 offset:22528
	ds_read_b128 v[156:159], v196 offset:22528
	s_add_u32 s56, s56, 0x80
	s_addc_u32 s57, s57, 0
	s_add_u32 m0, s99, 0x10000
	s_nop 0
	global_load_lds_dwordx4 v201, s[56:57]
	s_add_u32 m0, s99, 0x12000
	s_nop 0
	global_load_lds_dwordx4 v202, s[56:57]
	s_barrier
	s_waitcnt lgkmcnt(0)
	s_setprio 1
	v_mfma_f32_16x16x32_bf16 v[96:99], v[128:131], v[160:163], v[96:99]
	v_mfma_f32_16x16x32_bf16 v[96:99], v[132:135], v[164:167], v[96:99]
	v_mfma_f32_16x16x32_bf16 v[100:103], v[128:131], v[172:175], v[100:103]
	v_mfma_f32_16x16x32_bf16 v[100:103], v[132:135], v[176:179], v[100:103]
	v_mfma_f32_16x16x32_bf16 v[104:107], v[136:139], v[160:163], v[104:107]
	v_mfma_f32_16x16x32_bf16 v[104:107], v[140:143], v[164:167], v[104:107]
	v_mfma_f32_16x16x32_bf16 v[108:111], v[136:139], v[172:175], v[108:111]
	v_mfma_f32_16x16x32_bf16 v[108:111], v[140:143], v[176:179], v[108:111]
	v_mfma_f32_16x16x32_bf16 v[80:83], v[144:147], v[160:163], v[80:83]
	v_mfma_f32_16x16x32_bf16 v[80:83], v[148:151], v[164:167], v[80:83]
	v_mfma_f32_16x16x32_bf16 v[84:87], v[144:147], v[172:175], v[84:87]
	v_mfma_f32_16x16x32_bf16 v[84:87], v[148:151], v[176:179], v[84:87]
	v_mfma_f32_16x16x32_bf16 v[88:91], v[152:155], v[160:163], v[88:91]
	v_mfma_f32_16x16x32_bf16 v[88:91], v[156:159], v[164:167], v[88:91]
	v_mfma_f32_16x16x32_bf16 v[92:95], v[152:155], v[172:175], v[92:95]
	v_mfma_f32_16x16x32_bf16 v[92:95], v[156:159], v[176:179], v[92:95]
	s_setprio 0
	s_barrier
	s_add_u32 m0, s99, 0x1c000
	s_nop 0
	global_load_lds_dwordx4 v210, s[54:55]
	s_add_u32 m0, s99, 0x1e000
	s_nop 0
	global_load_lds_dwordx4 v211, s[54:55]
	s_waitcnt vmcnt(6)
	s_barrier
	s_setprio 1
	v_mfma_f32_16x16x32_bf16 v[32:35], v[128:131], v[180:183], v[32:35]
	v_mfma_f32_16x16x32_bf16 v[32:35], v[132:135], v[184:187], v[32:35]
	v_mfma_f32_16x16x32_bf16 v[36:39], v[128:131], v[188:191], v[36:39]
	v_mfma_f32_16x16x32_bf16 v[36:39], v[132:135], v[192:195], v[36:39]
	v_mfma_f32_16x16x32_bf16 v[40:43], v[136:139], v[180:183], v[40:43]
	v_mfma_f32_16x16x32_bf16 v[40:43], v[140:143], v[184:187], v[40:43]
	v_mfma_f32_16x16x32_bf16 v[44:47], v[136:139], v[188:191], v[44:47]
	v_mfma_f32_16x16x32_bf16 v[44:47], v[140:143], v[192:195], v[44:47]
	v_mfma_f32_16x16x32_bf16 v[16:19], v[144:147], v[180:183], v[16:19]
	v_mfma_f32_16x16x32_bf16 v[16:19], v[148:151], v[184:187], v[16:19]
	v_mfma_f32_16x16x32_bf16 v[20:23], v[144:147], v[188:191], v[20:23]
	v_mfma_f32_16x16x32_bf16 v[20:23], v[148:151], v[192:195], v[20:23]
	v_mfma_f32_16x16x32_bf16 v[24:27], v[152:155], v[180:183], v[24:27]
	v_mfma_f32_16x16x32_bf16 v[24:27], v[156:159], v[184:187], v[24:27]
	v_mfma_f32_16x16x32_bf16 v[28:31], v[152:155], v[188:191], v[28:31]
	v_mfma_f32_16x16x32_bf16 v[28:31], v[156:159], v[192:195], v[28:31]
	s_setprio 0
	s_barrier
	s_sub_u32 s101, s101, 1
	s_cmp_lg_u32 s101, 0
	s_cbranch_scc1 .Lg8_p6h_loop
	ds_read_b128 v[160:163], v197 offset:0
	ds_read_b128 v[164:167], v199 offset:0
	ds_read_b128 v[172:175], v197 offset:2048
	ds_read_b128 v[176:179], v199 offset:2048
	ds_read_b128 v[128:131], v168 offset:0
	ds_read_b128 v[132:135], v171 offset:0
	ds_read_b128 v[136:139], v168 offset:2048
	ds_read_b128 v[140:143], v171 offset:2048
	ds_read_b128 v[144:147], v168 offset:4096
	ds_read_b128 v[148:151], v171 offset:4096
	ds_read_b128 v[152:155], v168 offset:6144
	ds_read_b128 v[156:159], v171 offset:6144
	s_add_u32 m0, s99, 0x14000
	s_nop 0
	global_load_lds_dwordx4 v203, s[56:57]
	s_add_u32 m0, s99, 0x16000
	s_nop 0
	global_load_lds_dwordx4 v204, s[56:57]
	s_barrier
	s_waitcnt lgkmcnt(0)
	s_setprio 1
	v_mfma_f32_16x16x32_bf16 v[0:3], v[128:131], v[160:163], v[0:3]
	v_mfma_f32_16x16x32_bf16 v[0:3], v[132:135], v[164:167], v[0:3]
	v_mfma_f32_16x16x32_bf16 v[4:7], v[128:131], v[172:175], v[4:7]
	v_mfma_f32_16x16x32_bf16 v[4:7], v[132:135], v[176:179], v[4:7]
	v_mfma_f32_16x16x32_bf16 v[8:11], v[136:139], v[160:163], v[8:11]
	v_mfma_f32_16x16x32_bf16 v[8:11], v[140:143], v[164:167], v[8:11]
	v_mfma_f32_16x16x32_bf16 v[12:15], v[136:139], v[172:175], v[12:15]
	v_mfma_f32_16x16x32_bf16 v[12:15], v[140:143], v[176:179], v[12:15]
	v_mfma_f32_16x16x32_bf16 v[112:115], v[144:147], v[160:163], v[112:115]
	v_mfma_f32_16x16x32_bf16 v[112:115], v[148:151], v[164:167], v[112:115]
	v_mfma_f32_16x16x32_bf16 v[116:119], v[144:147], v[172:175], v[116:119]
	v_mfma_f32_16x16x32_bf16 v[116:119], v[148:151], v[176:179], v[116:119]
	v_mfma_f32_16x16x32_bf16 v[120:123], v[152:155], v[160:163], v[120:123]
	v_mfma_f32_16x16x32_bf16 v[120:123], v[156:159], v[164:167], v[120:123]
	v_mfma_f32_16x16x32_bf16 v[124:127], v[152:155], v[172:175], v[124:127]
	v_mfma_f32_16x16x32_bf16 v[124:127], v[156:159], v[176:179], v[124:127]
	s_setprio 0
	s_barrier
	ds_read_b128 v[180:183], v197 offset:16384
	ds_read_b128 v[184:187], v199 offset:16384
	ds_read_b128 v[188:191], v197 offset:18432
	ds_read_b128 v[192:195], v199 offset:18432
	s_barrier
	s_waitcnt lgkmcnt(0)
	s_setprio 1
	v_mfma_f32_16x16x32_bf16 v[64:67], v[128:131], v[180:183], v[64:67]
	v_mfma_f32_16x16x32_bf16 v[64:67], v[132:135], v[184:187], v[64:67]
	v_mfma_f32_16x16x32_bf16 v[68:71], v[128:131], v[188:191], v[68:71]
	v_mfma_f32_16x16x32_bf16 v[68:71], v[132:135], v[192:195], v[68:71]
	v_mfma_f32_16x16x32_bf16 v[72:75], v[136:139], v[180:183], v[72:75]
	v_mfma_f32_16x16x32_bf16 v[72:75], v[140:143], v[184:187], v[72:75]
	v_mfma_f32_16x16x32_bf16 v[76:79], v[136:139], v[188:191], v[76:79]
	v_mfma_f32_16x16x32_bf16 v[76:79], v[140:143], v[192:195], v[76:79]
	v_mfma_f32_16x16x32_bf16 v[48:51], v[144:147], v[180:183], v[48:51]
	v_mfma_f32_16x16x32_bf16 v[48:51], v[148:151], v[184:187], v[48:51]
	v_mfma_f32_16x16x32_bf16 v[52:55], v[144:147], v[188:191], v[52:55]
	v_mfma_f32_16x16x32_bf16 v[52:55], v[148:151], v[192:195], v[52:55]
	v_mfma_f32_16x16x32_bf16 v[56:59], v[152:155], v[180:183], v[56:59]
	v_mfma_f32_16x16x32_bf16 v[56:59], v[156:159], v[184:187], v[56:59]
	v_mfma_f32_16x16x32_bf16 v[60:63], v[152:155], v[188:191], v[60:63]
	v_mfma_f32_16x16x32_bf16 v[60:63], v[156:159], v[192:195], v[60:63]
	s_setprio 0
	s_barrier
	ds_read_b128 v[128:131], v168 offset:16384
	ds_read_b128 v[132:135], v171 offset:16384
	ds_read_b128 v[136:139], v168 offset:18432
	ds_read_b128 v[140:143], v171 offset:18432
	ds_read_b128 v[144:147], v168 offset:20480
	ds_read_b128 v[148:151], v171 offset:20480
	ds_read_b128 v[152:155], v168 offset:22528
	ds_read_b128 v[156:159], v171 offset:22528
	s_waitcnt vmcnt(4)
	s_barrier
	s_waitcnt lgkmcnt(0)
	s_setprio 1
	v_mfma_f32_16x16x32_bf16 v[96:99], v[128:131], v[160:163], v[96:99]
	v_mfma_f32_16x16x32_bf16 v[96:99], v[132:135], v[164:167], v[96:99]
	v_mfma_f32_16x16x32_bf16 v[100:103], v[128:131], v[172:175], v[100:103]
	v_mfma_f32_16x16x32_bf16 v[100:103], v[132:135], v[176:179], v[100:103]
	v_mfma_f32_16x16x32_bf16 v[104:107], v[136:139], v[160:163], v[104:107]
	v_mfma_f32_16x16x32_bf16 v[104:107], v[140:143], v[164:167], v[104:107]
	v_mfma_f32_16x16x32_bf16 v[108:111], v[136:139], v[172:175], v[108:111]
	v_mfma_f32_16x16x32_bf16 v[108:111], v[140:143], v[176:179], v[108:111]
	v_mfma_f32_16x16x32_bf16 v[80:83], v[144:147], v[160:163], v[80:83]
	v_mfma_f32_16x16x32_bf16 v[80:83], v[148:151], v[164:167], v[80:83]
	v_mfma_f32_16x16x32_bf16 v[84:87], v[144:147], v[172:175], v[84:87]
	v_mfma_f32_16x16x32_bf16 v[84:87], v[148:151], v[176:179], v[84:87]
	v_mfma_f32_16x16x32_bf16 v[88:91], v[152:155], v[160:163], v[88:91]
	v_mfma_f32_16x16x32_bf16 v[88:91], v[156:159], v[164:167], v[88:91]
	v_mfma_f32_16x16x32_bf16 v[92:95], v[152:155], v[172:175], v[92:95]
	v_mfma_f32_16x16x32_bf16 v[92:95], v[156:159], v[176:179], v[92:95]
	s_setprio 0
	s_setprio 1
	v_mfma_f32_16x16x32_bf16 v[32:35], v[128:131], v[180:183], v[32:35]
	v_mfma_f32_16x16x32_bf16 v[32:35], v[132:135], v[184:187], v[32:35]
	v_mfma_f32_16x16x32_bf16 v[36:39], v[128:131], v[188:191], v[36:39]
	v_mfma_f32_16x16x32_bf16 v[36:39], v[132:135], v[192:195], v[36:39]
	v_mfma_f32_16x16x32_bf16 v[40:43], v[136:139], v[180:183], v[40:43]
	v_mfma_f32_16x16x32_bf16 v[40:43], v[140:143], v[184:187], v[40:43]
	v_mfma_f32_16x16x32_bf16 v[44:47], v[136:139], v[188:191], v[44:47]
	v_mfma_f32_16x16x32_bf16 v[44:47], v[140:143], v[192:195], v[44:47]
	v_mfma_f32_16x16x32_bf16 v[16:19], v[144:147], v[180:183], v[16:19]
	v_mfma_f32_16x16x32_bf16 v[16:19], v[148:151], v[184:187], v[16:19]
	v_mfma_f32_16x16x32_bf16 v[20:23], v[144:147], v[188:191], v[20:23]
	v_mfma_f32_16x16x32_bf16 v[20:23], v[148:151], v[192:195], v[20:23]
	v_mfma_f32_16x16x32_bf16 v[24:27], v[152:155], v[180:183], v[24:27]
	v_mfma_f32_16x16x32_bf16 v[24:27], v[156:159], v[184:187], v[24:27]
	v_mfma_f32_16x16x32_bf16 v[28:31], v[152:155], v[188:191], v[28:31]
	v_mfma_f32_16x16x32_bf16 v[28:31], v[156:159], v[192:195], v[28:31]
	s_setprio 0
	s_barrier
	ds_read_b128 v[160:163], v198 offset:0
	ds_read_b128 v[164:167], v200 offset:0
	ds_read_b128 v[172:175], v198 offset:2048
	ds_read_b128 v[176:179], v200 offset:2048
	ds_read_b128 v[128:131], v170 offset:0
	ds_read_b128 v[132:135], v196 offset:0
	ds_read_b128 v[136:139], v170 offset:2048
	ds_read_b128 v[140:143], v196 offset:2048
	ds_read_b128 v[144:147], v170 offset:4096
	ds_read_b128 v[148:151], v196 offset:4096
	ds_read_b128 v[152:155], v170 offset:6144
	ds_read_b128 v[156:159], v196 offset:6144
	s_waitcnt vmcnt(2)
	s_barrier
	s_waitcnt lgkmcnt(0)
	s_setprio 1
	v_mfma_f32_16x16x32_bf16 v[0:3], v[128:131], v[160:163], v[0:3]
	v_mfma_f32_16x16x32_bf16 v[0:3], v[132:135], v[164:167], v[0:3]
	v_mfma_f32_16x16x32_bf16 v[4:7], v[128:131], v[172:175], v[4:7]
	v_mfma_f32_16x16x32_bf16 v[4:7], v[132:135], v[176:179], v[4:7]
	v_mfma_f32_16x16x32_bf16 v[8:11], v[136:139], v[160:163], v[8:11]
	v_mfma_f32_16x16x32_bf16 v[8:11], v[140:143], v[164:167], v[8:11]
	v_mfma_f32_16x16x32_bf16 v[12:15], v[136:139], v[172:175], v[12:15]
	v_mfma_f32_16x16x32_bf16 v[12:15], v[140:143], v[176:179], v[12:15]
	v_mfma_f32_16x16x32_bf16 v[112:115], v[144:147], v[160:163], v[112:115]
	v_mfma_f32_16x16x32_bf16 v[112:115], v[148:151], v[164:167], v[112:115]
	v_mfma_f32_16x16x32_bf16 v[116:119], v[144:147], v[172:175], v[116:119]
	v_mfma_f32_16x16x32_bf16 v[116:119], v[148:151], v[176:179], v[116:119]
	v_mfma_f32_16x16x32_bf16 v[120:123], v[152:155], v[160:163], v[120:123]
	v_mfma_f32_16x16x32_bf16 v[120:123], v[156:159], v[164:167], v[120:123]
	v_mfma_f32_16x16x32_bf16 v[124:127], v[152:155], v[172:175], v[124:127]
	v_mfma_f32_16x16x32_bf16 v[124:127], v[156:159], v[176:179], v[124:127]
	s_setprio 0
	s_barrier
	ds_read_b128 v[180:183], v198 offset:16384
	ds_read_b128 v[184:187], v200 offset:16384
	ds_read_b128 v[188:191], v198 offset:18432
	ds_read_b128 v[192:195], v200 offset:18432
	s_waitcnt vmcnt(0)
	s_barrier
	s_waitcnt lgkmcnt(0)
	s_setprio 1
	v_mfma_f32_16x16x32_bf16 v[64:67], v[128:131], v[180:183], v[64:67]
	v_mfma_f32_16x16x32_bf16 v[64:67], v[132:135], v[184:187], v[64:67]
	v_mfma_f32_16x16x32_bf16 v[68:71], v[128:131], v[188:191], v[68:71]
	v_mfma_f32_16x16x32_bf16 v[68:71], v[132:135], v[192:195], v[68:71]
	v_mfma_f32_16x16x32_bf16 v[72:75], v[136:139], v[180:183], v[72:75]
	v_mfma_f32_16x16x32_bf16 v[72:75], v[140:143], v[184:187], v[72:75]
	v_mfma_f32_16x16x32_bf16 v[76:79], v[136:139], v[188:191], v[76:79]
	v_mfma_f32_16x16x32_bf16 v[76:79], v[140:143], v[192:195], v[76:79]
	v_mfma_f32_16x16x32_bf16 v[48:51], v[144:147], v[180:183], v[48:51]
	v_mfma_f32_16x16x32_bf16 v[48:51], v[148:151], v[184:187], v[48:51]
	v_mfma_f32_16x16x32_bf16 v[52:55], v[144:147], v[188:191], v[52:55]
	v_mfma_f32_16x16x32_bf16 v[52:55], v[148:151], v[192:195], v[52:55]
	v_mfma_f32_16x16x32_bf16 v[56:59], v[152:155], v[180:183], v[56:59]
	v_mfma_f32_16x16x32_bf16 v[56:59], v[156:159], v[184:187], v[56:59]
	v_mfma_f32_16x16x32_bf16 v[60:63], v[152:155], v[188:191], v[60:63]
	v_mfma_f32_16x16x32_bf16 v[60:63], v[156:159], v[192:195], v[60:63]
	s_setprio 0
	s_barrier
	ds_read_b128 v[128:131], v170 offset:16384
	ds_read_b128 v[132:135], v196 offset:16384
	ds_read_b128 v[136:139], v170 offset:18432
	ds_read_b128 v[140:143], v196 offset:18432
	ds_read_b128 v[144:147], v170 offset:20480
	ds_read_b128 v[148:151], v196 offset:20480
	ds_read_b128 v[152:155], v170 offset:22528
	ds_read_b128 v[156:159], v196 offset:22528
	s_barrier
	s_waitcnt lgkmcnt(0)
	s_setprio 1
	v_mfma_f32_16x16x32_bf16 v[96:99], v[128:131], v[160:163], v[96:99]
	v_mfma_f32_16x16x32_bf16 v[96:99], v[132:135], v[164:167], v[96:99]
	v_mfma_f32_16x16x32_bf16 v[100:103], v[128:131], v[172:175], v[100:103]
	v_mfma_f32_16x16x32_bf16 v[100:103], v[132:135], v[176:179], v[100:103]
	v_mfma_f32_16x16x32_bf16 v[104:107], v[136:139], v[160:163], v[104:107]
	v_mfma_f32_16x16x32_bf16 v[104:107], v[140:143], v[164:167], v[104:107]
	v_mfma_f32_16x16x32_bf16 v[108:111], v[136:139], v[172:175], v[108:111]
	v_mfma_f32_16x16x32_bf16 v[108:111], v[140:143], v[176:179], v[108:111]
	v_mfma_f32_16x16x32_bf16 v[80:83], v[144:147], v[160:163], v[80:83]
	v_mfma_f32_16x16x32_bf16 v[80:83], v[148:151], v[164:167], v[80:83]
	v_mfma_f32_16x16x32_bf16 v[84:87], v[144:147], v[172:175], v[84:87]
	v_mfma_f32_16x16x32_bf16 v[84:87], v[148:151], v[176:179], v[84:87]
	v_mfma_f32_16x16x32_bf16 v[88:91], v[152:155], v[160:163], v[88:91]
	v_mfma_f32_16x16x32_bf16 v[88:91], v[156:159], v[164:167], v[88:91]
	v_mfma_f32_16x16x32_bf16 v[92:95], v[152:155], v[172:175], v[92:95]
	v_mfma_f32_16x16x32_bf16 v[92:95], v[156:159], v[176:179], v[92:95]
	s_setprio 0
	s_setprio 1
	v_mfma_f32_16x16x32_bf16 v[32:35], v[128:131], v[180:183], v[32:35]
	v_mfma_f32_16x16x32_bf16 v[32:35], v[132:135], v[184:187], v[32:35]
	v_mfma_f32_16x16x32_bf16 v[36:39], v[128:131], v[188:191], v[36:39]
	v_mfma_f32_16x16x32_bf16 v[36:39], v[132:135], v[192:195], v[36:39]
	v_mfma_f32_16x16x32_bf16 v[40:43], v[136:139], v[180:183], v[40:43]
	v_mfma_f32_16x16x32_bf16 v[40:43], v[140:143], v[184:187], v[40:43]
	v_mfma_f32_16x16x32_bf16 v[44:47], v[136:139], v[188:191], v[44:47]
	v_mfma_f32_16x16x32_bf16 v[44:47], v[140:143], v[192:195], v[44:47]
	v_mfma_f32_16x16x32_bf16 v[16:19], v[144:147], v[180:183], v[16:19]
	v_mfma_f32_16x16x32_bf16 v[16:19], v[148:151], v[184:187], v[16:19]
	v_mfma_f32_16x16x32_bf16 v[20:23], v[144:147], v[188:191], v[20:23]
	v_mfma_f32_16x16x32_bf16 v[20:23], v[148:151], v[192:195], v[20:23]
	v_mfma_f32_16x16x32_bf16 v[24:27], v[152:155], v[180:183], v[24:27]
	v_mfma_f32_16x16x32_bf16 v[24:27], v[156:159], v[184:187], v[24:27]
	v_mfma_f32_16x16x32_bf16 v[28:31], v[152:155], v[188:191], v[28:31]
	v_mfma_f32_16x16x32_bf16 v[28:31], v[156:159], v[192:195], v[28:31]
	s_setprio 0
	s_barrier
	s_cmp_lg_u32 s100, 0
	s_cbranch_scc1 .Lg8_p6h_gb1
	s_barrier

.LBB0_840:
	s_ashr_i32 s45, s44, 31
	s_bfe_u32 s27, s56, 0x40004
	s_bfe_u32 s26, s56, 0x10003
	s_lshl_b64 s[58:59], s[44:45], 19
	s_add_u32 s18, s47, s58
	s_addc_u32 s45, s48, s59
	s_lshl_b32 s57, s26, 18
	s_add_u32 s58, s18, s57
	s_addc_u32 s59, s45, 0
	s_mov_b32 s70, s58
	s_mov_b32 s71, s59
	s_lshl_b32 s18, s56, 8
	s_and_b32 s45, s18, 0x700
	s_lshl_b32 s18, s27, 21
	s_add_u32 s2, s2, s18
	s_addc_u32 s3, s3, 0
	s_lshl_b32 s18, s45, 10
	s_add_u32 s2, s2, s18
	s_addc_u32 s3, s3, 0
	s_mov_b32 s72, s2
	s_mov_b32 s73, s3
	s_movk_i32 s2, 0x100
	s_mov_b32 s3, -2
	v_lshrrev_b32_e32 v212, 6, v208
	v_and_b32_e32 v213, 63, v208
	v_readfirstlane_b32 s98, v212
	v_and_b32_e32 v214, 3, v213
	v_bfe_u32 v215, v213, 2, 1
	v_lshl_or_b32 v214, v215, 3, v214
	v_bfe_u32 v215, v213, 3, 1
	v_lshl_or_b32 v214, v215, 2, v214
	s_and_b32 s74, s98, 1
	s_lshr_b32 s100, s98, 2
	s_lshl_b32 s99, s98, 10
	v_lshrrev_b32_e32 v215, 4, v213
	v_bfe_u32 v216, v214, 1, 3
	v_xor_b32_e32 v216, v215, v216
	v_lshlrev_b32_e32 v216, 4, v216
	v_lshl_add_u32 v214, s74, 6, v214
	v_lshl_add_u32 v168, v214, 7, v216
	v_xor_b32_e32 v171, 64, v168
	v_add_u32_e32 v170, 0x10000, v168
	v_add_u32_e32 v196, 0x10000, v171
	v_bfe_u32 v216, v213, 1, 3
	v_xor_b32_e32 v216, v215, v216
	v_lshlrev_b32_e32 v216, 4, v216
	v_and_b32_e32 v214, 15, v213
	s_lshr_b32 s101, s98, 1
	v_lshl_add_u32 v214, s101, 5, v214
	v_lshl_add_u32 v197, v214, 7, v216
	v_add_u32_e32 v197, 0x8000, v197
	v_xor_b32_e32 v199, 64, v197
	v_add_u32_e32 v198, 0x10000, v197
	v_add_u32_e32 v200, 0x10000, v199
	v_lshl_add_u32 v216, s74, 2, v215
	v_and_b32_e32 v214, 7, v213
	v_xor_b32_e32 v216, v214, v216
	v_lshlrev_b32_e32 v216, 4, v216
	v_lshrrev_b32_e32 v214, 3, v213
	v_lshl_add_u32 v215, s98, 3, v214
	v_lshl_add_u32 v201, v215, 10, v216
	v_add_u32_e32 v202, 0x20000, v201
	v_add_u32_e32 v203, 0x10000, v201
	v_add_u32_e32 v204, 0x30000, v201
	s_and_b32 s101, s98, 3
	s_lshl_b32 s101, s101, 3
	s_lshl_b32 s74, s100, 6
	s_add_u32 s101, s101, s74
	v_add_u32_e32 v215, s101, v214
	v_lshl_add_u32 v205, v215, 10, v216
	v_add_u32_e32 v206, 0x20000, v205
	v_add_u32_e32 v210, 0x8000, v205
	v_add_u32_e32 v211, 0x28000, v205
	s_add_u32 m0, s99, 0x8000
	s_nop 0
	global_load_lds_dwordx4 v205, s[70:71]
	s_add_u32 m0, s99, 0xa000
	s_nop 0
	global_load_lds_dwordx4 v206, s[70:71]
	s_add_u32 m0, s99, 0x0
	s_nop 0
	global_load_lds_dwordx4 v201, s[72:73]
	s_add_u32 m0, s99, 0x2000
	s_nop 0
	global_load_lds_dwordx4 v202, s[72:73]
	s_add_u32 m0, s99, 0xc000
	s_nop 0
	global_load_lds_dwordx4 v210, s[70:71]
	s_add_u32 m0, s99, 0xe000
	s_nop 0
	global_load_lds_dwordx4 v211, s[70:71]
	s_add_u32 m0, s99, 0x4000
	s_nop 0
	global_load_lds_dwordx4 v203, s[72:73]
	s_add_u32 m0, s99, 0x6000
	s_nop 0
	global_load_lds_dwordx4 v204, s[72:73]
	v_mov_b32_e32 v112, 0
	v_mov_b32_e32 v113, 0
	v_mov_b32_e32 v114, 0
	v_mov_b32_e32 v115, 0
	v_mov_b32_e32 v116, 0
	v_mov_b32_e32 v117, 0
	v_mov_b32_e32 v118, 0
	v_mov_b32_e32 v119, 0
	v_mov_b32_e32 v120, 0
	v_mov_b32_e32 v121, 0
	v_mov_b32_e32 v122, 0
	v_mov_b32_e32 v123, 0
	v_mov_b32_e32 v124, 0
	v_mov_b32_e32 v125, 0
	v_mov_b32_e32 v126, 0
	v_mov_b32_e32 v127, 0
	v_mov_b32_e32 v96, 0
	v_mov_b32_e32 v97, 0
	v_mov_b32_e32 v98, 0
	v_mov_b32_e32 v99, 0
	v_mov_b32_e32 v100, 0
	v_mov_b32_e32 v101, 0
	v_mov_b32_e32 v102, 0
	v_mov_b32_e32 v103, 0
	v_mov_b32_e32 v104, 0
	v_mov_b32_e32 v105, 0
	v_mov_b32_e32 v106, 0
	v_mov_b32_e32 v107, 0
	v_mov_b32_e32 v108, 0
	v_mov_b32_e32 v109, 0
	v_mov_b32_e32 v110, 0
	v_mov_b32_e32 v111, 0
	v_mov_b32_e32 v80, 0
	v_mov_b32_e32 v81, 0
	v_mov_b32_e32 v82, 0
	v_mov_b32_e32 v83, 0
	v_mov_b32_e32 v84, 0
	v_mov_b32_e32 v85, 0
	v_mov_b32_e32 v86, 0
	v_mov_b32_e32 v87, 0
	v_mov_b32_e32 v88, 0
	v_mov_b32_e32 v89, 0
	v_mov_b32_e32 v90, 0
	v_mov_b32_e32 v91, 0
	v_mov_b32_e32 v92, 0
	v_mov_b32_e32 v93, 0
	v_mov_b32_e32 v94, 0
	v_mov_b32_e32 v95, 0
	v_mov_b32_e32 v64, 0
	v_mov_b32_e32 v65, 0
	v_mov_b32_e32 v66, 0
	v_mov_b32_e32 v67, 0
	v_mov_b32_e32 v68, 0
	v_mov_b32_e32 v69, 0
	v_mov_b32_e32 v70, 0
	v_mov_b32_e32 v71, 0
	v_mov_b32_e32 v72, 0
	v_mov_b32_e32 v73, 0
	v_mov_b32_e32 v74, 0
	v_mov_b32_e32 v75, 0
	v_mov_b32_e32 v76, 0
	v_mov_b32_e32 v77, 0
	v_mov_b32_e32 v78, 0
	v_mov_b32_e32 v79, 0
	v_mov_b32_e32 v48, 0
	v_mov_b32_e32 v49, 0
	v_mov_b32_e32 v50, 0
	v_mov_b32_e32 v51, 0
	v_mov_b32_e32 v52, 0
	v_mov_b32_e32 v53, 0
	v_mov_b32_e32 v54, 0
	v_mov_b32_e32 v55, 0
	v_mov_b32_e32 v56, 0
	v_mov_b32_e32 v57, 0
	v_mov_b32_e32 v58, 0
	v_mov_b32_e32 v59, 0
	v_mov_b32_e32 v60, 0
	v_mov_b32_e32 v61, 0
	v_mov_b32_e32 v62, 0
	v_mov_b32_e32 v63, 0
	v_mov_b32_e32 v32, 0
	v_mov_b32_e32 v33, 0
	v_mov_b32_e32 v34, 0
	v_mov_b32_e32 v35, 0
	v_mov_b32_e32 v36, 0
	v_mov_b32_e32 v37, 0
	v_mov_b32_e32 v38, 0
	v_mov_b32_e32 v39, 0
	v_mov_b32_e32 v40, 0
	v_mov_b32_e32 v41, 0
	v_mov_b32_e32 v42, 0
	v_mov_b32_e32 v43, 0
	v_mov_b32_e32 v44, 0
	v_mov_b32_e32 v45, 0
	v_mov_b32_e32 v46, 0
	v_mov_b32_e32 v47, 0
	v_mov_b32_e32 v16, 0
	v_mov_b32_e32 v17, 0
	v_mov_b32_e32 v18, 0
	v_mov_b32_e32 v19, 0
	v_mov_b32_e32 v20, 0
	v_mov_b32_e32 v21, 0
	v_mov_b32_e32 v22, 0
	v_mov_b32_e32 v23, 0
	v_mov_b32_e32 v24, 0
	v_mov_b32_e32 v25, 0
	v_mov_b32_e32 v26, 0
	v_mov_b32_e32 v27, 0
	v_mov_b32_e32 v28, 0
	v_mov_b32_e32 v29, 0
	v_mov_b32_e32 v30, 0
	v_mov_b32_e32 v31, 0
	v_mov_b32_e32 v0, 0
	v_mov_b32_e32 v1, 0
	v_mov_b32_e32 v2, 0
	v_mov_b32_e32 v3, 0
	v_mov_b32_e32 v4, 0
	v_mov_b32_e32 v5, 0
	v_mov_b32_e32 v6, 0
	v_mov_b32_e32 v7, 0
	v_mov_b32_e32 v8, 0
	v_mov_b32_e32 v9, 0
	v_mov_b32_e32 v10, 0
	v_mov_b32_e32 v11, 0
	v_mov_b32_e32 v12, 0
	v_mov_b32_e32 v13, 0
	v_mov_b32_e32 v14, 0
	v_mov_b32_e32 v15, 0
	s_cmp_eq_u32 s100, 0
	s_cbranch_scc1 .Lg8_p7_gb0
	s_barrier
.Lg8_p7_gb0:
	s_waitcnt vmcnt(4)
	s_barrier
	s_add_u32 s70, s70, 0x80
	s_addc_u32 s71, s71, 0
	s_add_u32 m0, s99, 0x18000
	s_nop 0
	global_load_lds_dwordx4 v205, s[70:71]
	s_add_u32 m0, s99, 0x1a000
	s_nop 0
	global_load_lds_dwordx4 v206, s[70:71]
	s_add_u32 s72, s72, 0x80
	s_addc_u32 s73, s73, 0
	s_add_u32 m0, s99, 0x10000
	s_nop 0
	global_load_lds_dwordx4 v201, s[72:73]
	s_add_u32 m0, s99, 0x12000
	s_nop 0
	global_load_lds_dwordx4 v202, s[72:73]
	s_add_u32 m0, s99, 0x1c000
	s_nop 0
	global_load_lds_dwordx4 v210, s[70:71]
	s_add_u32 m0, s99, 0x1e000
	s_nop 0
	global_load_lds_dwordx4 v211, s[70:71]
	s_waitcnt vmcnt(6)
	s_barrier
	s_mov_b32 s101, 3
.Lg8_p7_loop:
	ds_read_b128 v[160:163], v197 offset:0
	ds_read_b128 v[164:167], v199 offset:0
	ds_read_b128 v[172:175], v197 offset:2048
	ds_read_b128 v[176:179], v199 offset:2048
	ds_read_b128 v[128:131], v168 offset:0
	ds_read_b128 v[132:135], v171 offset:0
	ds_read_b128 v[136:139], v168 offset:2048
	ds_read_b128 v[140:143], v171 offset:2048
	ds_read_b128 v[144:147], v168 offset:4096
	ds_read_b128 v[148:151], v171 offset:4096
	ds_read_b128 v[152:155], v168 offset:6144
	ds_read_b128 v[156:159], v171 offset:6144
	s_add_u32 m0, s99, 0x14000
	s_nop 0
	global_load_lds_dwordx4 v203, s[72:73]
	s_add_u32 m0, s99, 0x16000
	s_nop 0
	global_load_lds_dwordx4 v204, s[72:73]
	s_waitcnt lgkmcnt(8)
	s_barrier
	s_waitcnt lgkmcnt(0)
	s_setprio 1
	v_mfma_f32_16x16x32_bf16 v[112:115], v[128:131], v[160:163], v[112:115]
	v_mfma_f32_16x16x32_bf16 v[112:115], v[132:135], v[164:167], v[112:115]
	v_mfma_f32_16x16x32_bf16 v[116:119], v[128:131], v[172:175], v[116:119]
	v_mfma_f32_16x16x32_bf16 v[116:119], v[132:135], v[176:179], v[116:119]
	v_mfma_f32_16x16x32_bf16 v[120:123], v[136:139], v[160:163], v[120:123]
	v_mfma_f32_16x16x32_bf16 v[120:123], v[140:143], v[164:167], v[120:123]
	v_mfma_f32_16x16x32_bf16 v[124:127], v[136:139], v[172:175], v[124:127]
	v_mfma_f32_16x16x32_bf16 v[124:127], v[140:143], v[176:179], v[124:127]
	v_mfma_f32_16x16x32_bf16 v[96:99], v[144:147], v[160:163], v[96:99]
	v_mfma_f32_16x16x32_bf16 v[96:99], v[148:151], v[164:167], v[96:99]
	v_mfma_f32_16x16x32_bf16 v[100:103], v[144:147], v[172:175], v[100:103]
	v_mfma_f32_16x16x32_bf16 v[100:103], v[148:151], v[176:179], v[100:103]
	v_mfma_f32_16x16x32_bf16 v[104:107], v[152:155], v[160:163], v[104:107]
	v_mfma_f32_16x16x32_bf16 v[104:107], v[156:159], v[164:167], v[104:107]
	v_mfma_f32_16x16x32_bf16 v[108:111], v[152:155], v[172:175], v[108:111]
	v_mfma_f32_16x16x32_bf16 v[108:111], v[156:159], v[176:179], v[108:111]
	s_setprio 0
	s_barrier
	ds_read_b128 v[180:183], v197 offset:16384
	ds_read_b128 v[184:187], v199 offset:16384
	ds_read_b128 v[188:191], v197 offset:18432
	ds_read_b128 v[192:195], v199 offset:18432
	s_add_u32 s70, s70, 0x80
	s_addc_u32 s71, s71, 0
	s_add_u32 m0, s99, 0x8000
	s_nop 0
	global_load_lds_dwordx4 v205, s[70:71]
	s_add_u32 m0, s99, 0xa000
	s_nop 0
	global_load_lds_dwordx4 v206, s[70:71]
	s_barrier
	s_waitcnt lgkmcnt(0)
	s_setprio 1
	v_mfma_f32_16x16x32_bf16 v[48:51], v[128:131], v[180:183], v[48:51]
	v_mfma_f32_16x16x32_bf16 v[48:51], v[132:135], v[184:187], v[48:51]
	v_mfma_f32_16x16x32_bf16 v[52:55], v[128:131], v[188:191], v[52:55]
	v_mfma_f32_16x16x32_bf16 v[52:55], v[132:135], v[192:195], v[52:55]
	v_mfma_f32_16x16x32_bf16 v[56:59], v[136:139], v[180:183], v[56:59]
	v_mfma_f32_16x16x32_bf16 v[56:59], v[140:143], v[184:187], v[56:59]
	v_mfma_f32_16x16x32_bf16 v[60:63], v[136:139], v[188:191], v[60:63]
	v_mfma_f32_16x16x32_bf16 v[60:63], v[140:143], v[192:195], v[60:63]
	v_mfma_f32_16x16x32_bf16 v[32:35], v[144:147], v[180:183], v[32:35]
	v_mfma_f32_16x16x32_bf16 v[32:35], v[148:151], v[184:187], v[32:35]
	v_mfma_f32_16x16x32_bf16 v[36:39], v[144:147], v[188:191], v[36:39]
	v_mfma_f32_16x16x32_bf16 v[36:39], v[148:151], v[192:195], v[36:39]
	v_mfma_f32_16x16x32_bf16 v[40:43], v[152:155], v[180:183], v[40:43]
	v_mfma_f32_16x16x32_bf16 v[40:43], v[156:159], v[184:187], v[40:43]
	v_mfma_f32_16x16x32_bf16 v[44:47], v[152:155], v[188:191], v[44:47]
	v_mfma_f32_16x16x32_bf16 v[44:47], v[156:159], v[192:195], v[44:47]
	s_setprio 0
	s_barrier
	ds_read_b128 v[128:131], v168 offset:16384
	ds_read_b128 v[132:135], v171 offset:16384
	ds_read_b128 v[136:139], v168 offset:18432
	ds_read_b128 v[140:143], v171 offset:18432
	ds_read_b128 v[144:147], v168 offset:20480
	ds_read_b128 v[148:151], v171 offset:20480
	ds_read_b128 v[152:155], v168 offset:22528
	ds_read_b128 v[156:159], v171 offset:22528
	s_add_u32 s72, s72, 0x80
	s_addc_u32 s73, s73, 0
	s_add_u32 m0, s99, 0x0
	s_nop 0
	global_load_lds_dwordx4 v201, s[72:73]
	s_add_u32 m0, s99, 0x2000
	s_nop 0
	global_load_lds_dwordx4 v202, s[72:73]
	s_barrier
	s_waitcnt lgkmcnt(0)
	s_setprio 1
	v_mfma_f32_16x16x32_bf16 v[80:83], v[128:131], v[160:163], v[80:83]
	v_mfma_f32_16x16x32_bf16 v[80:83], v[132:135], v[164:167], v[80:83]
	v_mfma_f32_16x16x32_bf16 v[84:87], v[128:131], v[172:175], v[84:87]
	v_mfma_f32_16x16x32_bf16 v[84:87], v[132:135], v[176:179], v[84:87]
	v_mfma_f32_16x16x32_bf16 v[88:91], v[136:139], v[160:163], v[88:91]
	v_mfma_f32_16x16x32_bf16 v[88:91], v[140:143], v[164:167], v[88:91]
	v_mfma_f32_16x16x32_bf16 v[92:95], v[136:139], v[172:175], v[92:95]
	v_mfma_f32_16x16x32_bf16 v[92:95], v[140:143], v[176:179], v[92:95]
	v_mfma_f32_16x16x32_bf16 v[64:67], v[144:147], v[160:163], v[64:67]
	v_mfma_f32_16x16x32_bf16 v[64:67], v[148:151], v[164:167], v[64:67]
	v_mfma_f32_16x16x32_bf16 v[68:71], v[144:147], v[172:175], v[68:71]
	v_mfma_f32_16x16x32_bf16 v[68:71], v[148:151], v[176:179], v[68:71]
	v_mfma_f32_16x16x32_bf16 v[72:75], v[152:155], v[160:163], v[72:75]
	v_mfma_f32_16x16x32_bf16 v[72:75], v[156:159], v[164:167], v[72:75]
	v_mfma_f32_16x16x32_bf16 v[76:79], v[152:155], v[172:175], v[76:79]
	v_mfma_f32_16x16x32_bf16 v[76:79], v[156:159], v[176:179], v[76:79]
	s_setprio 0
	s_barrier
	s_add_u32 m0, s99, 0xc000
	s_nop 0
	global_load_lds_dwordx4 v210, s[70:71]
	s_add_u32 m0, s99, 0xe000
	s_nop 0
	global_load_lds_dwordx4 v211, s[70:71]
	s_waitcnt vmcnt(6)
	s_barrier
	s_setprio 1
	v_mfma_f32_16x16x32_bf16 v[16:19], v[128:131], v[180:183], v[16:19]
	v_mfma_f32_16x16x32_bf16 v[16:19], v[132:135], v[184:187], v[16:19]
	v_mfma_f32_16x16x32_bf16 v[20:23], v[128:131], v[188:191], v[20:23]
	v_mfma_f32_16x16x32_bf16 v[20:23], v[132:135], v[192:195], v[20:23]
	v_mfma_f32_16x16x32_bf16 v[24:27], v[136:139], v[180:183], v[24:27]
	v_mfma_f32_16x16x32_bf16 v[24:27], v[140:143], v[184:187], v[24:27]
	v_mfma_f32_16x16x32_bf16 v[28:31], v[136:139], v[188:191], v[28:31]
	v_mfma_f32_16x16x32_bf16 v[28:31], v[140:143], v[192:195], v[28:31]
	v_mfma_f32_16x16x32_bf16 v[0:3], v[144:147], v[180:183], v[0:3]
	v_mfma_f32_16x16x32_bf16 v[0:3], v[148:151], v[184:187], v[0:3]
	v_mfma_f32_16x16x32_bf16 v[4:7], v[144:147], v[188:191], v[4:7]
	v_mfma_f32_16x16x32_bf16 v[4:7], v[148:151], v[192:195], v[4:7]
	v_mfma_f32_16x16x32_bf16 v[8:11], v[152:155], v[180:183], v[8:11]
	v_mfma_f32_16x16x32_bf16 v[8:11], v[156:159], v[184:187], v[8:11]
	v_mfma_f32_16x16x32_bf16 v[12:15], v[152:155], v[188:191], v[12:15]
	v_mfma_f32_16x16x32_bf16 v[12:15], v[156:159], v[192:195], v[12:15]
	s_setprio 0
	s_barrier
	ds_read_b128 v[160:163], v198 offset:0
	ds_read_b128 v[164:167], v200 offset:0
	ds_read_b128 v[172:175], v198 offset:2048
	ds_read_b128 v[176:179], v200 offset:2048
	ds_read_b128 v[128:131], v170 offset:0
	ds_read_b128 v[132:135], v196 offset:0
	ds_read_b128 v[136:139], v170 offset:2048
	ds_read_b128 v[140:143], v196 offset:2048
	ds_read_b128 v[144:147], v170 offset:4096
	ds_read_b128 v[148:151], v196 offset:4096
	ds_read_b128 v[152:155], v170 offset:6144
	ds_read_b128 v[156:159], v196 offset:6144
	s_add_u32 m0, s99, 0x4000
	s_nop 0
	global_load_lds_dwordx4 v203, s[72:73]
	s_add_u32 m0, s99, 0x6000
	s_nop 0
	global_load_lds_dwordx4 v204, s[72:73]
	s_waitcnt lgkmcnt(8)
	s_barrier
	s_waitcnt lgkmcnt(0)
	s_setprio 1
	v_mfma_f32_16x16x32_bf16 v[112:115], v[128:131], v[160:163], v[112:115]
	v_mfma_f32_16x16x32_bf16 v[112:115], v[132:135], v[164:167], v[112:115]
	v_mfma_f32_16x16x32_bf16 v[116:119], v[128:131], v[172:175], v[116:119]
	v_mfma_f32_16x16x32_bf16 v[116:119], v[132:135], v[176:179], v[116:119]
	v_mfma_f32_16x16x32_bf16 v[120:123], v[136:139], v[160:163], v[120:123]
	v_mfma_f32_16x16x32_bf16 v[120:123], v[140:143], v[164:167], v[120:123]
	v_mfma_f32_16x16x32_bf16 v[124:127], v[136:139], v[172:175], v[124:127]
	v_mfma_f32_16x16x32_bf16 v[124:127], v[140:143], v[176:179], v[124:127]
	v_mfma_f32_16x16x32_bf16 v[96:99], v[144:147], v[160:163], v[96:99]
	v_mfma_f32_16x16x32_bf16 v[96:99], v[148:151], v[164:167], v[96:99]
	v_mfma_f32_16x16x32_bf16 v[100:103], v[144:147], v[172:175], v[100:103]
	v_mfma_f32_16x16x32_bf16 v[100:103], v[148:151], v[176:179], v[100:103]
	v_mfma_f32_16x16x32_bf16 v[104:107], v[152:155], v[160:163], v[104:107]
	v_mfma_f32_16x16x32_bf16 v[104:107], v[156:159], v[164:167], v[104:107]
	v_mfma_f32_16x16x32_bf16 v[108:111], v[152:155], v[172:175], v[108:111]
	v_mfma_f32_16x16x32_bf16 v[108:111], v[156:159], v[176:179], v[108:111]
	s_setprio 0
	s_barrier
	ds_read_b128 v[180:183], v198 offset:16384
	ds_read_b128 v[184:187], v200 offset:16384
	ds_read_b128 v[188:191], v198 offset:18432
	ds_read_b128 v[192:195], v200 offset:18432
	s_add_u32 s70, s70, 0x80
	s_addc_u32 s71, s71, 0
	s_add_u32 m0, s99, 0x18000
	s_nop 0
	global_load_lds_dwordx4 v205, s[70:71]
	s_add_u32 m0, s99, 0x1a000
	s_nop 0
	global_load_lds_dwordx4 v206, s[70:71]
	s_barrier
	s_waitcnt lgkmcnt(0)
	s_setprio 1
	v_mfma_f32_16x16x32_bf16 v[48:51], v[128:131], v[180:183], v[48:51]
	v_mfma_f32_16x16x32_bf16 v[48:51], v[132:135], v[184:187], v[48:51]
	v_mfma_f32_16x16x32_bf16 v[52:55], v[128:131], v[188:191], v[52:55]
	v_mfma_f32_16x16x32_bf16 v[52:55], v[132:135], v[192:195], v[52:55]
	v_mfma_f32_16x16x32_bf16 v[56:59], v[136:139], v[180:183], v[56:59]
	v_mfma_f32_16x16x32_bf16 v[56:59], v[140:143], v[184:187], v[56:59]
	v_mfma_f32_16x16x32_bf16 v[60:63], v[136:139], v[188:191], v[60:63]
	v_mfma_f32_16x16x32_bf16 v[60:63], v[140:143], v[192:195], v[60:63]
	v_mfma_f32_16x16x32_bf16 v[32:35], v[144:147], v[180:183], v[32:35]
	v_mfma_f32_16x16x32_bf16 v[32:35], v[148:151], v[184:187], v[32:35]
	v_mfma_f32_16x16x32_bf16 v[36:39], v[144:147], v[188:191], v[36:39]
	v_mfma_f32_16x16x32_bf16 v[36:39], v[148:151], v[192:195], v[36:39]
	v_mfma_f32_16x16x32_bf16 v[40:43], v[152:155], v[180:183], v[40:43]
	v_mfma_f32_16x16x32_bf16 v[40:43], v[156:159], v[184:187], v[40:43]
	v_mfma_f32_16x16x32_bf16 v[44:47], v[152:155], v[188:191], v[44:47]
	v_mfma_f32_16x16x32_bf16 v[44:47], v[156:159], v[192:195], v[44:47]
	s_setprio 0
	s_barrier
	ds_read_b128 v[128:131], v170 offset:16384
	ds_read_b128 v[132:135], v196 offset:16384
	ds_read_b128 v[136:139], v170 offset:18432
	ds_read_b128 v[140:143], v196 offset:18432
	ds_read_b128 v[144:147], v170 offset:20480
	ds_read_b128 v[148:151], v196 offset:20480
	ds_read_b128 v[152:155], v170 offset:22528
	ds_read_b128 v[156:159], v196 offset:22528
	s_add_u32 s72, s72, 0x80
	s_addc_u32 s73, s73, 0
	s_add_u32 m0, s99, 0x10000
	s_nop 0
	global_load_lds_dwordx4 v201, s[72:73]
	s_add_u32 m0, s99, 0x12000
	s_nop 0
	global_load_lds_dwordx4 v202, s[72:73]
	s_barrier
	s_waitcnt lgkmcnt(0)
	s_setprio 1
	v_mfma_f32_16x16x32_bf16 v[80:83], v[128:131], v[160:163], v[80:83]
	v_mfma_f32_16x16x32_bf16 v[80:83], v[132:135], v[164:167], v[80:83]
	v_mfma_f32_16x16x32_bf16 v[84:87], v[128:131], v[172:175], v[84:87]
	v_mfma_f32_16x16x32_bf16 v[84:87], v[132:135], v[176:179], v[84:87]
	v_mfma_f32_16x16x32_bf16 v[88:91], v[136:139], v[160:163], v[88:91]
	v_mfma_f32_16x16x32_bf16 v[88:91], v[140:143], v[164:167], v[88:91]
	v_mfma_f32_16x16x32_bf16 v[92:95], v[136:139], v[172:175], v[92:95]
	v_mfma_f32_16x16x32_bf16 v[92:95], v[140:143], v[176:179], v[92:95]
	v_mfma_f32_16x16x32_bf16 v[64:67], v[144:147], v[160:163], v[64:67]
	v_mfma_f32_16x16x32_bf16 v[64:67], v[148:151], v[164:167], v[64:67]
	v_mfma_f32_16x16x32_bf16 v[68:71], v[144:147], v[172:175], v[68:71]
	v_mfma_f32_16x16x32_bf16 v[68:71], v[148:151], v[176:179], v[68:71]
	v_mfma_f32_16x16x32_bf16 v[72:75], v[152:155], v[160:163], v[72:75]
	v_mfma_f32_16x16x32_bf16 v[72:75], v[156:159], v[164:167], v[72:75]
	v_mfma_f32_16x16x32_bf16 v[76:79], v[152:155], v[172:175], v[76:79]
	v_mfma_f32_16x16x32_bf16 v[76:79], v[156:159], v[176:179], v[76:79]
	s_setprio 0
	s_barrier
	s_add_u32 m0, s99, 0x1c000
	s_nop 0
	global_load_lds_dwordx4 v210, s[70:71]
	s_add_u32 m0, s99, 0x1e000
	s_nop 0
	global_load_lds_dwordx4 v211, s[70:71]
	s_waitcnt vmcnt(6)
	s_barrier
	s_setprio 1
	v_mfma_f32_16x16x32_bf16 v[16:19], v[128:131], v[180:183], v[16:19]
	v_mfma_f32_16x16x32_bf16 v[16:19], v[132:135], v[184:187], v[16:19]
	v_mfma_f32_16x16x32_bf16 v[20:23], v[128:131], v[188:191], v[20:23]
	v_mfma_f32_16x16x32_bf16 v[20:23], v[132:135], v[192:195], v[20:23]
	v_mfma_f32_16x16x32_bf16 v[24:27], v[136:139], v[180:183], v[24:27]
	v_mfma_f32_16x16x32_bf16 v[24:27], v[140:143], v[184:187], v[24:27]
	v_mfma_f32_16x16x32_bf16 v[28:31], v[136:139], v[188:191], v[28:31]
	v_mfma_f32_16x16x32_bf16 v[28:31], v[140:143], v[192:195], v[28:31]
	v_mfma_f32_16x16x32_bf16 v[0:3], v[144:147], v[180:183], v[0:3]
	v_mfma_f32_16x16x32_bf16 v[0:3], v[148:151], v[184:187], v[0:3]
	v_mfma_f32_16x16x32_bf16 v[4:7], v[144:147], v[188:191], v[4:7]
	v_mfma_f32_16x16x32_bf16 v[4:7], v[148:151], v[192:195], v[4:7]
	v_mfma_f32_16x16x32_bf16 v[8:11], v[152:155], v[180:183], v[8:11]
	v_mfma_f32_16x16x32_bf16 v[8:11], v[156:159], v[184:187], v[8:11]
	v_mfma_f32_16x16x32_bf16 v[12:15], v[152:155], v[188:191], v[12:15]
	v_mfma_f32_16x16x32_bf16 v[12:15], v[156:159], v[192:195], v[12:15]
	s_setprio 0
	s_barrier
	s_sub_u32 s101, s101, 1
	s_cmp_lg_u32 s101, 0
	s_cbranch_scc1 .Lg8_p7_loop
	ds_read_b128 v[160:163], v197 offset:0
	ds_read_b128 v[164:167], v199 offset:0
	ds_read_b128 v[172:175], v197 offset:2048
	ds_read_b128 v[176:179], v199 offset:2048
	ds_read_b128 v[128:131], v168 offset:0
	ds_read_b128 v[132:135], v171 offset:0
	ds_read_b128 v[136:139], v168 offset:2048
	ds_read_b128 v[140:143], v171 offset:2048
	ds_read_b128 v[144:147], v168 offset:4096
	ds_read_b128 v[148:151], v171 offset:4096
	ds_read_b128 v[152:155], v168 offset:6144
	ds_read_b128 v[156:159], v171 offset:6144
	s_add_u32 m0, s99, 0x14000
	s_nop 0
	global_load_lds_dwordx4 v203, s[72:73]
	s_add_u32 m0, s99, 0x16000
	s_nop 0
	global_load_lds_dwordx4 v204, s[72:73]
	s_barrier
	s_waitcnt lgkmcnt(0)
	s_setprio 1
	v_mfma_f32_16x16x32_bf16 v[112:115], v[128:131], v[160:163], v[112:115]
	v_mfma_f32_16x16x32_bf16 v[112:115], v[132:135], v[164:167], v[112:115]
	v_mfma_f32_16x16x32_bf16 v[116:119], v[128:131], v[172:175], v[116:119]
	v_mfma_f32_16x16x32_bf16 v[116:119], v[132:135], v[176:179], v[116:119]
	v_mfma_f32_16x16x32_bf16 v[120:123], v[136:139], v[160:163], v[120:123]
	v_mfma_f32_16x16x32_bf16 v[120:123], v[140:143], v[164:167], v[120:123]
	v_mfma_f32_16x16x32_bf16 v[124:127], v[136:139], v[172:175], v[124:127]
	v_mfma_f32_16x16x32_bf16 v[124:127], v[140:143], v[176:179], v[124:127]
	v_mfma_f32_16x16x32_bf16 v[96:99], v[144:147], v[160:163], v[96:99]
	v_mfma_f32_16x16x32_bf16 v[96:99], v[148:151], v[164:167], v[96:99]
	v_mfma_f32_16x16x32_bf16 v[100:103], v[144:147], v[172:175], v[100:103]
	v_mfma_f32_16x16x32_bf16 v[100:103], v[148:151], v[176:179], v[100:103]
	v_mfma_f32_16x16x32_bf16 v[104:107], v[152:155], v[160:163], v[104:107]
	v_mfma_f32_16x16x32_bf16 v[104:107], v[156:159], v[164:167], v[104:107]
	v_mfma_f32_16x16x32_bf16 v[108:111], v[152:155], v[172:175], v[108:111]
	v_mfma_f32_16x16x32_bf16 v[108:111], v[156:159], v[176:179], v[108:111]
	s_setprio 0
	s_barrier
	ds_read_b128 v[180:183], v197 offset:16384
	ds_read_b128 v[184:187], v199 offset:16384
	ds_read_b128 v[188:191], v197 offset:18432
	ds_read_b128 v[192:195], v199 offset:18432
	s_barrier
	s_waitcnt lgkmcnt(0)
	s_setprio 1
	v_mfma_f32_16x16x32_bf16 v[48:51], v[128:131], v[180:183], v[48:51]
	v_mfma_f32_16x16x32_bf16 v[48:51], v[132:135], v[184:187], v[48:51]
	v_mfma_f32_16x16x32_bf16 v[52:55], v[128:131], v[188:191], v[52:55]
	v_mfma_f32_16x16x32_bf16 v[52:55], v[132:135], v[192:195], v[52:55]
	v_mfma_f32_16x16x32_bf16 v[56:59], v[136:139], v[180:183], v[56:59]
	v_mfma_f32_16x16x32_bf16 v[56:59], v[140:143], v[184:187], v[56:59]
	v_mfma_f32_16x16x32_bf16 v[60:63], v[136:139], v[188:191], v[60:63]
	v_mfma_f32_16x16x32_bf16 v[60:63], v[140:143], v[192:195], v[60:63]
	v_mfma_f32_16x16x32_bf16 v[32:35], v[144:147], v[180:183], v[32:35]
	v_mfma_f32_16x16x32_bf16 v[32:35], v[148:151], v[184:187], v[32:35]
	v_mfma_f32_16x16x32_bf16 v[36:39], v[144:147], v[188:191], v[36:39]
	v_mfma_f32_16x16x32_bf16 v[36:39], v[148:151], v[192:195], v[36:39]
	v_mfma_f32_16x16x32_bf16 v[40:43], v[152:155], v[180:183], v[40:43]
	v_mfma_f32_16x16x32_bf16 v[40:43], v[156:159], v[184:187], v[40:43]
	v_mfma_f32_16x16x32_bf16 v[44:47], v[152:155], v[188:191], v[44:47]
	v_mfma_f32_16x16x32_bf16 v[44:47], v[156:159], v[192:195], v[44:47]
	s_setprio 0
	s_barrier
	ds_read_b128 v[128:131], v168 offset:16384
	ds_read_b128 v[132:135], v171 offset:16384
	ds_read_b128 v[136:139], v168 offset:18432
	ds_read_b128 v[140:143], v171 offset:18432
	ds_read_b128 v[144:147], v168 offset:20480
	ds_read_b128 v[148:151], v171 offset:20480
	ds_read_b128 v[152:155], v168 offset:22528
	ds_read_b128 v[156:159], v171 offset:22528
	s_waitcnt vmcnt(4)
	s_barrier
	s_waitcnt lgkmcnt(0)
	s_setprio 1
	v_mfma_f32_16x16x32_bf16 v[80:83], v[128:131], v[160:163], v[80:83]
	v_mfma_f32_16x16x32_bf16 v[80:83], v[132:135], v[164:167], v[80:83]
	v_mfma_f32_16x16x32_bf16 v[84:87], v[128:131], v[172:175], v[84:87]
	v_mfma_f32_16x16x32_bf16 v[84:87], v[132:135], v[176:179], v[84:87]
	v_mfma_f32_16x16x32_bf16 v[88:91], v[136:139], v[160:163], v[88:91]
	v_mfma_f32_16x16x32_bf16 v[88:91], v[140:143], v[164:167], v[88:91]
	v_mfma_f32_16x16x32_bf16 v[92:95], v[136:139], v[172:175], v[92:95]
	v_mfma_f32_16x16x32_bf16 v[92:95], v[140:143], v[176:179], v[92:95]
	v_mfma_f32_16x16x32_bf16 v[64:67], v[144:147], v[160:163], v[64:67]
	v_mfma_f32_16x16x32_bf16 v[64:67], v[148:151], v[164:167], v[64:67]
	v_mfma_f32_16x16x32_bf16 v[68:71], v[144:147], v[172:175], v[68:71]
	v_mfma_f32_16x16x32_bf16 v[68:71], v[148:151], v[176:179], v[68:71]
	v_mfma_f32_16x16x32_bf16 v[72:75], v[152:155], v[160:163], v[72:75]
	v_mfma_f32_16x16x32_bf16 v[72:75], v[156:159], v[164:167], v[72:75]
	v_mfma_f32_16x16x32_bf16 v[76:79], v[152:155], v[172:175], v[76:79]
	v_mfma_f32_16x16x32_bf16 v[76:79], v[156:159], v[176:179], v[76:79]
	s_setprio 0
	s_setprio 1
	v_mfma_f32_16x16x32_bf16 v[16:19], v[128:131], v[180:183], v[16:19]
	v_mfma_f32_16x16x32_bf16 v[16:19], v[132:135], v[184:187], v[16:19]
	v_mfma_f32_16x16x32_bf16 v[20:23], v[128:131], v[188:191], v[20:23]
	v_mfma_f32_16x16x32_bf16 v[20:23], v[132:135], v[192:195], v[20:23]
	v_mfma_f32_16x16x32_bf16 v[24:27], v[136:139], v[180:183], v[24:27]
	v_mfma_f32_16x16x32_bf16 v[24:27], v[140:143], v[184:187], v[24:27]
	v_mfma_f32_16x16x32_bf16 v[28:31], v[136:139], v[188:191], v[28:31]
	v_mfma_f32_16x16x32_bf16 v[28:31], v[140:143], v[192:195], v[28:31]
	v_mfma_f32_16x16x32_bf16 v[0:3], v[144:147], v[180:183], v[0:3]
	v_mfma_f32_16x16x32_bf16 v[0:3], v[148:151], v[184:187], v[0:3]
	v_mfma_f32_16x16x32_bf16 v[4:7], v[144:147], v[188:191], v[4:7]
	v_mfma_f32_16x16x32_bf16 v[4:7], v[148:151], v[192:195], v[4:7]
	v_mfma_f32_16x16x32_bf16 v[8:11], v[152:155], v[180:183], v[8:11]
	v_mfma_f32_16x16x32_bf16 v[8:11], v[156:159], v[184:187], v[8:11]
	v_mfma_f32_16x16x32_bf16 v[12:15], v[152:155], v[188:191], v[12:15]
	v_mfma_f32_16x16x32_bf16 v[12:15], v[156:159], v[192:195], v[12:15]
	s_setprio 0
	s_barrier
	ds_read_b128 v[160:163], v198 offset:0
	ds_read_b128 v[164:167], v200 offset:0
	ds_read_b128 v[172:175], v198 offset:2048
	ds_read_b128 v[176:179], v200 offset:2048
	ds_read_b128 v[128:131], v170 offset:0
	ds_read_b128 v[132:135], v196 offset:0
	ds_read_b128 v[136:139], v170 offset:2048
	ds_read_b128 v[140:143], v196 offset:2048
	ds_read_b128 v[144:147], v170 offset:4096
	ds_read_b128 v[148:151], v196 offset:4096
	ds_read_b128 v[152:155], v170 offset:6144
	ds_read_b128 v[156:159], v196 offset:6144
	s_waitcnt vmcnt(2)
	s_barrier
	s_waitcnt lgkmcnt(0)
	s_setprio 1
	v_mfma_f32_16x16x32_bf16 v[112:115], v[128:131], v[160:163], v[112:115]
	v_mfma_f32_16x16x32_bf16 v[112:115], v[132:135], v[164:167], v[112:115]
	v_mfma_f32_16x16x32_bf16 v[116:119], v[128:131], v[172:175], v[116:119]
	v_mfma_f32_16x16x32_bf16 v[116:119], v[132:135], v[176:179], v[116:119]
	v_mfma_f32_16x16x32_bf16 v[120:123], v[136:139], v[160:163], v[120:123]
	v_mfma_f32_16x16x32_bf16 v[120:123], v[140:143], v[164:167], v[120:123]
	v_mfma_f32_16x16x32_bf16 v[124:127], v[136:139], v[172:175], v[124:127]
	v_mfma_f32_16x16x32_bf16 v[124:127], v[140:143], v[176:179], v[124:127]
	v_mfma_f32_16x16x32_bf16 v[96:99], v[144:147], v[160:163], v[96:99]
	v_mfma_f32_16x16x32_bf16 v[96:99], v[148:151], v[164:167], v[96:99]
	v_mfma_f32_16x16x32_bf16 v[100:103], v[144:147], v[172:175], v[100:103]
	v_mfma_f32_16x16x32_bf16 v[100:103], v[148:151], v[176:179], v[100:103]
	v_mfma_f32_16x16x32_bf16 v[104:107], v[152:155], v[160:163], v[104:107]
	v_mfma_f32_16x16x32_bf16 v[104:107], v[156:159], v[164:167], v[104:107]
	v_mfma_f32_16x16x32_bf16 v[108:111], v[152:155], v[172:175], v[108:111]
	v_mfma_f32_16x16x32_bf16 v[108:111], v[156:159], v[176:179], v[108:111]
	s_setprio 0
	s_barrier
	ds_read_b128 v[180:183], v198 offset:16384
	ds_read_b128 v[184:187], v200 offset:16384
	ds_read_b128 v[188:191], v198 offset:18432
	ds_read_b128 v[192:195], v200 offset:18432
	s_waitcnt vmcnt(0)
	s_barrier
	s_waitcnt lgkmcnt(0)
	s_setprio 1
	v_mfma_f32_16x16x32_bf16 v[48:51], v[128:131], v[180:183], v[48:51]
	v_mfma_f32_16x16x32_bf16 v[48:51], v[132:135], v[184:187], v[48:51]
	v_mfma_f32_16x16x32_bf16 v[52:55], v[128:131], v[188:191], v[52:55]
	v_mfma_f32_16x16x32_bf16 v[52:55], v[132:135], v[192:195], v[52:55]
	v_mfma_f32_16x16x32_bf16 v[56:59], v[136:139], v[180:183], v[56:59]
	v_mfma_f32_16x16x32_bf16 v[56:59], v[140:143], v[184:187], v[56:59]
	v_mfma_f32_16x16x32_bf16 v[60:63], v[136:139], v[188:191], v[60:63]
	v_mfma_f32_16x16x32_bf16 v[60:63], v[140:143], v[192:195], v[60:63]
	v_mfma_f32_16x16x32_bf16 v[32:35], v[144:147], v[180:183], v[32:35]
	v_mfma_f32_16x16x32_bf16 v[32:35], v[148:151], v[184:187], v[32:35]
	v_mfma_f32_16x16x32_bf16 v[36:39], v[144:147], v[188:191], v[36:39]
	v_mfma_f32_16x16x32_bf16 v[36:39], v[148:151], v[192:195], v[36:39]
	v_mfma_f32_16x16x32_bf16 v[40:43], v[152:155], v[180:183], v[40:43]
	v_mfma_f32_16x16x32_bf16 v[40:43], v[156:159], v[184:187], v[40:43]
	v_mfma_f32_16x16x32_bf16 v[44:47], v[152:155], v[188:191], v[44:47]
	v_mfma_f32_16x16x32_bf16 v[44:47], v[156:159], v[192:195], v[44:47]
	s_setprio 0
	s_barrier
	ds_read_b128 v[128:131], v170 offset:16384
	ds_read_b128 v[132:135], v196 offset:16384
	ds_read_b128 v[136:139], v170 offset:18432
	ds_read_b128 v[140:143], v196 offset:18432
	ds_read_b128 v[144:147], v170 offset:20480
	ds_read_b128 v[148:151], v196 offset:20480
	ds_read_b128 v[152:155], v170 offset:22528
	ds_read_b128 v[156:159], v196 offset:22528
	s_barrier
	s_waitcnt lgkmcnt(0)
	s_setprio 1
	v_mfma_f32_16x16x32_bf16 v[80:83], v[128:131], v[160:163], v[80:83]
	v_mfma_f32_16x16x32_bf16 v[80:83], v[132:135], v[164:167], v[80:83]
	v_mfma_f32_16x16x32_bf16 v[84:87], v[128:131], v[172:175], v[84:87]
	v_mfma_f32_16x16x32_bf16 v[84:87], v[132:135], v[176:179], v[84:87]
	v_mfma_f32_16x16x32_bf16 v[88:91], v[136:139], v[160:163], v[88:91]
	v_mfma_f32_16x16x32_bf16 v[88:91], v[140:143], v[164:167], v[88:91]
	v_mfma_f32_16x16x32_bf16 v[92:95], v[136:139], v[172:175], v[92:95]
	v_mfma_f32_16x16x32_bf16 v[92:95], v[140:143], v[176:179], v[92:95]
	v_mfma_f32_16x16x32_bf16 v[64:67], v[144:147], v[160:163], v[64:67]
	v_mfma_f32_16x16x32_bf16 v[64:67], v[148:151], v[164:167], v[64:67]
	v_mfma_f32_16x16x32_bf16 v[68:71], v[144:147], v[172:175], v[68:71]
	v_mfma_f32_16x16x32_bf16 v[68:71], v[148:151], v[176:179], v[68:71]
	v_mfma_f32_16x16x32_bf16 v[72:75], v[152:155], v[160:163], v[72:75]
	v_mfma_f32_16x16x32_bf16 v[72:75], v[156:159], v[164:167], v[72:75]
	v_mfma_f32_16x16x32_bf16 v[76:79], v[152:155], v[172:175], v[76:79]
	v_mfma_f32_16x16x32_bf16 v[76:79], v[156:159], v[176:179], v[76:79]
	s_setprio 0
	s_setprio 1
	v_mfma_f32_16x16x32_bf16 v[16:19], v[128:131], v[180:183], v[16:19]
	v_mfma_f32_16x16x32_bf16 v[16:19], v[132:135], v[184:187], v[16:19]
	v_mfma_f32_16x16x32_bf16 v[20:23], v[128:131], v[188:191], v[20:23]
	v_mfma_f32_16x16x32_bf16 v[20:23], v[132:135], v[192:195], v[20:23]
	v_mfma_f32_16x16x32_bf16 v[24:27], v[136:139], v[180:183], v[24:27]
	v_mfma_f32_16x16x32_bf16 v[24:27], v[140:143], v[184:187], v[24:27]
	v_mfma_f32_16x16x32_bf16 v[28:31], v[136:139], v[188:191], v[28:31]
	v_mfma_f32_16x16x32_bf16 v[28:31], v[140:143], v[192:195], v[28:31]
	v_mfma_f32_16x16x32_bf16 v[0:3], v[144:147], v[180:183], v[0:3]
	v_mfma_f32_16x16x32_bf16 v[0:3], v[148:151], v[184:187], v[0:3]
	v_mfma_f32_16x16x32_bf16 v[4:7], v[144:147], v[188:191], v[4:7]
	v_mfma_f32_16x16x32_bf16 v[4:7], v[148:151], v[192:195], v[4:7]
	v_mfma_f32_16x16x32_bf16 v[8:11], v[152:155], v[180:183], v[8:11]
	v_mfma_f32_16x16x32_bf16 v[8:11], v[156:159], v[184:187], v[8:11]
	v_mfma_f32_16x16x32_bf16 v[12:15], v[152:155], v[188:191], v[12:15]
	v_mfma_f32_16x16x32_bf16 v[12:15], v[156:159], v[192:195], v[12:15]
	s_setprio 0
	s_barrier
	s_cmp_lg_u32 s100, 0
	s_cbranch_scc1 .Lg8_p7_gb1
	s_barrier

.LBB0_1393:
	s_ashr_i32 s20, s56, 2
	s_ashr_i32 s21, s20, 31
	s_and_b32 s39, s56, 3
	v_lshrrev_b32_e32 v212, 6, v208
	v_and_b32_e32 v213, 63, v208
	v_readfirstlane_b32 s98, v212
	v_and_b32_e32 v214, 3, v213
	v_bfe_u32 v215, v213, 2, 1
	v_lshl_or_b32 v214, v215, 3, v214
	v_bfe_u32 v215, v213, 3, 1
	v_lshl_or_b32 v214, v215, 2, v214
	s_and_b32 s2, s98, 1
	s_lshr_b32 s100, s98, 2
	s_lshl_b32 s99, s98, 10
	v_lshrrev_b32_e32 v215, 4, v213
	v_bfe_u32 v216, v214, 1, 3
	v_xor_b32_e32 v216, v215, v216
	v_lshlrev_b32_e32 v216, 4, v216
	v_lshl_add_u32 v214, s2, 6, v214
	v_lshl_add_u32 v184, v214, 7, v216
	v_xor_b32_e32 v187, 64, v184
	v_add_u32_e32 v186, 0x10000, v184
	v_add_u32_e32 v196, 0x10000, v187
	v_bfe_u32 v216, v213, 1, 3
	v_xor_b32_e32 v216, v215, v216
	v_lshlrev_b32_e32 v216, 4, v216
	v_and_b32_e32 v214, 15, v213
	s_lshr_b32 s101, s98, 1
	v_lshl_add_u32 v214, s101, 5, v214
	v_lshl_add_u32 v197, v214, 7, v216
	v_add_u32_e32 v197, 0x8000, v197
	v_xor_b32_e32 v199, 64, v197
	v_add_u32_e32 v198, 0x10000, v197
	v_add_u32_e32 v200, 0x10000, v199
	v_lshl_add_u32 v216, s2, 2, v215
	v_and_b32_e32 v214, 7, v213
	v_xor_b32_e32 v216, v214, v216
	v_lshlrev_b32_e32 v216, 4, v216
	v_lshrrev_b32_e32 v214, 3, v213
	v_lshl_add_u32 v215, s98, 3, v214
	v_lshl_add_u32 v201, v215, 12, v216
	v_add_u32_e32 v202, 0x80000, v201
	v_add_u32_e32 v203, 0x40000, v201
	v_add_u32_e32 v204, 0xc0000, v201
	s_and_b32 s101, s98, 3
	s_lshl_b32 s101, s101, 3
	s_lshl_b32 s2, s100, 6
	s_add_u32 s101, s101, s2
	v_add_u32_e32 v215, s101, v214
	v_lshl_add_u32 v205, v215, 12, v216
	v_add_u32_e32 v206, 0x80000, v205
	v_add_u32_e32 v210, 0x20000, v205
	v_add_u32_e32 v211, 0xa0000, v205
	s_lshl_b64 s[40:41], s[20:21], 20
	s_add_u32 s40, s61, s40
	s_addc_u32 s41, s62, s41
	s_lshl_b32 s2, s39, 20
	s_add_u32 s42, s1, s2
	s_addc_u32 s43, s26, 0
	s_add_u32 m0, s99, 0x8000
	s_nop 0
	global_load_lds_dwordx4 v205, s[40:41]
	s_add_u32 m0, s99, 0xa000
	s_nop 0
	global_load_lds_dwordx4 v206, s[40:41]
	s_add_u32 m0, s99, 0x0
	s_nop 0
	global_load_lds_dwordx4 v201, s[42:43]
	s_add_u32 m0, s99, 0x2000
	s_nop 0
	global_load_lds_dwordx4 v202, s[42:43]
	s_add_u32 m0, s99, 0xc000
	s_nop 0
	global_load_lds_dwordx4 v210, s[40:41]
	s_add_u32 m0, s99, 0xe000
	s_nop 0
	global_load_lds_dwordx4 v211, s[40:41]
	s_add_u32 m0, s99, 0x4000
	s_nop 0
	global_load_lds_dwordx4 v203, s[42:43]
	s_add_u32 m0, s99, 0x6000
	s_nop 0
	global_load_lds_dwordx4 v204, s[42:43]
	v_mov_b32_e32 v112, 0
	v_mov_b32_e32 v113, 0
	v_mov_b32_e32 v114, 0
	v_mov_b32_e32 v115, 0
	v_mov_b32_e32 v116, 0
	v_mov_b32_e32 v117, 0
	v_mov_b32_e32 v118, 0
	v_mov_b32_e32 v119, 0
	v_mov_b32_e32 v120, 0
	v_mov_b32_e32 v121, 0
	v_mov_b32_e32 v122, 0
	v_mov_b32_e32 v123, 0
	v_mov_b32_e32 v124, 0
	v_mov_b32_e32 v125, 0
	v_mov_b32_e32 v126, 0
	v_mov_b32_e32 v127, 0
	v_mov_b32_e32 v96, 0
	v_mov_b32_e32 v97, 0
	v_mov_b32_e32 v98, 0
	v_mov_b32_e32 v99, 0
	v_mov_b32_e32 v100, 0
	v_mov_b32_e32 v101, 0
	v_mov_b32_e32 v102, 0
	v_mov_b32_e32 v103, 0
	v_mov_b32_e32 v104, 0
	v_mov_b32_e32 v105, 0
	v_mov_b32_e32 v106, 0
	v_mov_b32_e32 v107, 0
	v_mov_b32_e32 v108, 0
	v_mov_b32_e32 v109, 0
	v_mov_b32_e32 v110, 0
	v_mov_b32_e32 v111, 0
	v_mov_b32_e32 v64, 0
	v_mov_b32_e32 v65, 0
	v_mov_b32_e32 v66, 0
	v_mov_b32_e32 v67, 0
	v_mov_b32_e32 v68, 0
	v_mov_b32_e32 v69, 0
	v_mov_b32_e32 v70, 0
	v_mov_b32_e32 v71, 0
	v_mov_b32_e32 v72, 0
	v_mov_b32_e32 v73, 0
	v_mov_b32_e32 v74, 0
	v_mov_b32_e32 v75, 0
	v_mov_b32_e32 v76, 0
	v_mov_b32_e32 v77, 0
	v_mov_b32_e32 v78, 0
	v_mov_b32_e32 v79, 0
	v_mov_b32_e32 v80, 0
	v_mov_b32_e32 v81, 0
	v_mov_b32_e32 v82, 0
	v_mov_b32_e32 v83, 0
	v_mov_b32_e32 v84, 0
	v_mov_b32_e32 v85, 0
	v_mov_b32_e32 v86, 0
	v_mov_b32_e32 v87, 0
	v_mov_b32_e32 v88, 0
	v_mov_b32_e32 v89, 0
	v_mov_b32_e32 v90, 0
	v_mov_b32_e32 v91, 0
	v_mov_b32_e32 v92, 0
	v_mov_b32_e32 v93, 0
	v_mov_b32_e32 v94, 0
	v_mov_b32_e32 v95, 0
	v_mov_b32_e32 v48, 0
	v_mov_b32_e32 v49, 0
	v_mov_b32_e32 v50, 0
	v_mov_b32_e32 v51, 0
	v_mov_b32_e32 v52, 0
	v_mov_b32_e32 v53, 0
	v_mov_b32_e32 v54, 0
	v_mov_b32_e32 v55, 0
	v_mov_b32_e32 v56, 0
	v_mov_b32_e32 v57, 0
	v_mov_b32_e32 v58, 0
	v_mov_b32_e32 v59, 0
	v_mov_b32_e32 v60, 0
	v_mov_b32_e32 v61, 0
	v_mov_b32_e32 v62, 0
	v_mov_b32_e32 v63, 0
	v_mov_b32_e32 v32, 0
	v_mov_b32_e32 v33, 0
	v_mov_b32_e32 v34, 0
	v_mov_b32_e32 v35, 0
	v_mov_b32_e32 v36, 0
	v_mov_b32_e32 v37, 0
	v_mov_b32_e32 v38, 0
	v_mov_b32_e32 v39, 0
	v_mov_b32_e32 v40, 0
	v_mov_b32_e32 v41, 0
	v_mov_b32_e32 v42, 0
	v_mov_b32_e32 v43, 0
	v_mov_b32_e32 v44, 0
	v_mov_b32_e32 v45, 0
	v_mov_b32_e32 v46, 0
	v_mov_b32_e32 v47, 0
	v_mov_b32_e32 v16, 0
	v_mov_b32_e32 v17, 0
	v_mov_b32_e32 v18, 0
	v_mov_b32_e32 v19, 0
	v_mov_b32_e32 v20, 0
	v_mov_b32_e32 v21, 0
	v_mov_b32_e32 v22, 0
	v_mov_b32_e32 v23, 0
	v_mov_b32_e32 v24, 0
	v_mov_b32_e32 v25, 0
	v_mov_b32_e32 v26, 0
	v_mov_b32_e32 v27, 0
	v_mov_b32_e32 v28, 0
	v_mov_b32_e32 v29, 0
	v_mov_b32_e32 v30, 0
	v_mov_b32_e32 v31, 0
	v_mov_b32_e32 v0, 0
	v_mov_b32_e32 v1, 0
	v_mov_b32_e32 v2, 0
	v_mov_b32_e32 v3, 0
	v_mov_b32_e32 v4, 0
	v_mov_b32_e32 v5, 0
	v_mov_b32_e32 v6, 0
	v_mov_b32_e32 v7, 0
	v_mov_b32_e32 v8, 0
	v_mov_b32_e32 v9, 0
	v_mov_b32_e32 v10, 0
	v_mov_b32_e32 v11, 0
	v_mov_b32_e32 v12, 0
	v_mov_b32_e32 v13, 0
	v_mov_b32_e32 v14, 0
	v_mov_b32_e32 v15, 0
	s_cmp_eq_u32 s100, 0
	s_cbranch_scc1 .Lg8_p9_gb0
	s_barrier
.Lg8_p9_gb0:
	s_waitcnt vmcnt(4)
	s_barrier
	s_add_u32 s40, s40, 0x80
	s_addc_u32 s41, s41, 0
	s_add_u32 m0, s99, 0x18000
	s_nop 0
	global_load_lds_dwordx4 v205, s[40:41]
	s_add_u32 m0, s99, 0x1a000
	s_nop 0
	global_load_lds_dwordx4 v206, s[40:41]
	s_add_u32 s42, s42, 0x80
	s_addc_u32 s43, s43, 0
	s_add_u32 m0, s99, 0x10000
	s_nop 0
	global_load_lds_dwordx4 v201, s[42:43]
	s_add_u32 m0, s99, 0x12000
	s_nop 0
	global_load_lds_dwordx4 v202, s[42:43]
	s_add_u32 m0, s99, 0x1c000
	s_nop 0
	global_load_lds_dwordx4 v210, s[40:41]
	s_add_u32 m0, s99, 0x1e000
	s_nop 0
	global_load_lds_dwordx4 v211, s[40:41]
	s_waitcnt vmcnt(6)
	s_barrier
	s_mov_b32 s101, 15
.Lg8_p9_loop:
	ds_read_b128 v[160:163], v197 offset:0
	ds_read_b128 v[164:167], v199 offset:0
	ds_read_b128 v[168:171], v197 offset:2048
	ds_read_b128 v[172:175], v199 offset:2048
	ds_read_b128 v[128:131], v184 offset:0
	ds_read_b128 v[132:135], v187 offset:0
	ds_read_b128 v[136:139], v184 offset:2048
	ds_read_b128 v[140:143], v187 offset:2048
	ds_read_b128 v[144:147], v184 offset:4096
	ds_read_b128 v[148:151], v187 offset:4096
	ds_read_b128 v[152:155], v184 offset:6144
	ds_read_b128 v[156:159], v187 offset:6144
	s_add_u32 m0, s99, 0x14000
	s_nop 0
	global_load_lds_dwordx4 v203, s[42:43]
	s_add_u32 m0, s99, 0x16000
	s_nop 0
	global_load_lds_dwordx4 v204, s[42:43]
	s_waitcnt lgkmcnt(8)
	s_barrier
	s_waitcnt lgkmcnt(0)
	s_setprio 1
	v_mfma_f32_16x16x32_bf16 v[112:115], v[128:131], v[160:163], v[112:115]
	v_mfma_f32_16x16x32_bf16 v[112:115], v[132:135], v[164:167], v[112:115]
	v_mfma_f32_16x16x32_bf16 v[116:119], v[128:131], v[168:171], v[116:119]
	v_mfma_f32_16x16x32_bf16 v[116:119], v[132:135], v[172:175], v[116:119]
	v_mfma_f32_16x16x32_bf16 v[120:123], v[136:139], v[160:163], v[120:123]
	v_mfma_f32_16x16x32_bf16 v[120:123], v[140:143], v[164:167], v[120:123]
	v_mfma_f32_16x16x32_bf16 v[124:127], v[136:139], v[168:171], v[124:127]
	v_mfma_f32_16x16x32_bf16 v[124:127], v[140:143], v[172:175], v[124:127]
	v_mfma_f32_16x16x32_bf16 v[96:99], v[144:147], v[160:163], v[96:99]
	v_mfma_f32_16x16x32_bf16 v[96:99], v[148:151], v[164:167], v[96:99]
	v_mfma_f32_16x16x32_bf16 v[100:103], v[144:147], v[168:171], v[100:103]
	v_mfma_f32_16x16x32_bf16 v[100:103], v[148:151], v[172:175], v[100:103]
	v_mfma_f32_16x16x32_bf16 v[104:107], v[152:155], v[160:163], v[104:107]
	v_mfma_f32_16x16x32_bf16 v[104:107], v[156:159], v[164:167], v[104:107]
	v_mfma_f32_16x16x32_bf16 v[108:111], v[152:155], v[168:171], v[108:111]
	v_mfma_f32_16x16x32_bf16 v[108:111], v[156:159], v[172:175], v[108:111]
	s_setprio 0
	s_barrier
	ds_read_b128 v[176:179], v197 offset:16384
	ds_read_b128 v[180:183], v199 offset:16384
	ds_read_b128 v[188:191], v197 offset:18432
	ds_read_b128 v[192:195], v199 offset:18432
	s_add_u32 s40, s40, 0x80
	s_addc_u32 s41, s41, 0
	s_add_u32 m0, s99, 0x8000
	s_nop 0
	global_load_lds_dwordx4 v205, s[40:41]
	s_add_u32 m0, s99, 0xa000
	s_nop 0
	global_load_lds_dwordx4 v206, s[40:41]
	s_barrier
	s_waitcnt lgkmcnt(0)
	s_setprio 1
	v_mfma_f32_16x16x32_bf16 v[48:51], v[128:131], v[176:179], v[48:51]
	v_mfma_f32_16x16x32_bf16 v[48:51], v[132:135], v[180:183], v[48:51]
	v_mfma_f32_16x16x32_bf16 v[52:55], v[128:131], v[188:191], v[52:55]
	v_mfma_f32_16x16x32_bf16 v[52:55], v[132:135], v[192:195], v[52:55]
	v_mfma_f32_16x16x32_bf16 v[56:59], v[136:139], v[176:179], v[56:59]
	v_mfma_f32_16x16x32_bf16 v[56:59], v[140:143], v[180:183], v[56:59]
	v_mfma_f32_16x16x32_bf16 v[60:63], v[136:139], v[188:191], v[60:63]
	v_mfma_f32_16x16x32_bf16 v[60:63], v[140:143], v[192:195], v[60:63]
	v_mfma_f32_16x16x32_bf16 v[32:35], v[144:147], v[176:179], v[32:35]
	v_mfma_f32_16x16x32_bf16 v[32:35], v[148:151], v[180:183], v[32:35]
	v_mfma_f32_16x16x32_bf16 v[36:39], v[144:147], v[188:191], v[36:39]
	v_mfma_f32_16x16x32_bf16 v[36:39], v[148:151], v[192:195], v[36:39]
	v_mfma_f32_16x16x32_bf16 v[40:43], v[152:155], v[176:179], v[40:43]
	v_mfma_f32_16x16x32_bf16 v[40:43], v[156:159], v[180:183], v[40:43]
	v_mfma_f32_16x16x32_bf16 v[44:47], v[152:155], v[188:191], v[44:47]
	v_mfma_f32_16x16x32_bf16 v[44:47], v[156:159], v[192:195], v[44:47]
	s_setprio 0
	s_barrier
	ds_read_b128 v[128:131], v184 offset:16384
	ds_read_b128 v[132:135], v187 offset:16384
	ds_read_b128 v[136:139], v184 offset:18432
	ds_read_b128 v[140:143], v187 offset:18432
	ds_read_b128 v[144:147], v184 offset:20480
	ds_read_b128 v[148:151], v187 offset:20480
	ds_read_b128 v[152:155], v184 offset:22528
	ds_read_b128 v[156:159], v187 offset:22528
	s_add_u32 s42, s42, 0x80
	s_addc_u32 s43, s43, 0
	s_add_u32 m0, s99, 0x0
	s_nop 0
	global_load_lds_dwordx4 v201, s[42:43]
	s_add_u32 m0, s99, 0x2000
	s_nop 0
	global_load_lds_dwordx4 v202, s[42:43]
	s_barrier
	s_waitcnt lgkmcnt(0)
	s_setprio 1
	v_mfma_f32_16x16x32_bf16 v[64:67], v[128:131], v[160:163], v[64:67]
	v_mfma_f32_16x16x32_bf16 v[64:67], v[132:135], v[164:167], v[64:67]
	v_mfma_f32_16x16x32_bf16 v[68:71], v[128:131], v[168:171], v[68:71]
	v_mfma_f32_16x16x32_bf16 v[68:71], v[132:135], v[172:175], v[68:71]
	v_mfma_f32_16x16x32_bf16 v[72:75], v[136:139], v[160:163], v[72:75]
	v_mfma_f32_16x16x32_bf16 v[72:75], v[140:143], v[164:167], v[72:75]
	v_mfma_f32_16x16x32_bf16 v[76:79], v[136:139], v[168:171], v[76:79]
	v_mfma_f32_16x16x32_bf16 v[76:79], v[140:143], v[172:175], v[76:79]
	v_mfma_f32_16x16x32_bf16 v[80:83], v[144:147], v[160:163], v[80:83]
	v_mfma_f32_16x16x32_bf16 v[80:83], v[148:151], v[164:167], v[80:83]
	v_mfma_f32_16x16x32_bf16 v[84:87], v[144:147], v[168:171], v[84:87]
	v_mfma_f32_16x16x32_bf16 v[84:87], v[148:151], v[172:175], v[84:87]
	v_mfma_f32_16x16x32_bf16 v[88:91], v[152:155], v[160:163], v[88:91]
	v_mfma_f32_16x16x32_bf16 v[88:91], v[156:159], v[164:167], v[88:91]
	v_mfma_f32_16x16x32_bf16 v[92:95], v[152:155], v[168:171], v[92:95]
	v_mfma_f32_16x16x32_bf16 v[92:95], v[156:159], v[172:175], v[92:95]
	s_setprio 0
	s_barrier
	s_add_u32 m0, s99, 0xc000
	s_nop 0
	global_load_lds_dwordx4 v210, s[40:41]
	s_add_u32 m0, s99, 0xe000
	s_nop 0
	global_load_lds_dwordx4 v211, s[40:41]
	s_waitcnt vmcnt(6)
	s_barrier
	s_setprio 1
	v_mfma_f32_16x16x32_bf16 v[16:19], v[128:131], v[176:179], v[16:19]
	v_mfma_f32_16x16x32_bf16 v[16:19], v[132:135], v[180:183], v[16:19]
	v_mfma_f32_16x16x32_bf16 v[20:23], v[128:131], v[188:191], v[20:23]
	v_mfma_f32_16x16x32_bf16 v[20:23], v[132:135], v[192:195], v[20:23]
	v_mfma_f32_16x16x32_bf16 v[24:27], v[136:139], v[176:179], v[24:27]
	v_mfma_f32_16x16x32_bf16 v[24:27], v[140:143], v[180:183], v[24:27]
	v_mfma_f32_16x16x32_bf16 v[28:31], v[136:139], v[188:191], v[28:31]
	v_mfma_f32_16x16x32_bf16 v[28:31], v[140:143], v[192:195], v[28:31]
	v_mfma_f32_16x16x32_bf16 v[0:3], v[144:147], v[176:179], v[0:3]
	v_mfma_f32_16x16x32_bf16 v[0:3], v[148:151], v[180:183], v[0:3]
	v_mfma_f32_16x16x32_bf16 v[4:7], v[144:147], v[188:191], v[4:7]
	v_mfma_f32_16x16x32_bf16 v[4:7], v[148:151], v[192:195], v[4:7]
	v_mfma_f32_16x16x32_bf16 v[8:11], v[152:155], v[176:179], v[8:11]
	v_mfma_f32_16x16x32_bf16 v[8:11], v[156:159], v[180:183], v[8:11]
	v_mfma_f32_16x16x32_bf16 v[12:15], v[152:155], v[188:191], v[12:15]
	v_mfma_f32_16x16x32_bf16 v[12:15], v[156:159], v[192:195], v[12:15]
	s_setprio 0
	s_barrier
	ds_read_b128 v[160:163], v198 offset:0
	ds_read_b128 v[164:167], v200 offset:0
	ds_read_b128 v[168:171], v198 offset:2048
	ds_read_b128 v[172:175], v200 offset:2048
	ds_read_b128 v[128:131], v186 offset:0
	ds_read_b128 v[132:135], v196 offset:0
	ds_read_b128 v[136:139], v186 offset:2048
	ds_read_b128 v[140:143], v196 offset:2048
	ds_read_b128 v[144:147], v186 offset:4096
	ds_read_b128 v[148:151], v196 offset:4096
	ds_read_b128 v[152:155], v186 offset:6144
	ds_read_b128 v[156:159], v196 offset:6144
	s_add_u32 m0, s99, 0x4000
	s_nop 0
	global_load_lds_dwordx4 v203, s[42:43]
	s_add_u32 m0, s99, 0x6000
	s_nop 0
	global_load_lds_dwordx4 v204, s[42:43]
	s_waitcnt lgkmcnt(8)
	s_barrier
	s_waitcnt lgkmcnt(0)
	s_setprio 1
	v_mfma_f32_16x16x32_bf16 v[112:115], v[128:131], v[160:163], v[112:115]
	v_mfma_f32_16x16x32_bf16 v[112:115], v[132:135], v[164:167], v[112:115]
	v_mfma_f32_16x16x32_bf16 v[116:119], v[128:131], v[168:171], v[116:119]
	v_mfma_f32_16x16x32_bf16 v[116:119], v[132:135], v[172:175], v[116:119]
	v_mfma_f32_16x16x32_bf16 v[120:123], v[136:139], v[160:163], v[120:123]
	v_mfma_f32_16x16x32_bf16 v[120:123], v[140:143], v[164:167], v[120:123]
	v_mfma_f32_16x16x32_bf16 v[124:127], v[136:139], v[168:171], v[124:127]
	v_mfma_f32_16x16x32_bf16 v[124:127], v[140:143], v[172:175], v[124:127]
	v_mfma_f32_16x16x32_bf16 v[96:99], v[144:147], v[160:163], v[96:99]
	v_mfma_f32_16x16x32_bf16 v[96:99], v[148:151], v[164:167], v[96:99]
	v_mfma_f32_16x16x32_bf16 v[100:103], v[144:147], v[168:171], v[100:103]
	v_mfma_f32_16x16x32_bf16 v[100:103], v[148:151], v[172:175], v[100:103]
	v_mfma_f32_16x16x32_bf16 v[104:107], v[152:155], v[160:163], v[104:107]
	v_mfma_f32_16x16x32_bf16 v[104:107], v[156:159], v[164:167], v[104:107]
	v_mfma_f32_16x16x32_bf16 v[108:111], v[152:155], v[168:171], v[108:111]
	v_mfma_f32_16x16x32_bf16 v[108:111], v[156:159], v[172:175], v[108:111]
	s_setprio 0
	s_barrier
	ds_read_b128 v[176:179], v198 offset:16384
	ds_read_b128 v[180:183], v200 offset:16384
	ds_read_b128 v[188:191], v198 offset:18432
	ds_read_b128 v[192:195], v200 offset:18432
	s_add_u32 s40, s40, 0x80
	s_addc_u32 s41, s41, 0
	s_add_u32 m0, s99, 0x18000
	s_nop 0
	global_load_lds_dwordx4 v205, s[40:41]
	s_add_u32 m0, s99, 0x1a000
	s_nop 0
	global_load_lds_dwordx4 v206, s[40:41]
	s_barrier
	s_waitcnt lgkmcnt(0)
	s_setprio 1
	v_mfma_f32_16x16x32_bf16 v[48:51], v[128:131], v[176:179], v[48:51]
	v_mfma_f32_16x16x32_bf16 v[48:51], v[132:135], v[180:183], v[48:51]
	v_mfma_f32_16x16x32_bf16 v[52:55], v[128:131], v[188:191], v[52:55]
	v_mfma_f32_16x16x32_bf16 v[52:55], v[132:135], v[192:195], v[52:55]
	v_mfma_f32_16x16x32_bf16 v[56:59], v[136:139], v[176:179], v[56:59]
	v_mfma_f32_16x16x32_bf16 v[56:59], v[140:143], v[180:183], v[56:59]
	v_mfma_f32_16x16x32_bf16 v[60:63], v[136:139], v[188:191], v[60:63]
	v_mfma_f32_16x16x32_bf16 v[60:63], v[140:143], v[192:195], v[60:63]
	v_mfma_f32_16x16x32_bf16 v[32:35], v[144:147], v[176:179], v[32:35]
	v_mfma_f32_16x16x32_bf16 v[32:35], v[148:151], v[180:183], v[32:35]
	v_mfma_f32_16x16x32_bf16 v[36:39], v[144:147], v[188:191], v[36:39]
	v_mfma_f32_16x16x32_bf16 v[36:39], v[148:151], v[192:195], v[36:39]
	v_mfma_f32_16x16x32_bf16 v[40:43], v[152:155], v[176:179], v[40:43]
	v_mfma_f32_16x16x32_bf16 v[40:43], v[156:159], v[180:183], v[40:43]
	v_mfma_f32_16x16x32_bf16 v[44:47], v[152:155], v[188:191], v[44:47]
	v_mfma_f32_16x16x32_bf16 v[44:47], v[156:159], v[192:195], v[44:47]
	s_setprio 0
	s_barrier
	ds_read_b128 v[128:131], v186 offset:16384
	ds_read_b128 v[132:135], v196 offset:16384
	ds_read_b128 v[136:139], v186 offset:18432
	ds_read_b128 v[140:143], v196 offset:18432
	ds_read_b128 v[144:147], v186 offset:20480
	ds_read_b128 v[148:151], v196 offset:20480
	ds_read_b128 v[152:155], v186 offset:22528
	ds_read_b128 v[156:159], v196 offset:22528
	s_add_u32 s42, s42, 0x80
	s_addc_u32 s43, s43, 0
	s_add_u32 m0, s99, 0x10000
	s_nop 0
	global_load_lds_dwordx4 v201, s[42:43]
	s_add_u32 m0, s99, 0x12000
	s_nop 0
	global_load_lds_dwordx4 v202, s[42:43]
	s_barrier
	s_waitcnt lgkmcnt(0)
	s_setprio 1
	v_mfma_f32_16x16x32_bf16 v[64:67], v[128:131], v[160:163], v[64:67]
	v_mfma_f32_16x16x32_bf16 v[64:67], v[132:135], v[164:167], v[64:67]
	v_mfma_f32_16x16x32_bf16 v[68:71], v[128:131], v[168:171], v[68:71]
	v_mfma_f32_16x16x32_bf16 v[68:71], v[132:135], v[172:175], v[68:71]
	v_mfma_f32_16x16x32_bf16 v[72:75], v[136:139], v[160:163], v[72:75]
	v_mfma_f32_16x16x32_bf16 v[72:75], v[140:143], v[164:167], v[72:75]
	v_mfma_f32_16x16x32_bf16 v[76:79], v[136:139], v[168:171], v[76:79]
	v_mfma_f32_16x16x32_bf16 v[76:79], v[140:143], v[172:175], v[76:79]
	v_mfma_f32_16x16x32_bf16 v[80:83], v[144:147], v[160:163], v[80:83]
	v_mfma_f32_16x16x32_bf16 v[80:83], v[148:151], v[164:167], v[80:83]
	v_mfma_f32_16x16x32_bf16 v[84:87], v[144:147], v[168:171], v[84:87]
	v_mfma_f32_16x16x32_bf16 v[84:87], v[148:151], v[172:175], v[84:87]
	v_mfma_f32_16x16x32_bf16 v[88:91], v[152:155], v[160:163], v[88:91]
	v_mfma_f32_16x16x32_bf16 v[88:91], v[156:159], v[164:167], v[88:91]
	v_mfma_f32_16x16x32_bf16 v[92:95], v[152:155], v[168:171], v[92:95]
	v_mfma_f32_16x16x32_bf16 v[92:95], v[156:159], v[172:175], v[92:95]
	s_setprio 0
	s_barrier
	s_add_u32 m0, s99, 0x1c000
	s_nop 0
	global_load_lds_dwordx4 v210, s[40:41]
	s_add_u32 m0, s99, 0x1e000
	s_nop 0
	global_load_lds_dwordx4 v211, s[40:41]
	s_waitcnt vmcnt(6)
	s_barrier
	s_setprio 1
	v_mfma_f32_16x16x32_bf16 v[16:19], v[128:131], v[176:179], v[16:19]
	v_mfma_f32_16x16x32_bf16 v[16:19], v[132:135], v[180:183], v[16:19]
	v_mfma_f32_16x16x32_bf16 v[20:23], v[128:131], v[188:191], v[20:23]
	v_mfma_f32_16x16x32_bf16 v[20:23], v[132:135], v[192:195], v[20:23]
	v_mfma_f32_16x16x32_bf16 v[24:27], v[136:139], v[176:179], v[24:27]
	v_mfma_f32_16x16x32_bf16 v[24:27], v[140:143], v[180:183], v[24:27]
	v_mfma_f32_16x16x32_bf16 v[28:31], v[136:139], v[188:191], v[28:31]
	v_mfma_f32_16x16x32_bf16 v[28:31], v[140:143], v[192:195], v[28:31]
	v_mfma_f32_16x16x32_bf16 v[0:3], v[144:147], v[176:179], v[0:3]
	v_mfma_f32_16x16x32_bf16 v[0:3], v[148:151], v[180:183], v[0:3]
	v_mfma_f32_16x16x32_bf16 v[4:7], v[144:147], v[188:191], v[4:7]
	v_mfma_f32_16x16x32_bf16 v[4:7], v[148:151], v[192:195], v[4:7]
	v_mfma_f32_16x16x32_bf16 v[8:11], v[152:155], v[176:179], v[8:11]
	v_mfma_f32_16x16x32_bf16 v[8:11], v[156:159], v[180:183], v[8:11]
	v_mfma_f32_16x16x32_bf16 v[12:15], v[152:155], v[188:191], v[12:15]
	v_mfma_f32_16x16x32_bf16 v[12:15], v[156:159], v[192:195], v[12:15]
	s_setprio 0
	s_barrier
	s_sub_u32 s101, s101, 1
	s_cmp_lg_u32 s101, 0
	s_cbranch_scc1 .Lg8_p9_loop
	ds_read_b128 v[160:163], v197 offset:0
	ds_read_b128 v[164:167], v199 offset:0
	ds_read_b128 v[168:171], v197 offset:2048
	ds_read_b128 v[172:175], v199 offset:2048
	ds_read_b128 v[128:131], v184 offset:0
	ds_read_b128 v[132:135], v187 offset:0
	ds_read_b128 v[136:139], v184 offset:2048
	ds_read_b128 v[140:143], v187 offset:2048
	ds_read_b128 v[144:147], v184 offset:4096
	ds_read_b128 v[148:151], v187 offset:4096
	ds_read_b128 v[152:155], v184 offset:6144
	ds_read_b128 v[156:159], v187 offset:6144
	s_add_u32 m0, s99, 0x14000
	s_nop 0
	global_load_lds_dwordx4 v203, s[42:43]
	s_add_u32 m0, s99, 0x16000
	s_nop 0
	global_load_lds_dwordx4 v204, s[42:43]
	s_barrier
	s_waitcnt lgkmcnt(0)
	s_setprio 1
	v_mfma_f32_16x16x32_bf16 v[112:115], v[128:131], v[160:163], v[112:115]
	v_mfma_f32_16x16x32_bf16 v[112:115], v[132:135], v[164:167], v[112:115]
	v_mfma_f32_16x16x32_bf16 v[116:119], v[128:131], v[168:171], v[116:119]
	v_mfma_f32_16x16x32_bf16 v[116:119], v[132:135], v[172:175], v[116:119]
	v_mfma_f32_16x16x32_bf16 v[120:123], v[136:139], v[160:163], v[120:123]
	v_mfma_f32_16x16x32_bf16 v[120:123], v[140:143], v[164:167], v[120:123]
	v_mfma_f32_16x16x32_bf16 v[124:127], v[136:139], v[168:171], v[124:127]
	v_mfma_f32_16x16x32_bf16 v[124:127], v[140:143], v[172:175], v[124:127]
	v_mfma_f32_16x16x32_bf16 v[96:99], v[144:147], v[160:163], v[96:99]
	v_mfma_f32_16x16x32_bf16 v[96:99], v[148:151], v[164:167], v[96:99]
	v_mfma_f32_16x16x32_bf16 v[100:103], v[144:147], v[168:171], v[100:103]
	v_mfma_f32_16x16x32_bf16 v[100:103], v[148:151], v[172:175], v[100:103]
	v_mfma_f32_16x16x32_bf16 v[104:107], v[152:155], v[160:163], v[104:107]
	v_mfma_f32_16x16x32_bf16 v[104:107], v[156:159], v[164:167], v[104:107]
	v_mfma_f32_16x16x32_bf16 v[108:111], v[152:155], v[168:171], v[108:111]
	v_mfma_f32_16x16x32_bf16 v[108:111], v[156:159], v[172:175], v[108:111]
	s_setprio 0
	s_barrier
	ds_read_b128 v[176:179], v197 offset:16384
	ds_read_b128 v[180:183], v199 offset:16384
	ds_read_b128 v[188:191], v197 offset:18432
	ds_read_b128 v[192:195], v199 offset:18432
	s_barrier
	s_waitcnt lgkmcnt(0)
	s_setprio 1
	v_mfma_f32_16x16x32_bf16 v[48:51], v[128:131], v[176:179], v[48:51]
	v_mfma_f32_16x16x32_bf16 v[48:51], v[132:135], v[180:183], v[48:51]
	v_mfma_f32_16x16x32_bf16 v[52:55], v[128:131], v[188:191], v[52:55]
	v_mfma_f32_16x16x32_bf16 v[52:55], v[132:135], v[192:195], v[52:55]
	v_mfma_f32_16x16x32_bf16 v[56:59], v[136:139], v[176:179], v[56:59]
	v_mfma_f32_16x16x32_bf16 v[56:59], v[140:143], v[180:183], v[56:59]
	v_mfma_f32_16x16x32_bf16 v[60:63], v[136:139], v[188:191], v[60:63]
	v_mfma_f32_16x16x32_bf16 v[60:63], v[140:143], v[192:195], v[60:63]
	v_mfma_f32_16x16x32_bf16 v[32:35], v[144:147], v[176:179], v[32:35]
	v_mfma_f32_16x16x32_bf16 v[32:35], v[148:151], v[180:183], v[32:35]
	v_mfma_f32_16x16x32_bf16 v[36:39], v[144:147], v[188:191], v[36:39]
	v_mfma_f32_16x16x32_bf16 v[36:39], v[148:151], v[192:195], v[36:39]
	v_mfma_f32_16x16x32_bf16 v[40:43], v[152:155], v[176:179], v[40:43]
	v_mfma_f32_16x16x32_bf16 v[40:43], v[156:159], v[180:183], v[40:43]
	v_mfma_f32_16x16x32_bf16 v[44:47], v[152:155], v[188:191], v[44:47]
	v_mfma_f32_16x16x32_bf16 v[44:47], v[156:159], v[192:195], v[44:47]
	s_setprio 0
	s_barrier
	ds_read_b128 v[128:131], v184 offset:16384
	ds_read_b128 v[132:135], v187 offset:16384
	ds_read_b128 v[136:139], v184 offset:18432
	ds_read_b128 v[140:143], v187 offset:18432
	ds_read_b128 v[144:147], v184 offset:20480
	ds_read_b128 v[148:151], v187 offset:20480
	ds_read_b128 v[152:155], v184 offset:22528
	ds_read_b128 v[156:159], v187 offset:22528
	s_waitcnt vmcnt(4)
	s_barrier
	s_waitcnt lgkmcnt(0)
	s_setprio 1
	v_mfma_f32_16x16x32_bf16 v[64:67], v[128:131], v[160:163], v[64:67]
	v_mfma_f32_16x16x32_bf16 v[64:67], v[132:135], v[164:167], v[64:67]
	v_mfma_f32_16x16x32_bf16 v[68:71], v[128:131], v[168:171], v[68:71]
	v_mfma_f32_16x16x32_bf16 v[68:71], v[132:135], v[172:175], v[68:71]
	v_mfma_f32_16x16x32_bf16 v[72:75], v[136:139], v[160:163], v[72:75]
	v_mfma_f32_16x16x32_bf16 v[72:75], v[140:143], v[164:167], v[72:75]
	v_mfma_f32_16x16x32_bf16 v[76:79], v[136:139], v[168:171], v[76:79]
	v_mfma_f32_16x16x32_bf16 v[76:79], v[140:143], v[172:175], v[76:79]
	v_mfma_f32_16x16x32_bf16 v[80:83], v[144:147], v[160:163], v[80:83]
	v_mfma_f32_16x16x32_bf16 v[80:83], v[148:151], v[164:167], v[80:83]
	v_mfma_f32_16x16x32_bf16 v[84:87], v[144:147], v[168:171], v[84:87]
	v_mfma_f32_16x16x32_bf16 v[84:87], v[148:151], v[172:175], v[84:87]
	v_mfma_f32_16x16x32_bf16 v[88:91], v[152:155], v[160:163], v[88:91]
	v_mfma_f32_16x16x32_bf16 v[88:91], v[156:159], v[164:167], v[88:91]
	v_mfma_f32_16x16x32_bf16 v[92:95], v[152:155], v[168:171], v[92:95]
	v_mfma_f32_16x16x32_bf16 v[92:95], v[156:159], v[172:175], v[92:95]
	s_setprio 0
	s_setprio 1
	v_mfma_f32_16x16x32_bf16 v[16:19], v[128:131], v[176:179], v[16:19]
	v_mfma_f32_16x16x32_bf16 v[16:19], v[132:135], v[180:183], v[16:19]
	v_mfma_f32_16x16x32_bf16 v[20:23], v[128:131], v[188:191], v[20:23]
	v_mfma_f32_16x16x32_bf16 v[20:23], v[132:135], v[192:195], v[20:23]
	v_mfma_f32_16x16x32_bf16 v[24:27], v[136:139], v[176:179], v[24:27]
	v_mfma_f32_16x16x32_bf16 v[24:27], v[140:143], v[180:183], v[24:27]
	v_mfma_f32_16x16x32_bf16 v[28:31], v[136:139], v[188:191], v[28:31]
	v_mfma_f32_16x16x32_bf16 v[28:31], v[140:143], v[192:195], v[28:31]
	v_mfma_f32_16x16x32_bf16 v[0:3], v[144:147], v[176:179], v[0:3]
	v_mfma_f32_16x16x32_bf16 v[0:3], v[148:151], v[180:183], v[0:3]
	v_mfma_f32_16x16x32_bf16 v[4:7], v[144:147], v[188:191], v[4:7]
	v_mfma_f32_16x16x32_bf16 v[4:7], v[148:151], v[192:195], v[4:7]
	v_mfma_f32_16x16x32_bf16 v[8:11], v[152:155], v[176:179], v[8:11]
	v_mfma_f32_16x16x32_bf16 v[8:11], v[156:159], v[180:183], v[8:11]
	v_mfma_f32_16x16x32_bf16 v[12:15], v[152:155], v[188:191], v[12:15]
	v_mfma_f32_16x16x32_bf16 v[12:15], v[156:159], v[192:195], v[12:15]
	s_setprio 0
	s_barrier
	ds_read_b128 v[160:163], v198 offset:0
	ds_read_b128 v[164:167], v200 offset:0
	ds_read_b128 v[168:171], v198 offset:2048
	ds_read_b128 v[172:175], v200 offset:2048
	ds_read_b128 v[128:131], v186 offset:0
	ds_read_b128 v[132:135], v196 offset:0
	ds_read_b128 v[136:139], v186 offset:2048
	ds_read_b128 v[140:143], v196 offset:2048
	ds_read_b128 v[144:147], v186 offset:4096
	ds_read_b128 v[148:151], v196 offset:4096
	ds_read_b128 v[152:155], v186 offset:6144
	ds_read_b128 v[156:159], v196 offset:6144
	s_waitcnt vmcnt(2)
	s_barrier
	s_waitcnt lgkmcnt(0)
	s_setprio 1
	v_mfma_f32_16x16x32_bf16 v[112:115], v[128:131], v[160:163], v[112:115]
	v_mfma_f32_16x16x32_bf16 v[112:115], v[132:135], v[164:167], v[112:115]
	v_mfma_f32_16x16x32_bf16 v[116:119], v[128:131], v[168:171], v[116:119]
	v_mfma_f32_16x16x32_bf16 v[116:119], v[132:135], v[172:175], v[116:119]
	v_mfma_f32_16x16x32_bf16 v[120:123], v[136:139], v[160:163], v[120:123]
	v_mfma_f32_16x16x32_bf16 v[120:123], v[140:143], v[164:167], v[120:123]
	v_mfma_f32_16x16x32_bf16 v[124:127], v[136:139], v[168:171], v[124:127]
	v_mfma_f32_16x16x32_bf16 v[124:127], v[140:143], v[172:175], v[124:127]
	v_mfma_f32_16x16x32_bf16 v[96:99], v[144:147], v[160:163], v[96:99]
	v_mfma_f32_16x16x32_bf16 v[96:99], v[148:151], v[164:167], v[96:99]
	v_mfma_f32_16x16x32_bf16 v[100:103], v[144:147], v[168:171], v[100:103]
	v_mfma_f32_16x16x32_bf16 v[100:103], v[148:151], v[172:175], v[100:103]
	v_mfma_f32_16x16x32_bf16 v[104:107], v[152:155], v[160:163], v[104:107]
	v_mfma_f32_16x16x32_bf16 v[104:107], v[156:159], v[164:167], v[104:107]
	v_mfma_f32_16x16x32_bf16 v[108:111], v[152:155], v[168:171], v[108:111]
	v_mfma_f32_16x16x32_bf16 v[108:111], v[156:159], v[172:175], v[108:111]
	s_setprio 0
	s_barrier
	ds_read_b128 v[176:179], v198 offset:16384
	ds_read_b128 v[180:183], v200 offset:16384
	ds_read_b128 v[188:191], v198 offset:18432
	ds_read_b128 v[192:195], v200 offset:18432
	s_waitcnt vmcnt(0)
	s_barrier
	s_waitcnt lgkmcnt(0)
	s_setprio 1
	v_mfma_f32_16x16x32_bf16 v[48:51], v[128:131], v[176:179], v[48:51]
	v_mfma_f32_16x16x32_bf16 v[48:51], v[132:135], v[180:183], v[48:51]
	v_mfma_f32_16x16x32_bf16 v[52:55], v[128:131], v[188:191], v[52:55]
	v_mfma_f32_16x16x32_bf16 v[52:55], v[132:135], v[192:195], v[52:55]
	v_mfma_f32_16x16x32_bf16 v[56:59], v[136:139], v[176:179], v[56:59]
	v_mfma_f32_16x16x32_bf16 v[56:59], v[140:143], v[180:183], v[56:59]
	v_mfma_f32_16x16x32_bf16 v[60:63], v[136:139], v[188:191], v[60:63]
	v_mfma_f32_16x16x32_bf16 v[60:63], v[140:143], v[192:195], v[60:63]
	v_mfma_f32_16x16x32_bf16 v[32:35], v[144:147], v[176:179], v[32:35]
	v_mfma_f32_16x16x32_bf16 v[32:35], v[148:151], v[180:183], v[32:35]
	v_mfma_f32_16x16x32_bf16 v[36:39], v[144:147], v[188:191], v[36:39]
	v_mfma_f32_16x16x32_bf16 v[36:39], v[148:151], v[192:195], v[36:39]
	v_mfma_f32_16x16x32_bf16 v[40:43], v[152:155], v[176:179], v[40:43]
	v_mfma_f32_16x16x32_bf16 v[40:43], v[156:159], v[180:183], v[40:43]
	v_mfma_f32_16x16x32_bf16 v[44:47], v[152:155], v[188:191], v[44:47]
	v_mfma_f32_16x16x32_bf16 v[44:47], v[156:159], v[192:195], v[44:47]
	s_setprio 0
	s_barrier
	ds_read_b128 v[128:131], v186 offset:16384
	ds_read_b128 v[132:135], v196 offset:16384
	ds_read_b128 v[136:139], v186 offset:18432
	ds_read_b128 v[140:143], v196 offset:18432
	ds_read_b128 v[144:147], v186 offset:20480
	ds_read_b128 v[148:151], v196 offset:20480
	ds_read_b128 v[152:155], v186 offset:22528
	ds_read_b128 v[156:159], v196 offset:22528
	s_barrier
	s_waitcnt lgkmcnt(0)
	s_setprio 1
	v_mfma_f32_16x16x32_bf16 v[64:67], v[128:131], v[160:163], v[64:67]
	v_mfma_f32_16x16x32_bf16 v[64:67], v[132:135], v[164:167], v[64:67]
	v_mfma_f32_16x16x32_bf16 v[68:71], v[128:131], v[168:171], v[68:71]
	v_mfma_f32_16x16x32_bf16 v[68:71], v[132:135], v[172:175], v[68:71]
	v_mfma_f32_16x16x32_bf16 v[72:75], v[136:139], v[160:163], v[72:75]
	v_mfma_f32_16x16x32_bf16 v[72:75], v[140:143], v[164:167], v[72:75]
	v_mfma_f32_16x16x32_bf16 v[76:79], v[136:139], v[168:171], v[76:79]
	v_mfma_f32_16x16x32_bf16 v[76:79], v[140:143], v[172:175], v[76:79]
	v_mfma_f32_16x16x32_bf16 v[80:83], v[144:147], v[160:163], v[80:83]
	v_mfma_f32_16x16x32_bf16 v[80:83], v[148:151], v[164:167], v[80:83]
	v_mfma_f32_16x16x32_bf16 v[84:87], v[144:147], v[168:171], v[84:87]
	v_mfma_f32_16x16x32_bf16 v[84:87], v[148:151], v[172:175], v[84:87]
	v_mfma_f32_16x16x32_bf16 v[88:91], v[152:155], v[160:163], v[88:91]
	v_mfma_f32_16x16x32_bf16 v[88:91], v[156:159], v[164:167], v[88:91]
	v_mfma_f32_16x16x32_bf16 v[92:95], v[152:155], v[168:171], v[92:95]
	v_mfma_f32_16x16x32_bf16 v[92:95], v[156:159], v[172:175], v[92:95]
	s_setprio 0
	s_setprio 1
	v_mfma_f32_16x16x32_bf16 v[16:19], v[128:131], v[176:179], v[16:19]
	v_mfma_f32_16x16x32_bf16 v[16:19], v[132:135], v[180:183], v[16:19]
	v_mfma_f32_16x16x32_bf16 v[20:23], v[128:131], v[188:191], v[20:23]
	v_mfma_f32_16x16x32_bf16 v[20:23], v[132:135], v[192:195], v[20:23]
	v_mfma_f32_16x16x32_bf16 v[24:27], v[136:139], v[176:179], v[24:27]
	v_mfma_f32_16x16x32_bf16 v[24:27], v[140:143], v[180:183], v[24:27]
	v_mfma_f32_16x16x32_bf16 v[28:31], v[136:139], v[188:191], v[28:31]
	v_mfma_f32_16x16x32_bf16 v[28:31], v[140:143], v[192:195], v[28:31]
	v_mfma_f32_16x16x32_bf16 v[0:3], v[144:147], v[176:179], v[0:3]
	v_mfma_f32_16x16x32_bf16 v[0:3], v[148:151], v[180:183], v[0:3]
	v_mfma_f32_16x16x32_bf16 v[4:7], v[144:147], v[188:191], v[4:7]
	v_mfma_f32_16x16x32_bf16 v[4:7], v[148:151], v[192:195], v[4:7]
	v_mfma_f32_16x16x32_bf16 v[8:11], v[152:155], v[176:179], v[8:11]
	v_mfma_f32_16x16x32_bf16 v[8:11], v[156:159], v[180:183], v[8:11]
	v_mfma_f32_16x16x32_bf16 v[12:15], v[152:155], v[188:191], v[12:15]
	v_mfma_f32_16x16x32_bf16 v[12:15], v[156:159], v[192:195], v[12:15]
	s_setprio 0
	s_barrier
	s_cmp_lg_u32 s100, 0
	s_cbranch_scc1 .Lg8_p9_gb1
	s_barrier
